# 8-phase loops: the two LDS-DMA pieces of a phase are issued between the MFMAs of that phase instead of after the fragment reads (vmcnt counts adjusted)
# baseline (speedup 1.0000x reference)
; #define MFMA(a, b, c) __builtin_amdgcn_mfma_f32_32x32x16_bf16((a), (b), (c), 0, 0, 0)
; template <bool SWAP>
; DI void gemm_mainloop(f32x16 (&acc)[4][2], const u16* __restrict__ A, int lda, int rlo, int rhi,
;                       const u16* __restrict__ B, int ldb, int K, char* lds, const u16* zero_line) {
;     ...
;   auto glds = [&](int kt, int st) {
;     char* as_ = lds + st * 65536 + tid * 16;
; #pragma unroll
;     for (int i = 0; i < 4; ++i) {
;       const int rr = lr + 64 * i;
;       const u16* srca = (rr >= rlo && rr < rhi) ? (ap + (ptrdiff_t)(64 * i) * lda + kt * 64) : (zero_line + lc * 8);
;       __builtin_amdgcn_global_load_lds((const unsigned*)srca, (lds_u32*)(as_ + i * 8192), 16, 0, 0);
;       __builtin_amdgcn_global_load_lds((const unsigned*)(bp + (ptrdiff_t)(64 * i) * ldb + kt * 64), (lds_u32*)(as_ + 32768 + i * 8192), 16, 0, 0);
;     }
;   };
;     ...
;   auto ldfrag = [&](const char* st, int ks, int buf) {
;     const int co = ((2 * ks + h) ^ sw) << 4;
; #pragma unroll
;     for (int mi = 0; mi < 4; ++mi) fa[buf][mi] = *(const bf16x8*)(st + arow_off + mi * 4096 + co);
; #pragma unroll
;     for (int ni = 0; ni < 2; ++ni) fb[buf][ni] = *(const bf16x8*)(st + brow_off + ni * 4096 + co);
;   };
;   auto mma = [&](int buf) {
; #pragma unroll
;     for (int mi = 0; mi < 4; ++mi)
; #pragma unroll
;       for (int ni = 0; ni < 2; ++ni)
;         acc[mi][ni] = SWAP ? MFMA(fb[buf][ni], fa[buf][mi], acc[mi][ni]) : MFMA(fa[buf][mi], fb[buf][ni], acc[mi][ni]);
;   };
;   auto pat_rd = [&]() {
; #pragma unroll
;     for (int g = 0; g < 6; ++g) {
;       __builtin_amdgcn_sched_group_barrier(0x100, 1, 0);
;       __builtin_amdgcn_sched_group_barrier(0x008, 1, 0);
;     }
;     __builtin_amdgcn_sched_group_barrier(0x008, 2, 0);
;   };
; #pragma unroll 2
;   for (int kt = 0; kt < nk; ++kt) {
;     const char* st = lds + (kt & 1) * 65536;
;     ldfrag(st, 0, 0);
;     mma(1);
;     pat_rd();
;     if (kt + 1 < nk) glds(kt + 1, (kt + 1) & 1);
;     ldfrag(st, 1, 1);
;     mma(0);
;     pat_rd();
;     ldfrag(st, 2, 0);
;     mma(1);
;     pat_rd();
;     ldfrag(st, 3, 1);
;     mma(0);
;     pat_rd();
;     asm volatile("s_waitcnt vmcnt(0)" ::: "memory");
;     __syncthreads();
;   }
.Lg8_u0u:
	v_add3_u32 v166, v248, v244, 0
	v_add3_u32 v167, v248, v245, 0
	v_add3_u32 v175, v248, v246, 0
	v_add3_u32 v185, v248, v247, 0
	ds_read_b128 v[130:133], v166
	ds_read_b128 v[134:137], v167
	ds_read_b128 v[138:141], v175
	ds_read_b128 v[142:145], v185
	ds_read_b128 v[146:149], v166 offset:4096
	ds_read_b128 v[150:153], v167 offset:4096
	ds_read_b128 v[158:161], v175 offset:4096
	ds_read_b128 v[162:165], v185 offset:4096
	s_barrier
	s_waitcnt lgkmcnt(0)
	v_mfma_f32_32x32x16_bf16 v[114:129], v[176:179], v[130:133], v[114:129]
	v_mfma_f32_32x32x16_bf16 v[82:97], v[176:179], v[146:149], v[82:97]
	s_add_u32 m0, s100, 0x14000
	s_nop 0
	global_load_lds_dwordx4 v237, s[18:19]
	v_add_u32_e32 v237, 0x80, v237
	v_mfma_f32_32x32x16_bf16 v[114:129], v[180:183], v[134:137], v[114:129]
	v_mfma_f32_32x32x16_bf16 v[82:97], v[180:183], v[150:153], v[82:97]
	s_add_u32 m0, s100, 0x16000
	s_nop 0
	global_load_lds_dwordx4 v239, s[18:19]
	v_add_u32_e32 v239, 0x80, v239
	v_mfma_f32_32x32x16_bf16 v[114:129], v[186:189], v[138:141], v[114:129]
	v_mfma_f32_32x32x16_bf16 v[82:97], v[186:189], v[158:161], v[82:97]
	v_mfma_f32_32x32x16_bf16 v[114:129], v[190:193], v[142:145], v[114:129]
	v_mfma_f32_32x32x16_bf16 v[82:97], v[190:193], v[162:165], v[82:97]
	s_barrier
	v_add3_u32 v166, v249, v244, 0
	v_add3_u32 v167, v249, v245, 0
	v_add3_u32 v175, v249, v246, 0
	v_add3_u32 v185, v249, v247, 0
	ds_read_b128 v[194:197], v166 offset:49152
	ds_read_b128 v[198:201], v167 offset:49152
	ds_read_b128 v[228:231], v175 offset:49152
	ds_read_b128 v[232:235], v185 offset:49152
	s_barrier
	s_waitcnt lgkmcnt(0)
	v_mfma_f32_32x32x16_bf16 v[98:113], v[194:197], v[130:133], v[98:113]
	v_mfma_f32_32x32x16_bf16 v[66:81], v[194:197], v[146:149], v[66:81]
	s_add_u32 m0, s100, 0x8000
	s_nop 0
	global_load_lds_dwordx4 v240, s[22:23]
	v_add_u32_e32 v240, 0x80, v240
	v_mfma_f32_32x32x16_bf16 v[98:113], v[198:201], v[134:137], v[98:113]
	v_mfma_f32_32x32x16_bf16 v[66:81], v[198:201], v[150:153], v[66:81]
	s_add_u32 m0, s100, 0xa000
	s_nop 0
	global_load_lds_dwordx4 v242, s[22:23]
	v_add_u32_e32 v242, 0x80, v242
	v_mfma_f32_32x32x16_bf16 v[98:113], v[228:231], v[138:141], v[98:113]
	v_mfma_f32_32x32x16_bf16 v[66:81], v[228:231], v[158:161], v[66:81]
	v_mfma_f32_32x32x16_bf16 v[98:113], v[232:235], v[142:145], v[98:113]
	v_mfma_f32_32x32x16_bf16 v[66:81], v[232:235], v[162:165], v[66:81]
	s_barrier
	v_add3_u32 v166, v248, v244, 0
	v_add3_u32 v167, v248, v245, 0
	v_add3_u32 v175, v248, v246, 0
	v_add3_u32 v185, v248, v247, 0
	ds_read_b128 v[130:133], v166 offset:16384
	ds_read_b128 v[134:137], v167 offset:16384
	ds_read_b128 v[138:141], v175 offset:16384
	ds_read_b128 v[142:145], v185 offset:16384
	ds_read_b128 v[146:149], v166 offset:20480
	ds_read_b128 v[150:153], v167 offset:20480
	ds_read_b128 v[158:161], v175 offset:20480
	ds_read_b128 v[162:165], v185 offset:20480
	s_waitcnt vmcnt(8)
	s_barrier
	s_waitcnt lgkmcnt(0)
	v_mfma_f32_32x32x16_bf16 v[50:65], v[176:179], v[130:133], v[50:65]
	v_mfma_f32_32x32x16_bf16 v[18:33], v[176:179], v[146:149], v[18:33]
	s_add_u32 m0, s100, 0x0
	s_nop 0
	global_load_lds_dwordx4 v236, s[18:19]
	v_add_u32_e32 v236, 0x80, v236
	v_mfma_f32_32x32x16_bf16 v[50:65], v[180:183], v[134:137], v[50:65]
	v_mfma_f32_32x32x16_bf16 v[18:33], v[180:183], v[150:153], v[18:33]
	s_add_u32 m0, s100, 0x2000
	s_nop 0
	global_load_lds_dwordx4 v238, s[18:19]
	v_add_u32_e32 v238, 0x80, v238
	v_mfma_f32_32x32x16_bf16 v[50:65], v[186:189], v[138:141], v[50:65]
	v_mfma_f32_32x32x16_bf16 v[18:33], v[186:189], v[158:161], v[18:33]
	v_mfma_f32_32x32x16_bf16 v[50:65], v[190:193], v[142:145], v[50:65]
	v_mfma_f32_32x32x16_bf16 v[18:33], v[190:193], v[162:165], v[18:33]
	s_barrier
	v_add3_u32 v166, v249, v244, s21
	v_add3_u32 v167, v249, v245, s21
	v_add3_u32 v175, v249, v246, s21
	v_add3_u32 v185, v249, v247, s21
	ds_read_b128 v[176:179], v166 offset:32768
	ds_read_b128 v[180:183], v167 offset:32768
	ds_read_b128 v[186:189], v175 offset:32768
	ds_read_b128 v[190:193], v185 offset:32768
	s_waitcnt vmcnt(4)
	s_barrier
	s_waitcnt lgkmcnt(0)
	v_mfma_f32_32x32x16_bf16 v[34:49], v[194:197], v[130:133], v[34:49]
	v_mfma_f32_32x32x16_bf16 v[2:17], v[194:197], v[146:149], v[2:17]
	s_add_u32 m0, s100, 0xc000
	s_nop 0
	global_load_lds_dwordx4 v241, s[22:23]
	v_add_u32_e32 v241, 0x80, v241
	v_mfma_f32_32x32x16_bf16 v[34:49], v[198:201], v[134:137], v[34:49]
	v_mfma_f32_32x32x16_bf16 v[2:17], v[198:201], v[150:153], v[2:17]
	s_add_u32 m0, s100, 0xe000
	s_nop 0
	global_load_lds_dwordx4 v243, s[22:23]
	v_add_u32_e32 v243, 0x80, v243
	v_mfma_f32_32x32x16_bf16 v[34:49], v[228:231], v[138:141], v[34:49]
	v_mfma_f32_32x32x16_bf16 v[2:17], v[228:231], v[158:161], v[2:17]
	v_mfma_f32_32x32x16_bf16 v[34:49], v[232:235], v[142:145], v[34:49]
	v_mfma_f32_32x32x16_bf16 v[2:17], v[232:235], v[162:165], v[2:17]
	s_barrier
	v_add3_u32 v166, v248, v244, s21
	v_add3_u32 v167, v248, v245, s21
	v_add3_u32 v175, v248, v246, s21
	v_add3_u32 v185, v248, v247, s21
	ds_read_b128 v[130:133], v166
	ds_read_b128 v[134:137], v167
	ds_read_b128 v[138:141], v175
	ds_read_b128 v[142:145], v185
	ds_read_b128 v[146:149], v166 offset:4096
	ds_read_b128 v[150:153], v167 offset:4096
	ds_read_b128 v[158:161], v175 offset:4096
	ds_read_b128 v[162:165], v185 offset:4096
	s_barrier
; #define MFMA(a, b, c) __builtin_amdgcn_mfma_f32_32x32x16_bf16((a), (b), (c), 0, 0, 0)
; template <bool SWAP>
; DI void gemm_mainloop(f32x16 (&acc)[4][2], const u16* __restrict__ A, int lda, int rlo, int rhi,
;                       const u16* __restrict__ B, int ldb, int K, char* lds, const u16* zero_line) {
;     ...
;   auto glds = [&](int kt, int st) {
;     char* as_ = lds + st * 65536 + tid * 16;
; #pragma unroll
;     for (int i = 0; i < 4; ++i) {
;       const int rr = lr + 64 * i;
;       const u16* srca = (rr >= rlo && rr < rhi) ? (ap + (ptrdiff_t)(64 * i) * lda + kt * 64) : (zero_line + lc * 8);
;       __builtin_amdgcn_global_load_lds((const unsigned*)srca, (lds_u32*)(as_ + i * 8192), 16, 0, 0);
;       __builtin_amdgcn_global_load_lds((const unsigned*)(bp + (ptrdiff_t)(64 * i) * ldb + kt * 64), (lds_u32*)(as_ + 32768 + i * 8192), 16, 0, 0);
;     }
;   };
;     ...
;   auto ldfrag = [&](const char* st, int ks, int buf) {
;     const int co = ((2 * ks + h) ^ sw) << 4;
; #pragma unroll
;     for (int mi = 0; mi < 4; ++mi) fa[buf][mi] = *(const bf16x8*)(st + arow_off + mi * 4096 + co);
; #pragma unroll
;     for (int ni = 0; ni < 2; ++ni) fb[buf][ni] = *(const bf16x8*)(st + brow_off + ni * 4096 + co);
;   };
;   auto mma = [&](int buf) {
; #pragma unroll
;     for (int mi = 0; mi < 4; ++mi)
; #pragma unroll
;       for (int ni = 0; ni < 2; ++ni)
;         acc[mi][ni] = SWAP ? MFMA(fb[buf][ni], fa[buf][mi], acc[mi][ni]) : MFMA(fa[buf][mi], fb[buf][ni], acc[mi][ni]);
;   };
;   auto pat_rd = [&]() {
; #pragma unroll
;     for (int g = 0; g < 6; ++g) {
;       __builtin_amdgcn_sched_group_barrier(0x100, 1, 0);
;       __builtin_amdgcn_sched_group_barrier(0x008, 1, 0);
;     }
;     __builtin_amdgcn_sched_group_barrier(0x008, 2, 0);
;   };
; #pragma unroll 2
;   for (int kt = 0; kt < nk; ++kt) {
;     const char* st = lds + (kt & 1) * 65536;
;     ldfrag(st, 0, 0);
;     mma(1);
;     pat_rd();
;     if (kt + 1 < nk) glds(kt + 1, (kt + 1) & 1);
;     ldfrag(st, 1, 1);
;     mma(0);
;     pat_rd();
;     ldfrag(st, 2, 0);
;     mma(1);
;     pat_rd();
;     ldfrag(st, 3, 1);
;     mma(0);
;     pat_rd();
;     asm volatile("s_waitcnt vmcnt(0)" ::: "memory");
;     __syncthreads();
;   }
	s_waitcnt lgkmcnt(0)
	v_mfma_f32_32x32x16_bf16 v[114:129], v[176:179], v[130:133], v[114:129]
	v_mfma_f32_32x32x16_bf16 v[82:97], v[176:179], v[146:149], v[82:97]
	s_add_u32 m0, s100, 0x4000
	s_nop 0
	global_load_lds_dwordx4 v237, s[18:19]
	v_add_u32_e32 v237, 0x80, v237
	v_mfma_f32_32x32x16_bf16 v[114:129], v[180:183], v[134:137], v[114:129]
	v_mfma_f32_32x32x16_bf16 v[82:97], v[180:183], v[150:153], v[82:97]
	s_add_u32 m0, s100, 0x6000
	s_nop 0
	global_load_lds_dwordx4 v239, s[18:19]
	v_add_u32_e32 v239, 0x80, v239
	v_mfma_f32_32x32x16_bf16 v[114:129], v[186:189], v[138:141], v[114:129]
	v_mfma_f32_32x32x16_bf16 v[82:97], v[186:189], v[158:161], v[82:97]
	v_mfma_f32_32x32x16_bf16 v[114:129], v[190:193], v[142:145], v[114:129]
	v_mfma_f32_32x32x16_bf16 v[82:97], v[190:193], v[162:165], v[82:97]
	s_barrier
	v_add3_u32 v166, v249, v244, s21
	v_add3_u32 v167, v249, v245, s21
	v_add3_u32 v175, v249, v246, s21
	v_add3_u32 v185, v249, v247, s21
	ds_read_b128 v[194:197], v166 offset:49152
	ds_read_b128 v[198:201], v167 offset:49152
	ds_read_b128 v[228:231], v175 offset:49152
	ds_read_b128 v[232:235], v185 offset:49152
	s_barrier
	s_waitcnt lgkmcnt(0)
	v_mfma_f32_32x32x16_bf16 v[98:113], v[194:197], v[130:133], v[98:113]
	v_mfma_f32_32x32x16_bf16 v[66:81], v[194:197], v[146:149], v[66:81]
	s_add_u32 m0, s100, 0x18000
	s_nop 0
	global_load_lds_dwordx4 v240, s[22:23]
	v_add_u32_e32 v240, 0x80, v240
	v_mfma_f32_32x32x16_bf16 v[98:113], v[198:201], v[134:137], v[98:113]
	v_mfma_f32_32x32x16_bf16 v[66:81], v[198:201], v[150:153], v[66:81]
	s_add_u32 m0, s100, 0x1a000
	s_nop 0
	global_load_lds_dwordx4 v242, s[22:23]
	v_add_u32_e32 v242, 0x80, v242
	v_mfma_f32_32x32x16_bf16 v[98:113], v[228:231], v[138:141], v[98:113]
	v_mfma_f32_32x32x16_bf16 v[66:81], v[228:231], v[158:161], v[66:81]
	v_mfma_f32_32x32x16_bf16 v[98:113], v[232:235], v[142:145], v[98:113]
	v_mfma_f32_32x32x16_bf16 v[66:81], v[232:235], v[162:165], v[66:81]
	s_barrier
	v_add3_u32 v166, v248, v244, s21
	v_add3_u32 v167, v248, v245, s21
	v_add3_u32 v175, v248, v246, s21
	v_add3_u32 v185, v248, v247, s21
	ds_read_b128 v[130:133], v166 offset:16384
	ds_read_b128 v[134:137], v167 offset:16384
	ds_read_b128 v[138:141], v175 offset:16384
	ds_read_b128 v[142:145], v185 offset:16384
	ds_read_b128 v[146:149], v166 offset:20480
	ds_read_b128 v[150:153], v167 offset:20480
	ds_read_b128 v[158:161], v175 offset:20480
	ds_read_b128 v[162:165], v185 offset:20480
	s_waitcnt vmcnt(8)
	s_barrier
	s_waitcnt lgkmcnt(0)
	v_mfma_f32_32x32x16_bf16 v[50:65], v[176:179], v[130:133], v[50:65]
	v_mfma_f32_32x32x16_bf16 v[18:33], v[176:179], v[146:149], v[18:33]
	s_add_u32 m0, s100, 0x10000
	s_nop 0
	global_load_lds_dwordx4 v236, s[18:19]
	v_add_u32_e32 v236, 0x80, v236
	v_mfma_f32_32x32x16_bf16 v[50:65], v[180:183], v[134:137], v[50:65]
	v_mfma_f32_32x32x16_bf16 v[18:33], v[180:183], v[150:153], v[18:33]
	s_add_u32 m0, s100, 0x12000
	s_nop 0
	global_load_lds_dwordx4 v238, s[18:19]
	v_add_u32_e32 v238, 0x80, v238
	v_mfma_f32_32x32x16_bf16 v[50:65], v[186:189], v[138:141], v[50:65]
	v_mfma_f32_32x32x16_bf16 v[18:33], v[186:189], v[158:161], v[18:33]
	v_mfma_f32_32x32x16_bf16 v[50:65], v[190:193], v[142:145], v[50:65]
	v_mfma_f32_32x32x16_bf16 v[18:33], v[190:193], v[162:165], v[18:33]
	s_barrier
	v_add3_u32 v166, v249, v244, 0
	v_add3_u32 v167, v249, v245, 0
	v_add3_u32 v175, v249, v246, 0
	v_add3_u32 v185, v249, v247, 0
	ds_read_b128 v[176:179], v166 offset:32768
	ds_read_b128 v[180:183], v167 offset:32768
	ds_read_b128 v[186:189], v175 offset:32768
	ds_read_b128 v[190:193], v185 offset:32768
	s_waitcnt vmcnt(4)
	s_barrier
	s_waitcnt lgkmcnt(0)
	v_mfma_f32_32x32x16_bf16 v[34:49], v[194:197], v[130:133], v[34:49]
	v_mfma_f32_32x32x16_bf16 v[2:17], v[194:197], v[146:149], v[2:17]
	s_add_u32 m0, s100, 0x1c000
	s_nop 0
	global_load_lds_dwordx4 v241, s[22:23]
	v_add_u32_e32 v241, 0x80, v241
	v_mfma_f32_32x32x16_bf16 v[34:49], v[198:201], v[134:137], v[34:49]
	v_mfma_f32_32x32x16_bf16 v[2:17], v[198:201], v[150:153], v[2:17]
	s_add_u32 m0, s100, 0x1e000
	s_nop 0
	global_load_lds_dwordx4 v243, s[22:23]
	v_add_u32_e32 v243, 0x80, v243
	v_mfma_f32_32x32x16_bf16 v[34:49], v[228:231], v[138:141], v[34:49]
	v_mfma_f32_32x32x16_bf16 v[2:17], v[228:231], v[158:161], v[2:17]
	v_mfma_f32_32x32x16_bf16 v[34:49], v[232:235], v[142:145], v[34:49]
	v_mfma_f32_32x32x16_bf16 v[2:17], v[232:235], v[162:165], v[2:17]
	s_barrier
	s_add_i32 s29, s29, 2
	s_cmp_lt_u32 s29, 14
	s_cbranch_scc1 .Lg8_u0u
	v_add3_u32 v166, v248, v244, 0
	v_add3_u32 v167, v248, v245, 0
	v_add3_u32 v175, v248, v246, 0
	v_add3_u32 v185, v248, v247, 0
	ds_read_b128 v[130:133], v166
	ds_read_b128 v[134:137], v167
	ds_read_b128 v[138:141], v175
	ds_read_b128 v[142:145], v185
	ds_read_b128 v[146:149], v166 offset:4096
	ds_read_b128 v[150:153], v167 offset:4096
	ds_read_b128 v[158:161], v175 offset:4096
	ds_read_b128 v[162:165], v185 offset:4096
	s_add_u32 m0, s100, 0x14000
	s_nop 0
	global_load_lds_dwordx4 v237, s[18:19]
	v_add_u32_e32 v237, 0x80, v237
	s_add_u32 m0, s100, 0x16000
	s_nop 0
	global_load_lds_dwordx4 v239, s[18:19]
	v_add_u32_e32 v239, 0x80, v239
	s_barrier
	s_waitcnt lgkmcnt(0)
	v_mfma_f32_32x32x16_bf16 v[114:129], v[176:179], v[130:133], v[114:129]
	v_mfma_f32_32x32x16_bf16 v[82:97], v[176:179], v[146:149], v[82:97]
	v_mfma_f32_32x32x16_bf16 v[114:129], v[180:183], v[134:137], v[114:129]
	v_mfma_f32_32x32x16_bf16 v[82:97], v[180:183], v[150:153], v[82:97]
	v_mfma_f32_32x32x16_bf16 v[114:129], v[186:189], v[138:141], v[114:129]
	v_mfma_f32_32x32x16_bf16 v[82:97], v[186:189], v[158:161], v[82:97]
	v_mfma_f32_32x32x16_bf16 v[114:129], v[190:193], v[142:145], v[114:129]
	v_mfma_f32_32x32x16_bf16 v[82:97], v[190:193], v[162:165], v[82:97]
	s_barrier
; #define MFMA(a, b, c) __builtin_amdgcn_mfma_f32_32x32x16_bf16((a), (b), (c), 0, 0, 0)
; template <bool SWAP>
; DI void gemm_mainloop(f32x16 (&acc)[4][2], const u16* __restrict__ A, int lda, int rlo, int rhi,
;                       const u16* __restrict__ B, int ldb, int K, char* lds, const u16* zero_line) {
;     ...
;   auto ldfrag = [&](const char* st, int ks, int buf) {
;     const int co = ((2 * ks + h) ^ sw) << 4;
; #pragma unroll
;     for (int mi = 0; mi < 4; ++mi) fa[buf][mi] = *(const bf16x8*)(st + arow_off + mi * 4096 + co);
; #pragma unroll
;     for (int ni = 0; ni < 2; ++ni) fb[buf][ni] = *(const bf16x8*)(st + brow_off + ni * 4096 + co);
;   };
;   auto mma = [&](int buf) {
; #pragma unroll
;     for (int mi = 0; mi < 4; ++mi)
; #pragma unroll
;       for (int ni = 0; ni < 2; ++ni)
;         acc[mi][ni] = SWAP ? MFMA(fb[buf][ni], fa[buf][mi], acc[mi][ni]) : MFMA(fa[buf][mi], fb[buf][ni], acc[mi][ni]);
;   };
;   auto pat_rd = [&]() {
; #pragma unroll
;     for (int g = 0; g < 6; ++g) {
;       __builtin_amdgcn_sched_group_barrier(0x100, 1, 0);
;       __builtin_amdgcn_sched_group_barrier(0x008, 1, 0);
;     }
;     __builtin_amdgcn_sched_group_barrier(0x008, 2, 0);
;   };
; #pragma unroll 2
;   for (int kt = 0; kt < nk; ++kt) {
;     const char* st = lds + (kt & 1) * 65536;
;     ldfrag(st, 0, 0);
;     mma(1);
;     pat_rd();
;     if (kt + 1 < nk) glds(kt + 1, (kt + 1) & 1);
;     ldfrag(st, 1, 1);
;     mma(0);
;     pat_rd();
;     ldfrag(st, 2, 0);
;     mma(1);
;     pat_rd();
;     ldfrag(st, 3, 1);
;     mma(0);
;     pat_rd();
;     asm volatile("s_waitcnt vmcnt(0)" ::: "memory");
;     __syncthreads();
;   }
;   mma(1);
	v_add3_u32 v166, v249, v244, 0
	v_add3_u32 v167, v249, v245, 0
	v_add3_u32 v175, v249, v246, 0
	v_add3_u32 v185, v249, v247, 0
	ds_read_b128 v[194:197], v166 offset:49152
	ds_read_b128 v[198:201], v167 offset:49152
	ds_read_b128 v[228:231], v175 offset:49152
	ds_read_b128 v[232:235], v185 offset:49152
	s_barrier
	s_waitcnt lgkmcnt(0)
	v_mfma_f32_32x32x16_bf16 v[98:113], v[194:197], v[130:133], v[98:113]
	v_mfma_f32_32x32x16_bf16 v[66:81], v[194:197], v[146:149], v[66:81]
	v_mfma_f32_32x32x16_bf16 v[98:113], v[198:201], v[134:137], v[98:113]
	v_mfma_f32_32x32x16_bf16 v[66:81], v[198:201], v[150:153], v[66:81]
	v_mfma_f32_32x32x16_bf16 v[98:113], v[228:231], v[138:141], v[98:113]
	v_mfma_f32_32x32x16_bf16 v[66:81], v[228:231], v[158:161], v[66:81]
	v_mfma_f32_32x32x16_bf16 v[98:113], v[232:235], v[142:145], v[98:113]
	v_mfma_f32_32x32x16_bf16 v[66:81], v[232:235], v[162:165], v[66:81]
	s_barrier
	v_add3_u32 v166, v248, v244, 0
	v_add3_u32 v167, v248, v245, 0
	v_add3_u32 v175, v248, v246, 0
	v_add3_u32 v185, v248, v247, 0
	ds_read_b128 v[130:133], v166 offset:16384
	ds_read_b128 v[134:137], v167 offset:16384
	ds_read_b128 v[138:141], v175 offset:16384
	ds_read_b128 v[142:145], v185 offset:16384
	ds_read_b128 v[146:149], v166 offset:20480
	ds_read_b128 v[150:153], v167 offset:20480
	ds_read_b128 v[158:161], v175 offset:20480
	ds_read_b128 v[162:165], v185 offset:20480
	s_waitcnt vmcnt(4)
	s_barrier
	s_waitcnt lgkmcnt(0)
	v_mfma_f32_32x32x16_bf16 v[50:65], v[176:179], v[130:133], v[50:65]
	v_mfma_f32_32x32x16_bf16 v[18:33], v[176:179], v[146:149], v[18:33]
	v_mfma_f32_32x32x16_bf16 v[50:65], v[180:183], v[134:137], v[50:65]
	v_mfma_f32_32x32x16_bf16 v[18:33], v[180:183], v[150:153], v[18:33]
	v_mfma_f32_32x32x16_bf16 v[50:65], v[186:189], v[138:141], v[50:65]
	v_mfma_f32_32x32x16_bf16 v[18:33], v[186:189], v[158:161], v[18:33]
	v_mfma_f32_32x32x16_bf16 v[50:65], v[190:193], v[142:145], v[50:65]
	v_mfma_f32_32x32x16_bf16 v[18:33], v[190:193], v[162:165], v[18:33]
	v_mfma_f32_32x32x16_bf16 v[34:49], v[194:197], v[130:133], v[34:49]
	v_mfma_f32_32x32x16_bf16 v[2:17], v[194:197], v[146:149], v[2:17]
	v_mfma_f32_32x32x16_bf16 v[34:49], v[198:201], v[134:137], v[34:49]
	v_mfma_f32_32x32x16_bf16 v[2:17], v[198:201], v[150:153], v[2:17]
	v_mfma_f32_32x32x16_bf16 v[34:49], v[228:231], v[138:141], v[34:49]
	v_mfma_f32_32x32x16_bf16 v[2:17], v[228:231], v[158:161], v[2:17]
	v_mfma_f32_32x32x16_bf16 v[34:49], v[232:235], v[142:145], v[34:49]
	v_mfma_f32_32x32x16_bf16 v[2:17], v[232:235], v[162:165], v[2:17]
	s_barrier
	v_add3_u32 v166, v249, v244, s21
	v_add3_u32 v167, v249, v245, s21
	v_add3_u32 v175, v249, v246, s21
	v_add3_u32 v185, v249, v247, s21
	ds_read_b128 v[176:179], v166 offset:32768
	ds_read_b128 v[180:183], v167 offset:32768
	ds_read_b128 v[186:189], v175 offset:32768
	ds_read_b128 v[190:193], v185 offset:32768
	v_add3_u32 v166, v248, v244, s21
	v_add3_u32 v167, v248, v245, s21
	v_add3_u32 v175, v248, v246, s21
	v_add3_u32 v185, v248, v247, s21
	ds_read_b128 v[130:133], v166
	ds_read_b128 v[134:137], v167
	ds_read_b128 v[138:141], v175
	ds_read_b128 v[142:145], v185
	ds_read_b128 v[146:149], v166 offset:4096
	ds_read_b128 v[150:153], v167 offset:4096
	ds_read_b128 v[158:161], v175 offset:4096
	ds_read_b128 v[162:165], v185 offset:4096
	s_waitcnt vmcnt(2)
	s_barrier
	s_waitcnt lgkmcnt(0)
	v_mfma_f32_32x32x16_bf16 v[114:129], v[176:179], v[130:133], v[114:129]
	v_mfma_f32_32x32x16_bf16 v[82:97], v[176:179], v[146:149], v[82:97]
	v_mfma_f32_32x32x16_bf16 v[114:129], v[180:183], v[134:137], v[114:129]
	v_mfma_f32_32x32x16_bf16 v[82:97], v[180:183], v[150:153], v[82:97]
	v_mfma_f32_32x32x16_bf16 v[114:129], v[186:189], v[138:141], v[114:129]
	v_mfma_f32_32x32x16_bf16 v[82:97], v[186:189], v[158:161], v[82:97]
	v_mfma_f32_32x32x16_bf16 v[114:129], v[190:193], v[142:145], v[114:129]
	v_mfma_f32_32x32x16_bf16 v[82:97], v[190:193], v[162:165], v[82:97]
	s_barrier
	v_add3_u32 v166, v249, v244, s21
	v_add3_u32 v167, v249, v245, s21
	v_add3_u32 v175, v249, v246, s21
	v_add3_u32 v185, v249, v247, s21
	ds_read_b128 v[194:197], v166 offset:49152
	ds_read_b128 v[198:201], v167 offset:49152
	ds_read_b128 v[228:231], v175 offset:49152
	ds_read_b128 v[232:235], v185 offset:49152
	s_waitcnt vmcnt(0)
	s_barrier
	s_waitcnt lgkmcnt(0)
	v_mfma_f32_32x32x16_bf16 v[98:113], v[194:197], v[130:133], v[98:113]
	v_mfma_f32_32x32x16_bf16 v[66:81], v[194:197], v[146:149], v[66:81]
	v_mfma_f32_32x32x16_bf16 v[98:113], v[198:201], v[134:137], v[98:113]
	v_mfma_f32_32x32x16_bf16 v[66:81], v[198:201], v[150:153], v[66:81]
	v_mfma_f32_32x32x16_bf16 v[98:113], v[228:231], v[138:141], v[98:113]
	v_mfma_f32_32x32x16_bf16 v[66:81], v[228:231], v[158:161], v[66:81]
	v_mfma_f32_32x32x16_bf16 v[98:113], v[232:235], v[142:145], v[98:113]
	v_mfma_f32_32x32x16_bf16 v[66:81], v[232:235], v[162:165], v[66:81]
	s_barrier
	v_add3_u32 v166, v248, v244, s21
	v_add3_u32 v167, v248, v245, s21
	v_add3_u32 v175, v248, v246, s21
	v_add3_u32 v185, v248, v247, s21
	ds_read_b128 v[130:133], v166 offset:16384
	ds_read_b128 v[134:137], v167 offset:16384
	ds_read_b128 v[138:141], v175 offset:16384
	ds_read_b128 v[142:145], v185 offset:16384
	ds_read_b128 v[146:149], v166 offset:20480
	ds_read_b128 v[150:153], v167 offset:20480
	ds_read_b128 v[158:161], v175 offset:20480
	ds_read_b128 v[162:165], v185 offset:20480
	s_barrier
	s_waitcnt lgkmcnt(0)
	v_mfma_f32_32x32x16_bf16 v[50:65], v[176:179], v[130:133], v[50:65]
	v_mfma_f32_32x32x16_bf16 v[18:33], v[176:179], v[146:149], v[18:33]
	v_mfma_f32_32x32x16_bf16 v[50:65], v[180:183], v[134:137], v[50:65]
	v_mfma_f32_32x32x16_bf16 v[18:33], v[180:183], v[150:153], v[18:33]
	v_mfma_f32_32x32x16_bf16 v[50:65], v[186:189], v[138:141], v[50:65]
	v_mfma_f32_32x32x16_bf16 v[18:33], v[186:189], v[158:161], v[18:33]
	v_mfma_f32_32x32x16_bf16 v[50:65], v[190:193], v[142:145], v[50:65]
	v_mfma_f32_32x32x16_bf16 v[18:33], v[190:193], v[162:165], v[18:33]
	v_mfma_f32_32x32x16_bf16 v[34:49], v[194:197], v[130:133], v[34:49]
	v_mfma_f32_32x32x16_bf16 v[2:17], v[194:197], v[146:149], v[2:17]
	v_mfma_f32_32x32x16_bf16 v[34:49], v[198:201], v[134:137], v[34:49]
	v_mfma_f32_32x32x16_bf16 v[2:17], v[198:201], v[150:153], v[2:17]
	v_mfma_f32_32x32x16_bf16 v[34:49], v[228:231], v[138:141], v[34:49]
	v_mfma_f32_32x32x16_bf16 v[2:17], v[228:231], v[158:161], v[2:17]
	v_mfma_f32_32x32x16_bf16 v[34:49], v[232:235], v[142:145], v[34:49]
	v_mfma_f32_32x32x16_bf16 v[2:17], v[232:235], v[162:165], v[2:17]
	s_barrier
	s_cmp_eq_u32 s101, 0
	s_cbranch_scc0 .Lg8_u0u_p1
	s_barrier

; #define MFMA(a, b, c) __builtin_amdgcn_mfma_f32_32x32x16_bf16((a), (b), (c), 0, 0, 0)
; template <bool SWAP>
; DI void gemm_mainloop(f32x16 (&acc)[4][2], const u16* __restrict__ A, int lda, int rlo, int rhi,
;                       const u16* __restrict__ B, int ldb, int K, char* lds, const u16* zero_line) {
;     ...
;   auto glds = [&](int kt, int st) {
;     char* as_ = lds + st * 65536 + tid * 16;
; #pragma unroll
;     for (int i = 0; i < 4; ++i) {
;       const int rr = lr + 64 * i;
;       const u16* srca = (rr >= rlo && rr < rhi) ? (ap + (ptrdiff_t)(64 * i) * lda + kt * 64) : (zero_line + lc * 8);
;       __builtin_amdgcn_global_load_lds((const unsigned*)srca, (lds_u32*)(as_ + i * 8192), 16, 0, 0);
;       __builtin_amdgcn_global_load_lds((const unsigned*)(bp + (ptrdiff_t)(64 * i) * ldb + kt * 64), (lds_u32*)(as_ + 32768 + i * 8192), 16, 0, 0);
;     }
;   };
;     ...
;   auto ldfrag = [&](const char* st, int ks, int buf) {
;     const int co = ((2 * ks + h) ^ sw) << 4;
; #pragma unroll
;     for (int mi = 0; mi < 4; ++mi) fa[buf][mi] = *(const bf16x8*)(st + arow_off + mi * 4096 + co);
; #pragma unroll
;     for (int ni = 0; ni < 2; ++ni) fb[buf][ni] = *(const bf16x8*)(st + brow_off + ni * 4096 + co);
;   };
;   auto mma = [&](int buf) {
; #pragma unroll
;     for (int mi = 0; mi < 4; ++mi)
; #pragma unroll
;       for (int ni = 0; ni < 2; ++ni)
;         acc[mi][ni] = SWAP ? MFMA(fb[buf][ni], fa[buf][mi], acc[mi][ni]) : MFMA(fa[buf][mi], fb[buf][ni], acc[mi][ni]);
;   };
;   auto pat_rd = [&]() {
; #pragma unroll
;     for (int g = 0; g < 6; ++g) {
;       __builtin_amdgcn_sched_group_barrier(0x100, 1, 0);
;       __builtin_amdgcn_sched_group_barrier(0x008, 1, 0);
;     }
;     __builtin_amdgcn_sched_group_barrier(0x008, 2, 0);
;   };
; #pragma unroll 2
;   for (int kt = 0; kt < nk; ++kt) {
;     const char* st = lds + (kt & 1) * 65536;
;     ldfrag(st, 0, 0);
;     mma(1);
;     pat_rd();
;     if (kt + 1 < nk) glds(kt + 1, (kt + 1) & 1);
;     ldfrag(st, 1, 1);
;     mma(0);
;     pat_rd();
;     ldfrag(st, 2, 0);
;     mma(1);
;     pat_rd();
;     ldfrag(st, 3, 1);
;     mma(0);
;     pat_rd();
;     asm volatile("s_waitcnt vmcnt(0)" ::: "memory");
;     __syncthreads();
;   }
.Lg8_u0m:
	v_add3_u32 v166, v248, v244, 0
	v_add3_u32 v167, v248, v245, 0
	v_add3_u32 v175, v248, v246, 0
	v_add3_u32 v185, v248, v247, 0
	ds_read_b128 v[130:133], v166
	ds_read_b128 v[134:137], v167
	ds_read_b128 v[138:141], v175
	ds_read_b128 v[142:145], v185
	ds_read_b128 v[146:149], v166 offset:4096
	ds_read_b128 v[150:153], v167 offset:4096
	ds_read_b128 v[158:161], v175 offset:4096
	ds_read_b128 v[162:165], v185 offset:4096
	s_barrier
	s_waitcnt lgkmcnt(0)
	v_mfma_f32_32x32x16_bf16 v[114:129], v[176:179], v[130:133], v[114:129]
	v_mfma_f32_32x32x16_bf16 v[82:97], v[176:179], v[146:149], v[82:97]
	s_add_u32 m0, s100, 0x14000
	s_mov_b64 exec, s[12:13]
	global_load_lds_dwordx4 v237, s[18:19]
	s_mov_b64 exec, -1
	v_add_u32_e32 v237, 0x80, v237
	v_mfma_f32_32x32x16_bf16 v[114:129], v[180:183], v[134:137], v[114:129]
	v_mfma_f32_32x32x16_bf16 v[82:97], v[180:183], v[150:153], v[82:97]
	s_add_u32 m0, s100, 0x16000
	s_mov_b64 exec, s[16:17]
	global_load_lds_dwordx4 v239, s[18:19]
	s_mov_b64 exec, -1
	v_add_u32_e32 v239, 0x80, v239
	v_mfma_f32_32x32x16_bf16 v[114:129], v[186:189], v[138:141], v[114:129]
	v_mfma_f32_32x32x16_bf16 v[82:97], v[186:189], v[158:161], v[82:97]
	v_mfma_f32_32x32x16_bf16 v[114:129], v[190:193], v[142:145], v[114:129]
	v_mfma_f32_32x32x16_bf16 v[82:97], v[190:193], v[162:165], v[82:97]
	s_barrier
	v_add3_u32 v166, v249, v244, 0
	v_add3_u32 v167, v249, v245, 0
	v_add3_u32 v175, v249, v246, 0
	v_add3_u32 v185, v249, v247, 0
	ds_read_b128 v[194:197], v166 offset:49152
	ds_read_b128 v[198:201], v167 offset:49152
	ds_read_b128 v[228:231], v175 offset:49152
	ds_read_b128 v[232:235], v185 offset:49152
	s_barrier
	s_waitcnt lgkmcnt(0)
	v_mfma_f32_32x32x16_bf16 v[98:113], v[194:197], v[130:133], v[98:113]
	v_mfma_f32_32x32x16_bf16 v[66:81], v[194:197], v[146:149], v[66:81]
	s_add_u32 m0, s100, 0x8000
	s_nop 0
	global_load_lds_dwordx4 v240, s[22:23]
	v_add_u32_e32 v240, 0x80, v240
	v_mfma_f32_32x32x16_bf16 v[98:113], v[198:201], v[134:137], v[98:113]
	v_mfma_f32_32x32x16_bf16 v[66:81], v[198:201], v[150:153], v[66:81]
	s_add_u32 m0, s100, 0xa000
	s_nop 0
	global_load_lds_dwordx4 v242, s[22:23]
	v_add_u32_e32 v242, 0x80, v242
	v_mfma_f32_32x32x16_bf16 v[98:113], v[228:231], v[138:141], v[98:113]
	v_mfma_f32_32x32x16_bf16 v[66:81], v[228:231], v[158:161], v[66:81]
	v_mfma_f32_32x32x16_bf16 v[98:113], v[232:235], v[142:145], v[98:113]
	v_mfma_f32_32x32x16_bf16 v[66:81], v[232:235], v[162:165], v[66:81]
	s_barrier
	v_add3_u32 v166, v248, v244, 0
	v_add3_u32 v167, v248, v245, 0
	v_add3_u32 v175, v248, v246, 0
	v_add3_u32 v185, v248, v247, 0
	ds_read_b128 v[130:133], v166 offset:16384
	ds_read_b128 v[134:137], v167 offset:16384
	ds_read_b128 v[138:141], v175 offset:16384
	ds_read_b128 v[142:145], v185 offset:16384
	ds_read_b128 v[146:149], v166 offset:20480
	ds_read_b128 v[150:153], v167 offset:20480
	ds_read_b128 v[158:161], v175 offset:20480
	ds_read_b128 v[162:165], v185 offset:20480
	s_waitcnt vmcnt(8)
	s_barrier
	s_waitcnt lgkmcnt(0)
	v_mfma_f32_32x32x16_bf16 v[50:65], v[176:179], v[130:133], v[50:65]
	v_mfma_f32_32x32x16_bf16 v[18:33], v[176:179], v[146:149], v[18:33]
	s_add_u32 m0, s100, 0x0
	s_mov_b64 exec, s[10:11]
	global_load_lds_dwordx4 v236, s[18:19]
	s_mov_b64 exec, -1
	v_add_u32_e32 v236, 0x80, v236
	v_mfma_f32_32x32x16_bf16 v[50:65], v[180:183], v[134:137], v[50:65]
	v_mfma_f32_32x32x16_bf16 v[18:33], v[180:183], v[150:153], v[18:33]
	s_add_u32 m0, s100, 0x2000
	s_mov_b64 exec, s[14:15]
	global_load_lds_dwordx4 v238, s[18:19]
	s_mov_b64 exec, -1
	v_add_u32_e32 v238, 0x80, v238
	v_mfma_f32_32x32x16_bf16 v[50:65], v[186:189], v[138:141], v[50:65]
	v_mfma_f32_32x32x16_bf16 v[18:33], v[186:189], v[158:161], v[18:33]
	v_mfma_f32_32x32x16_bf16 v[50:65], v[190:193], v[142:145], v[50:65]
	v_mfma_f32_32x32x16_bf16 v[18:33], v[190:193], v[162:165], v[18:33]
	s_barrier
	v_add3_u32 v166, v249, v244, s21
	v_add3_u32 v167, v249, v245, s21
	v_add3_u32 v175, v249, v246, s21
	v_add3_u32 v185, v249, v247, s21
	ds_read_b128 v[176:179], v166 offset:32768
	ds_read_b128 v[180:183], v167 offset:32768
	ds_read_b128 v[186:189], v175 offset:32768
	ds_read_b128 v[190:193], v185 offset:32768
	s_waitcnt vmcnt(4)
	s_barrier
	s_waitcnt lgkmcnt(0)
	v_mfma_f32_32x32x16_bf16 v[34:49], v[194:197], v[130:133], v[34:49]
	v_mfma_f32_32x32x16_bf16 v[2:17], v[194:197], v[146:149], v[2:17]
	s_add_u32 m0, s100, 0xc000
	s_nop 0
	global_load_lds_dwordx4 v241, s[22:23]
	v_add_u32_e32 v241, 0x80, v241
	v_mfma_f32_32x32x16_bf16 v[34:49], v[198:201], v[134:137], v[34:49]
	v_mfma_f32_32x32x16_bf16 v[2:17], v[198:201], v[150:153], v[2:17]
	s_add_u32 m0, s100, 0xe000
	s_nop 0
	global_load_lds_dwordx4 v243, s[22:23]
	v_add_u32_e32 v243, 0x80, v243
	v_mfma_f32_32x32x16_bf16 v[34:49], v[228:231], v[138:141], v[34:49]
	v_mfma_f32_32x32x16_bf16 v[2:17], v[228:231], v[158:161], v[2:17]
	v_mfma_f32_32x32x16_bf16 v[34:49], v[232:235], v[142:145], v[34:49]
	v_mfma_f32_32x32x16_bf16 v[2:17], v[232:235], v[162:165], v[2:17]
	s_barrier
	v_add3_u32 v166, v248, v244, s21
	v_add3_u32 v167, v248, v245, s21
	v_add3_u32 v175, v248, v246, s21
	v_add3_u32 v185, v248, v247, s21
	ds_read_b128 v[130:133], v166
	ds_read_b128 v[134:137], v167
	ds_read_b128 v[138:141], v175
	ds_read_b128 v[142:145], v185
	ds_read_b128 v[146:149], v166 offset:4096
	ds_read_b128 v[150:153], v167 offset:4096
	ds_read_b128 v[158:161], v175 offset:4096
	ds_read_b128 v[162:165], v185 offset:4096
	s_barrier
; #define MFMA(a, b, c) __builtin_amdgcn_mfma_f32_32x32x16_bf16((a), (b), (c), 0, 0, 0)
; template <bool SWAP>
; DI void gemm_mainloop(f32x16 (&acc)[4][2], const u16* __restrict__ A, int lda, int rlo, int rhi,
;                       const u16* __restrict__ B, int ldb, int K, char* lds, const u16* zero_line) {
;     ...
;   auto glds = [&](int kt, int st) {
;     char* as_ = lds + st * 65536 + tid * 16;
; #pragma unroll
;     for (int i = 0; i < 4; ++i) {
;       const int rr = lr + 64 * i;
;       const u16* srca = (rr >= rlo && rr < rhi) ? (ap + (ptrdiff_t)(64 * i) * lda + kt * 64) : (zero_line + lc * 8);
;       __builtin_amdgcn_global_load_lds((const unsigned*)srca, (lds_u32*)(as_ + i * 8192), 16, 0, 0);
;       __builtin_amdgcn_global_load_lds((const unsigned*)(bp + (ptrdiff_t)(64 * i) * ldb + kt * 64), (lds_u32*)(as_ + 32768 + i * 8192), 16, 0, 0);
;     }
;   };
;     ...
;   auto ldfrag = [&](const char* st, int ks, int buf) {
;     const int co = ((2 * ks + h) ^ sw) << 4;
; #pragma unroll
;     for (int mi = 0; mi < 4; ++mi) fa[buf][mi] = *(const bf16x8*)(st + arow_off + mi * 4096 + co);
; #pragma unroll
;     for (int ni = 0; ni < 2; ++ni) fb[buf][ni] = *(const bf16x8*)(st + brow_off + ni * 4096 + co);
;   };
;   auto mma = [&](int buf) {
; #pragma unroll
;     for (int mi = 0; mi < 4; ++mi)
; #pragma unroll
;       for (int ni = 0; ni < 2; ++ni)
;         acc[mi][ni] = SWAP ? MFMA(fb[buf][ni], fa[buf][mi], acc[mi][ni]) : MFMA(fa[buf][mi], fb[buf][ni], acc[mi][ni]);
;   };
;   auto pat_rd = [&]() {
; #pragma unroll
;     for (int g = 0; g < 6; ++g) {
;       __builtin_amdgcn_sched_group_barrier(0x100, 1, 0);
;       __builtin_amdgcn_sched_group_barrier(0x008, 1, 0);
;     }
;     __builtin_amdgcn_sched_group_barrier(0x008, 2, 0);
;   };
; #pragma unroll 2
;   for (int kt = 0; kt < nk; ++kt) {
;     const char* st = lds + (kt & 1) * 65536;
;     ldfrag(st, 0, 0);
;     mma(1);
;     pat_rd();
;     if (kt + 1 < nk) glds(kt + 1, (kt + 1) & 1);
;     ldfrag(st, 1, 1);
;     mma(0);
;     pat_rd();
;     ldfrag(st, 2, 0);
;     mma(1);
;     pat_rd();
;     ldfrag(st, 3, 1);
;     mma(0);
;     pat_rd();
;     asm volatile("s_waitcnt vmcnt(0)" ::: "memory");
;     __syncthreads();
;   }
	s_waitcnt lgkmcnt(0)
	v_mfma_f32_32x32x16_bf16 v[114:129], v[176:179], v[130:133], v[114:129]
	v_mfma_f32_32x32x16_bf16 v[82:97], v[176:179], v[146:149], v[82:97]
	s_add_u32 m0, s100, 0x4000
	s_mov_b64 exec, s[12:13]
	global_load_lds_dwordx4 v237, s[18:19]
	s_mov_b64 exec, -1
	v_add_u32_e32 v237, 0x80, v237
	v_mfma_f32_32x32x16_bf16 v[114:129], v[180:183], v[134:137], v[114:129]
	v_mfma_f32_32x32x16_bf16 v[82:97], v[180:183], v[150:153], v[82:97]
	s_add_u32 m0, s100, 0x6000
	s_mov_b64 exec, s[16:17]
	global_load_lds_dwordx4 v239, s[18:19]
	s_mov_b64 exec, -1
	v_add_u32_e32 v239, 0x80, v239
	v_mfma_f32_32x32x16_bf16 v[114:129], v[186:189], v[138:141], v[114:129]
	v_mfma_f32_32x32x16_bf16 v[82:97], v[186:189], v[158:161], v[82:97]
	v_mfma_f32_32x32x16_bf16 v[114:129], v[190:193], v[142:145], v[114:129]
	v_mfma_f32_32x32x16_bf16 v[82:97], v[190:193], v[162:165], v[82:97]
	s_barrier
	v_add3_u32 v166, v249, v244, s21
	v_add3_u32 v167, v249, v245, s21
	v_add3_u32 v175, v249, v246, s21
	v_add3_u32 v185, v249, v247, s21
	ds_read_b128 v[194:197], v166 offset:49152
	ds_read_b128 v[198:201], v167 offset:49152
	ds_read_b128 v[228:231], v175 offset:49152
	ds_read_b128 v[232:235], v185 offset:49152
	s_barrier
	s_waitcnt lgkmcnt(0)
	v_mfma_f32_32x32x16_bf16 v[98:113], v[194:197], v[130:133], v[98:113]
	v_mfma_f32_32x32x16_bf16 v[66:81], v[194:197], v[146:149], v[66:81]
	s_add_u32 m0, s100, 0x18000
	s_nop 0
	global_load_lds_dwordx4 v240, s[22:23]
	v_add_u32_e32 v240, 0x80, v240
	v_mfma_f32_32x32x16_bf16 v[98:113], v[198:201], v[134:137], v[98:113]
	v_mfma_f32_32x32x16_bf16 v[66:81], v[198:201], v[150:153], v[66:81]
	s_add_u32 m0, s100, 0x1a000
	s_nop 0
	global_load_lds_dwordx4 v242, s[22:23]
	v_add_u32_e32 v242, 0x80, v242
	v_mfma_f32_32x32x16_bf16 v[98:113], v[228:231], v[138:141], v[98:113]
	v_mfma_f32_32x32x16_bf16 v[66:81], v[228:231], v[158:161], v[66:81]
	v_mfma_f32_32x32x16_bf16 v[98:113], v[232:235], v[142:145], v[98:113]
	v_mfma_f32_32x32x16_bf16 v[66:81], v[232:235], v[162:165], v[66:81]
	s_barrier
	v_add3_u32 v166, v248, v244, s21
	v_add3_u32 v167, v248, v245, s21
	v_add3_u32 v175, v248, v246, s21
	v_add3_u32 v185, v248, v247, s21
	ds_read_b128 v[130:133], v166 offset:16384
	ds_read_b128 v[134:137], v167 offset:16384
	ds_read_b128 v[138:141], v175 offset:16384
	ds_read_b128 v[142:145], v185 offset:16384
	ds_read_b128 v[146:149], v166 offset:20480
	ds_read_b128 v[150:153], v167 offset:20480
	ds_read_b128 v[158:161], v175 offset:20480
	ds_read_b128 v[162:165], v185 offset:20480
	s_waitcnt vmcnt(8)
	s_barrier
	s_waitcnt lgkmcnt(0)
	v_mfma_f32_32x32x16_bf16 v[50:65], v[176:179], v[130:133], v[50:65]
	v_mfma_f32_32x32x16_bf16 v[18:33], v[176:179], v[146:149], v[18:33]
	s_add_u32 m0, s100, 0x10000
	s_mov_b64 exec, s[10:11]
	global_load_lds_dwordx4 v236, s[18:19]
	s_mov_b64 exec, -1
	v_add_u32_e32 v236, 0x80, v236
	v_mfma_f32_32x32x16_bf16 v[50:65], v[180:183], v[134:137], v[50:65]
	v_mfma_f32_32x32x16_bf16 v[18:33], v[180:183], v[150:153], v[18:33]
	s_add_u32 m0, s100, 0x12000
	s_mov_b64 exec, s[14:15]
	global_load_lds_dwordx4 v238, s[18:19]
	s_mov_b64 exec, -1
	v_add_u32_e32 v238, 0x80, v238
	v_mfma_f32_32x32x16_bf16 v[50:65], v[186:189], v[138:141], v[50:65]
	v_mfma_f32_32x32x16_bf16 v[18:33], v[186:189], v[158:161], v[18:33]
	v_mfma_f32_32x32x16_bf16 v[50:65], v[190:193], v[142:145], v[50:65]
	v_mfma_f32_32x32x16_bf16 v[18:33], v[190:193], v[162:165], v[18:33]
	s_barrier
	v_add3_u32 v166, v249, v244, 0
	v_add3_u32 v167, v249, v245, 0
	v_add3_u32 v175, v249, v246, 0
	v_add3_u32 v185, v249, v247, 0
	ds_read_b128 v[176:179], v166 offset:32768
	ds_read_b128 v[180:183], v167 offset:32768
	ds_read_b128 v[186:189], v175 offset:32768
	ds_read_b128 v[190:193], v185 offset:32768
	s_waitcnt vmcnt(4)
	s_barrier
	s_waitcnt lgkmcnt(0)
	v_mfma_f32_32x32x16_bf16 v[34:49], v[194:197], v[130:133], v[34:49]
	v_mfma_f32_32x32x16_bf16 v[2:17], v[194:197], v[146:149], v[2:17]
	s_add_u32 m0, s100, 0x1c000
	s_nop 0
	global_load_lds_dwordx4 v241, s[22:23]
	v_add_u32_e32 v241, 0x80, v241
	v_mfma_f32_32x32x16_bf16 v[34:49], v[198:201], v[134:137], v[34:49]
	v_mfma_f32_32x32x16_bf16 v[2:17], v[198:201], v[150:153], v[2:17]
	s_add_u32 m0, s100, 0x1e000
	s_nop 0
	global_load_lds_dwordx4 v243, s[22:23]
	v_add_u32_e32 v243, 0x80, v243
	v_mfma_f32_32x32x16_bf16 v[34:49], v[228:231], v[138:141], v[34:49]
	v_mfma_f32_32x32x16_bf16 v[2:17], v[228:231], v[158:161], v[2:17]
	v_mfma_f32_32x32x16_bf16 v[34:49], v[232:235], v[142:145], v[34:49]
	v_mfma_f32_32x32x16_bf16 v[2:17], v[232:235], v[162:165], v[2:17]
	s_barrier
	s_add_i32 s29, s29, 2
	s_cmp_lt_u32 s29, 14
	s_cbranch_scc1 .Lg8_u0m
	v_add3_u32 v166, v248, v244, 0
	v_add3_u32 v167, v248, v245, 0
	v_add3_u32 v175, v248, v246, 0
	v_add3_u32 v185, v248, v247, 0
	ds_read_b128 v[130:133], v166
	ds_read_b128 v[134:137], v167
	ds_read_b128 v[138:141], v175
	ds_read_b128 v[142:145], v185
	ds_read_b128 v[146:149], v166 offset:4096
	ds_read_b128 v[150:153], v167 offset:4096
	ds_read_b128 v[158:161], v175 offset:4096
	ds_read_b128 v[162:165], v185 offset:4096
	s_add_u32 m0, s100, 0x14000
	s_mov_b64 exec, s[12:13]
	global_load_lds_dwordx4 v237, s[18:19]
	s_mov_b64 exec, -1
	v_add_u32_e32 v237, 0x80, v237
	s_add_u32 m0, s100, 0x16000
	s_mov_b64 exec, s[16:17]
	global_load_lds_dwordx4 v239, s[18:19]
	s_mov_b64 exec, -1
	v_add_u32_e32 v239, 0x80, v239
	s_barrier
; #define MFMA(a, b, c) __builtin_amdgcn_mfma_f32_32x32x16_bf16((a), (b), (c), 0, 0, 0)
; template <bool SWAP>
; DI void gemm_mainloop(f32x16 (&acc)[4][2], const u16* __restrict__ A, int lda, int rlo, int rhi,
;                       const u16* __restrict__ B, int ldb, int K, char* lds, const u16* zero_line) {
;     ...
;   auto ldfrag = [&](const char* st, int ks, int buf) {
;     const int co = ((2 * ks + h) ^ sw) << 4;
; #pragma unroll
;     for (int mi = 0; mi < 4; ++mi) fa[buf][mi] = *(const bf16x8*)(st + arow_off + mi * 4096 + co);
; #pragma unroll
;     for (int ni = 0; ni < 2; ++ni) fb[buf][ni] = *(const bf16x8*)(st + brow_off + ni * 4096 + co);
;   };
;   auto mma = [&](int buf) {
; #pragma unroll
;     for (int mi = 0; mi < 4; ++mi)
; #pragma unroll
;       for (int ni = 0; ni < 2; ++ni)
;         acc[mi][ni] = SWAP ? MFMA(fb[buf][ni], fa[buf][mi], acc[mi][ni]) : MFMA(fa[buf][mi], fb[buf][ni], acc[mi][ni]);
;   };
;   auto pat_rd = [&]() {
; #pragma unroll
;     for (int g = 0; g < 6; ++g) {
;       __builtin_amdgcn_sched_group_barrier(0x100, 1, 0);
;       __builtin_amdgcn_sched_group_barrier(0x008, 1, 0);
;     }
;     __builtin_amdgcn_sched_group_barrier(0x008, 2, 0);
;   };
; #pragma unroll 2
;   for (int kt = 0; kt < nk; ++kt) {
;     const char* st = lds + (kt & 1) * 65536;
;     ldfrag(st, 0, 0);
;     mma(1);
;     pat_rd();
;     if (kt + 1 < nk) glds(kt + 1, (kt + 1) & 1);
;     ldfrag(st, 1, 1);
;     mma(0);
;     pat_rd();
;     ldfrag(st, 2, 0);
;     mma(1);
;     pat_rd();
;     ldfrag(st, 3, 1);
;     mma(0);
;     pat_rd();
;     asm volatile("s_waitcnt vmcnt(0)" ::: "memory");
;     __syncthreads();
;   }
;   mma(1);
	s_waitcnt lgkmcnt(0)
	v_mfma_f32_32x32x16_bf16 v[114:129], v[176:179], v[130:133], v[114:129]
	v_mfma_f32_32x32x16_bf16 v[82:97], v[176:179], v[146:149], v[82:97]
	v_mfma_f32_32x32x16_bf16 v[114:129], v[180:183], v[134:137], v[114:129]
	v_mfma_f32_32x32x16_bf16 v[82:97], v[180:183], v[150:153], v[82:97]
	v_mfma_f32_32x32x16_bf16 v[114:129], v[186:189], v[138:141], v[114:129]
	v_mfma_f32_32x32x16_bf16 v[82:97], v[186:189], v[158:161], v[82:97]
	v_mfma_f32_32x32x16_bf16 v[114:129], v[190:193], v[142:145], v[114:129]
	v_mfma_f32_32x32x16_bf16 v[82:97], v[190:193], v[162:165], v[82:97]
	s_barrier
	v_add3_u32 v166, v249, v244, 0
	v_add3_u32 v167, v249, v245, 0
	v_add3_u32 v175, v249, v246, 0
	v_add3_u32 v185, v249, v247, 0
	ds_read_b128 v[194:197], v166 offset:49152
	ds_read_b128 v[198:201], v167 offset:49152
	ds_read_b128 v[228:231], v175 offset:49152
	ds_read_b128 v[232:235], v185 offset:49152
	s_barrier
	s_waitcnt lgkmcnt(0)
	v_mfma_f32_32x32x16_bf16 v[98:113], v[194:197], v[130:133], v[98:113]
	v_mfma_f32_32x32x16_bf16 v[66:81], v[194:197], v[146:149], v[66:81]
	v_mfma_f32_32x32x16_bf16 v[98:113], v[198:201], v[134:137], v[98:113]
	v_mfma_f32_32x32x16_bf16 v[66:81], v[198:201], v[150:153], v[66:81]
	v_mfma_f32_32x32x16_bf16 v[98:113], v[228:231], v[138:141], v[98:113]
	v_mfma_f32_32x32x16_bf16 v[66:81], v[228:231], v[158:161], v[66:81]
	v_mfma_f32_32x32x16_bf16 v[98:113], v[232:235], v[142:145], v[98:113]
	v_mfma_f32_32x32x16_bf16 v[66:81], v[232:235], v[162:165], v[66:81]
	s_barrier
	v_add3_u32 v166, v248, v244, 0
	v_add3_u32 v167, v248, v245, 0
	v_add3_u32 v175, v248, v246, 0
	v_add3_u32 v185, v248, v247, 0
	ds_read_b128 v[130:133], v166 offset:16384
	ds_read_b128 v[134:137], v167 offset:16384
	ds_read_b128 v[138:141], v175 offset:16384
	ds_read_b128 v[142:145], v185 offset:16384
	ds_read_b128 v[146:149], v166 offset:20480
	ds_read_b128 v[150:153], v167 offset:20480
	ds_read_b128 v[158:161], v175 offset:20480
	ds_read_b128 v[162:165], v185 offset:20480
	s_waitcnt vmcnt(4)
	s_barrier
	s_waitcnt lgkmcnt(0)
	v_mfma_f32_32x32x16_bf16 v[50:65], v[176:179], v[130:133], v[50:65]
	v_mfma_f32_32x32x16_bf16 v[18:33], v[176:179], v[146:149], v[18:33]
	v_mfma_f32_32x32x16_bf16 v[50:65], v[180:183], v[134:137], v[50:65]
	v_mfma_f32_32x32x16_bf16 v[18:33], v[180:183], v[150:153], v[18:33]
	v_mfma_f32_32x32x16_bf16 v[50:65], v[186:189], v[138:141], v[50:65]
	v_mfma_f32_32x32x16_bf16 v[18:33], v[186:189], v[158:161], v[18:33]
	v_mfma_f32_32x32x16_bf16 v[50:65], v[190:193], v[142:145], v[50:65]
	v_mfma_f32_32x32x16_bf16 v[18:33], v[190:193], v[162:165], v[18:33]
	v_mfma_f32_32x32x16_bf16 v[34:49], v[194:197], v[130:133], v[34:49]
	v_mfma_f32_32x32x16_bf16 v[2:17], v[194:197], v[146:149], v[2:17]
	v_mfma_f32_32x32x16_bf16 v[34:49], v[198:201], v[134:137], v[34:49]
	v_mfma_f32_32x32x16_bf16 v[2:17], v[198:201], v[150:153], v[2:17]
	v_mfma_f32_32x32x16_bf16 v[34:49], v[228:231], v[138:141], v[34:49]
	v_mfma_f32_32x32x16_bf16 v[2:17], v[228:231], v[158:161], v[2:17]
	v_mfma_f32_32x32x16_bf16 v[34:49], v[232:235], v[142:145], v[34:49]
	v_mfma_f32_32x32x16_bf16 v[2:17], v[232:235], v[162:165], v[2:17]
	s_barrier
	v_add3_u32 v166, v249, v244, s21
	v_add3_u32 v167, v249, v245, s21
	v_add3_u32 v175, v249, v246, s21
	v_add3_u32 v185, v249, v247, s21
	ds_read_b128 v[176:179], v166 offset:32768
	ds_read_b128 v[180:183], v167 offset:32768
	ds_read_b128 v[186:189], v175 offset:32768
	ds_read_b128 v[190:193], v185 offset:32768
	v_add3_u32 v166, v248, v244, s21
	v_add3_u32 v167, v248, v245, s21
	v_add3_u32 v175, v248, v246, s21
	v_add3_u32 v185, v248, v247, s21
	ds_read_b128 v[130:133], v166
	ds_read_b128 v[134:137], v167
	ds_read_b128 v[138:141], v175
	ds_read_b128 v[142:145], v185
	ds_read_b128 v[146:149], v166 offset:4096
	ds_read_b128 v[150:153], v167 offset:4096
	ds_read_b128 v[158:161], v175 offset:4096
	ds_read_b128 v[162:165], v185 offset:4096
	s_waitcnt vmcnt(2)
	s_barrier
; #define MFMA(a, b, c) __builtin_amdgcn_mfma_f32_32x32x16_bf16((a), (b), (c), 0, 0, 0)
; template <bool SWAP>
; DI void gemm_mainloop(f32x16 (&acc)[4][2], const u16* __restrict__ A, int lda, int rlo, int rhi,
;                       const u16* __restrict__ B, int ldb, int K, char* lds, const u16* zero_line) {
;     ...
;   auto ldfrag = [&](const char* st, int ks, int buf) {
;     const int co = ((2 * ks + h) ^ sw) << 4;
; #pragma unroll
;     for (int mi = 0; mi < 4; ++mi) fa[buf][mi] = *(const bf16x8*)(st + arow_off + mi * 4096 + co);
; #pragma unroll
;     for (int ni = 0; ni < 2; ++ni) fb[buf][ni] = *(const bf16x8*)(st + brow_off + ni * 4096 + co);
;   };
;   auto mma = [&](int buf) {
; #pragma unroll
;     for (int mi = 0; mi < 4; ++mi)
; #pragma unroll
;       for (int ni = 0; ni < 2; ++ni)
;         acc[mi][ni] = SWAP ? MFMA(fb[buf][ni], fa[buf][mi], acc[mi][ni]) : MFMA(fa[buf][mi], fb[buf][ni], acc[mi][ni]);
;   };
;   auto pat_rd = [&]() {
; #pragma unroll
;     for (int g = 0; g < 6; ++g) {
;       __builtin_amdgcn_sched_group_barrier(0x100, 1, 0);
;       __builtin_amdgcn_sched_group_barrier(0x008, 1, 0);
;     }
;     __builtin_amdgcn_sched_group_barrier(0x008, 2, 0);
;   };
; #pragma unroll 2
;   for (int kt = 0; kt < nk; ++kt) {
;     const char* st = lds + (kt & 1) * 65536;
;     ldfrag(st, 0, 0);
;     mma(1);
;     pat_rd();
;     if (kt + 1 < nk) glds(kt + 1, (kt + 1) & 1);
;     ldfrag(st, 1, 1);
;     mma(0);
;     pat_rd();
;     ldfrag(st, 2, 0);
;     mma(1);
;     pat_rd();
;     ldfrag(st, 3, 1);
;     mma(0);
;     pat_rd();
;     asm volatile("s_waitcnt vmcnt(0)" ::: "memory");
;     __syncthreads();
;   }
;   mma(1);
	s_waitcnt lgkmcnt(0)
	v_mfma_f32_32x32x16_bf16 v[114:129], v[176:179], v[130:133], v[114:129]
	v_mfma_f32_32x32x16_bf16 v[82:97], v[176:179], v[146:149], v[82:97]
	v_mfma_f32_32x32x16_bf16 v[114:129], v[180:183], v[134:137], v[114:129]
	v_mfma_f32_32x32x16_bf16 v[82:97], v[180:183], v[150:153], v[82:97]
	v_mfma_f32_32x32x16_bf16 v[114:129], v[186:189], v[138:141], v[114:129]
	v_mfma_f32_32x32x16_bf16 v[82:97], v[186:189], v[158:161], v[82:97]
	v_mfma_f32_32x32x16_bf16 v[114:129], v[190:193], v[142:145], v[114:129]
	v_mfma_f32_32x32x16_bf16 v[82:97], v[190:193], v[162:165], v[82:97]
	s_barrier
	v_add3_u32 v166, v249, v244, s21
	v_add3_u32 v167, v249, v245, s21
	v_add3_u32 v175, v249, v246, s21
	v_add3_u32 v185, v249, v247, s21
	ds_read_b128 v[194:197], v166 offset:49152
	ds_read_b128 v[198:201], v167 offset:49152
	ds_read_b128 v[228:231], v175 offset:49152
	ds_read_b128 v[232:235], v185 offset:49152
	s_waitcnt vmcnt(0)
	s_barrier
	s_waitcnt lgkmcnt(0)
	v_mfma_f32_32x32x16_bf16 v[98:113], v[194:197], v[130:133], v[98:113]
	v_mfma_f32_32x32x16_bf16 v[66:81], v[194:197], v[146:149], v[66:81]
	v_mfma_f32_32x32x16_bf16 v[98:113], v[198:201], v[134:137], v[98:113]
	v_mfma_f32_32x32x16_bf16 v[66:81], v[198:201], v[150:153], v[66:81]
	v_mfma_f32_32x32x16_bf16 v[98:113], v[228:231], v[138:141], v[98:113]
	v_mfma_f32_32x32x16_bf16 v[66:81], v[228:231], v[158:161], v[66:81]
	v_mfma_f32_32x32x16_bf16 v[98:113], v[232:235], v[142:145], v[98:113]
	v_mfma_f32_32x32x16_bf16 v[66:81], v[232:235], v[162:165], v[66:81]
	s_barrier
	v_add3_u32 v166, v248, v244, s21
	v_add3_u32 v167, v248, v245, s21
	v_add3_u32 v175, v248, v246, s21
	v_add3_u32 v185, v248, v247, s21
	ds_read_b128 v[130:133], v166 offset:16384
	ds_read_b128 v[134:137], v167 offset:16384
	ds_read_b128 v[138:141], v175 offset:16384
	ds_read_b128 v[142:145], v185 offset:16384
	ds_read_b128 v[146:149], v166 offset:20480
	ds_read_b128 v[150:153], v167 offset:20480
	ds_read_b128 v[158:161], v175 offset:20480
	ds_read_b128 v[162:165], v185 offset:20480
	s_barrier
	s_waitcnt lgkmcnt(0)
	v_mfma_f32_32x32x16_bf16 v[50:65], v[176:179], v[130:133], v[50:65]
	v_mfma_f32_32x32x16_bf16 v[18:33], v[176:179], v[146:149], v[18:33]
	v_mfma_f32_32x32x16_bf16 v[50:65], v[180:183], v[134:137], v[50:65]
	v_mfma_f32_32x32x16_bf16 v[18:33], v[180:183], v[150:153], v[18:33]
	v_mfma_f32_32x32x16_bf16 v[50:65], v[186:189], v[138:141], v[50:65]
	v_mfma_f32_32x32x16_bf16 v[18:33], v[186:189], v[158:161], v[18:33]
	v_mfma_f32_32x32x16_bf16 v[50:65], v[190:193], v[142:145], v[50:65]
	v_mfma_f32_32x32x16_bf16 v[18:33], v[190:193], v[162:165], v[18:33]
	v_mfma_f32_32x32x16_bf16 v[34:49], v[194:197], v[130:133], v[34:49]
	v_mfma_f32_32x32x16_bf16 v[2:17], v[194:197], v[146:149], v[2:17]
	v_mfma_f32_32x32x16_bf16 v[34:49], v[198:201], v[134:137], v[34:49]
	v_mfma_f32_32x32x16_bf16 v[2:17], v[198:201], v[150:153], v[2:17]
	v_mfma_f32_32x32x16_bf16 v[34:49], v[228:231], v[138:141], v[34:49]
	v_mfma_f32_32x32x16_bf16 v[2:17], v[228:231], v[158:161], v[2:17]
	v_mfma_f32_32x32x16_bf16 v[34:49], v[232:235], v[142:145], v[34:49]
	v_mfma_f32_32x32x16_bf16 v[2:17], v[232:235], v[162:165], v[2:17]
	s_barrier
	s_cmp_eq_u32 s101, 0
	s_cbranch_scc0 .Lg8_u0m_p1
	s_barrier

; #define MFMA(a, b, c) __builtin_amdgcn_mfma_f32_32x32x16_bf16((a), (b), (c), 0, 0, 0)
; template <bool SWAP>
; DI void gemm_mainloop(f32x16 (&acc)[4][2], const u16* __restrict__ A, int lda, int rlo, int rhi,
;                       const u16* __restrict__ B, int ldb, int K, char* lds, const u16* zero_line) {
;     ...
;   auto glds = [&](int kt, int st) {
;     char* as_ = lds + st * 65536 + tid * 16;
; #pragma unroll
;     for (int i = 0; i < 4; ++i) {
;       const int rr = lr + 64 * i;
;       const u16* srca = (rr >= rlo && rr < rhi) ? (ap + (ptrdiff_t)(64 * i) * lda + kt * 64) : (zero_line + lc * 8);
;       __builtin_amdgcn_global_load_lds((const unsigned*)srca, (lds_u32*)(as_ + i * 8192), 16, 0, 0);
;       __builtin_amdgcn_global_load_lds((const unsigned*)(bp + (ptrdiff_t)(64 * i) * ldb + kt * 64), (lds_u32*)(as_ + 32768 + i * 8192), 16, 0, 0);
;     }
;   };
;     ...
;   auto ldfrag = [&](const char* st, int ks, int buf) {
;     const int co = ((2 * ks + h) ^ sw) << 4;
; #pragma unroll
;     for (int mi = 0; mi < 4; ++mi) fa[buf][mi] = *(const bf16x8*)(st + arow_off + mi * 4096 + co);
; #pragma unroll
;     for (int ni = 0; ni < 2; ++ni) fb[buf][ni] = *(const bf16x8*)(st + brow_off + ni * 4096 + co);
;   };
;   auto mma = [&](int buf) {
; #pragma unroll
;     for (int mi = 0; mi < 4; ++mi)
; #pragma unroll
;       for (int ni = 0; ni < 2; ++ni)
;         acc[mi][ni] = SWAP ? MFMA(fb[buf][ni], fa[buf][mi], acc[mi][ni]) : MFMA(fa[buf][mi], fb[buf][ni], acc[mi][ni]);
;   };
;   auto pat_rd = [&]() {
; #pragma unroll
;     for (int g = 0; g < 6; ++g) {
;       __builtin_amdgcn_sched_group_barrier(0x100, 1, 0);
;       __builtin_amdgcn_sched_group_barrier(0x008, 1, 0);
;     }
;     __builtin_amdgcn_sched_group_barrier(0x008, 2, 0);
;   };
; #pragma unroll 2
;   for (int kt = 0; kt < nk; ++kt) {
;     const char* st = lds + (kt & 1) * 65536;
;     ldfrag(st, 0, 0);
;     mma(1);
;     pat_rd();
;     if (kt + 1 < nk) glds(kt + 1, (kt + 1) & 1);
;     ldfrag(st, 1, 1);
;     mma(0);
;     pat_rd();
;     ldfrag(st, 2, 0);
;     mma(1);
;     pat_rd();
;     ldfrag(st, 3, 1);
;     mma(0);
;     pat_rd();
;     asm volatile("s_waitcnt vmcnt(0)" ::: "memory");
;     __syncthreads();
;   }
.Lg8_qa:
	v_add3_u32 v246, v244, v240, 0
	v_add3_u32 v247, v244, v241, 0
	v_add3_u32 v248, v244, v242, 0
	v_add3_u32 v249, v244, v243, 0
	ds_read_b128 v[130:133], v246
	ds_read_b128 v[134:137], v247
	ds_read_b128 v[138:141], v248
	ds_read_b128 v[142:145], v249
	ds_read_b128 v[146:149], v246 offset:4096
	ds_read_b128 v[150:153], v247 offset:4096
	ds_read_b128 v[156:159], v248 offset:4096
	ds_read_b128 v[160:163], v249 offset:4096
	s_barrier
	s_waitcnt lgkmcnt(0)
	v_mfma_f32_32x32x16_bf16 v[114:129], v[130:133], v[170:173], v[114:129]
	v_mfma_f32_32x32x16_bf16 v[82:97], v[146:149], v[170:173], v[82:97]
	s_add_u32 m0, s100, 0x14000
	s_nop 0
	global_load_lds_dwordx4 v233, s[6:7]
	v_add_u32_e32 v233, 0x80, v233
	v_mfma_f32_32x32x16_bf16 v[114:129], v[134:137], v[174:177], v[114:129]
	v_mfma_f32_32x32x16_bf16 v[82:97], v[150:153], v[174:177], v[82:97]
	s_add_u32 m0, s100, 0x16000
	s_nop 0
	global_load_lds_dwordx4 v235, s[6:7]
	v_add_u32_e32 v235, 0x80, v235
	v_mfma_f32_32x32x16_bf16 v[114:129], v[138:141], v[178:181], v[114:129]
	v_mfma_f32_32x32x16_bf16 v[82:97], v[156:159], v[178:181], v[82:97]
	v_mfma_f32_32x32x16_bf16 v[114:129], v[142:145], v[186:189], v[114:129]
	v_mfma_f32_32x32x16_bf16 v[82:97], v[160:163], v[186:189], v[82:97]
	s_barrier
	v_add3_u32 v246, v245, v240, 0
	v_add3_u32 v247, v245, v241, 0
	v_add3_u32 v248, v245, v242, 0
	v_add3_u32 v249, v245, v243, 0
	ds_read_b128 v[190:193], v246 offset:49152
	ds_read_b128 v[194:197], v247 offset:49152
	ds_read_b128 v[198:201], v248 offset:49152
	ds_read_b128 v[228:231], v249 offset:49152
	s_barrier
	s_waitcnt lgkmcnt(0)
	v_mfma_f32_32x32x16_bf16 v[98:113], v[130:133], v[190:193], v[98:113]
	v_mfma_f32_32x32x16_bf16 v[66:81], v[146:149], v[190:193], v[66:81]
	s_add_u32 m0, s100, 0x8000
	s_nop 0
	global_load_lds_dwordx4 v236, s[8:9]
	v_add_u32_e32 v236, 0x80, v236
	v_mfma_f32_32x32x16_bf16 v[98:113], v[134:137], v[194:197], v[98:113]
	v_mfma_f32_32x32x16_bf16 v[66:81], v[150:153], v[194:197], v[66:81]
	s_add_u32 m0, s100, 0xa000
	s_nop 0
	global_load_lds_dwordx4 v238, s[8:9]
	v_add_u32_e32 v238, 0x80, v238
	v_mfma_f32_32x32x16_bf16 v[98:113], v[138:141], v[198:201], v[98:113]
	v_mfma_f32_32x32x16_bf16 v[66:81], v[156:159], v[198:201], v[66:81]
	v_mfma_f32_32x32x16_bf16 v[98:113], v[142:145], v[228:231], v[98:113]
	v_mfma_f32_32x32x16_bf16 v[66:81], v[160:163], v[228:231], v[66:81]
	s_barrier
	v_add3_u32 v246, v244, v240, 0
	v_add3_u32 v247, v244, v241, 0
	v_add3_u32 v248, v244, v242, 0
	v_add3_u32 v249, v244, v243, 0
	ds_read_b128 v[130:133], v246 offset:16384
	ds_read_b128 v[134:137], v247 offset:16384
	ds_read_b128 v[138:141], v248 offset:16384
	ds_read_b128 v[142:145], v249 offset:16384
	ds_read_b128 v[146:149], v246 offset:20480
	ds_read_b128 v[150:153], v247 offset:20480
	ds_read_b128 v[156:159], v248 offset:20480
	ds_read_b128 v[160:163], v249 offset:20480
	s_waitcnt vmcnt(8)
	s_barrier
	s_waitcnt lgkmcnt(0)
	v_mfma_f32_32x32x16_bf16 v[50:65], v[130:133], v[170:173], v[50:65]
	v_mfma_f32_32x32x16_bf16 v[18:33], v[146:149], v[170:173], v[18:33]
	s_add_u32 m0, s100, 0x0
	s_nop 0
	global_load_lds_dwordx4 v232, s[6:7]
	v_add_u32_e32 v232, 0x80, v232
	v_mfma_f32_32x32x16_bf16 v[50:65], v[134:137], v[174:177], v[50:65]
	v_mfma_f32_32x32x16_bf16 v[18:33], v[150:153], v[174:177], v[18:33]
	s_add_u32 m0, s100, 0x2000
	s_nop 0
	global_load_lds_dwordx4 v234, s[6:7]
	v_add_u32_e32 v234, 0x80, v234
	v_mfma_f32_32x32x16_bf16 v[50:65], v[138:141], v[178:181], v[50:65]
	v_mfma_f32_32x32x16_bf16 v[18:33], v[156:159], v[178:181], v[18:33]
	v_mfma_f32_32x32x16_bf16 v[50:65], v[142:145], v[186:189], v[50:65]
	v_mfma_f32_32x32x16_bf16 v[18:33], v[160:163], v[186:189], v[18:33]
	s_barrier
	v_add3_u32 v246, v245, v240, s10
	v_add3_u32 v247, v245, v241, s10
	v_add3_u32 v248, v245, v242, s10
	v_add3_u32 v249, v245, v243, s10
	ds_read_b128 v[170:173], v246 offset:32768
	ds_read_b128 v[174:177], v247 offset:32768
	ds_read_b128 v[178:181], v248 offset:32768
	ds_read_b128 v[186:189], v249 offset:32768
	s_waitcnt vmcnt(4)
	s_barrier
	s_waitcnt lgkmcnt(0)
	v_mfma_f32_32x32x16_bf16 v[34:49], v[130:133], v[190:193], v[34:49]
	v_mfma_f32_32x32x16_bf16 v[2:17], v[146:149], v[190:193], v[2:17]
	s_add_u32 m0, s100, 0xc000
	s_nop 0
	global_load_lds_dwordx4 v237, s[8:9]
	v_add_u32_e32 v237, 0x80, v237
	v_mfma_f32_32x32x16_bf16 v[34:49], v[134:137], v[194:197], v[34:49]
	v_mfma_f32_32x32x16_bf16 v[2:17], v[150:153], v[194:197], v[2:17]
	s_add_u32 m0, s100, 0xe000
	s_nop 0
	global_load_lds_dwordx4 v239, s[8:9]
	v_add_u32_e32 v239, 0x80, v239
	v_mfma_f32_32x32x16_bf16 v[34:49], v[138:141], v[198:201], v[34:49]
	v_mfma_f32_32x32x16_bf16 v[2:17], v[156:159], v[198:201], v[2:17]
	v_mfma_f32_32x32x16_bf16 v[34:49], v[142:145], v[228:231], v[34:49]
	v_mfma_f32_32x32x16_bf16 v[2:17], v[160:163], v[228:231], v[2:17]
	s_barrier
	v_add3_u32 v246, v244, v240, s10
	v_add3_u32 v247, v244, v241, s10
	v_add3_u32 v248, v244, v242, s10
	v_add3_u32 v249, v244, v243, s10
	ds_read_b128 v[130:133], v246
	ds_read_b128 v[134:137], v247
	ds_read_b128 v[138:141], v248
	ds_read_b128 v[142:145], v249
	ds_read_b128 v[146:149], v246 offset:4096
	ds_read_b128 v[150:153], v247 offset:4096
	ds_read_b128 v[156:159], v248 offset:4096
	ds_read_b128 v[160:163], v249 offset:4096
	s_barrier
; #define MFMA(a, b, c) __builtin_amdgcn_mfma_f32_32x32x16_bf16((a), (b), (c), 0, 0, 0)
; template <bool SWAP>
; DI void gemm_mainloop(f32x16 (&acc)[4][2], const u16* __restrict__ A, int lda, int rlo, int rhi,
;                       const u16* __restrict__ B, int ldb, int K, char* lds, const u16* zero_line) {
;     ...
;   auto glds = [&](int kt, int st) {
;     char* as_ = lds + st * 65536 + tid * 16;
; #pragma unroll
;     for (int i = 0; i < 4; ++i) {
;       const int rr = lr + 64 * i;
;       const u16* srca = (rr >= rlo && rr < rhi) ? (ap + (ptrdiff_t)(64 * i) * lda + kt * 64) : (zero_line + lc * 8);
;       __builtin_amdgcn_global_load_lds((const unsigned*)srca, (lds_u32*)(as_ + i * 8192), 16, 0, 0);
;       __builtin_amdgcn_global_load_lds((const unsigned*)(bp + (ptrdiff_t)(64 * i) * ldb + kt * 64), (lds_u32*)(as_ + 32768 + i * 8192), 16, 0, 0);
;     }
;   };
;     ...
;   auto ldfrag = [&](const char* st, int ks, int buf) {
;     const int co = ((2 * ks + h) ^ sw) << 4;
; #pragma unroll
;     for (int mi = 0; mi < 4; ++mi) fa[buf][mi] = *(const bf16x8*)(st + arow_off + mi * 4096 + co);
; #pragma unroll
;     for (int ni = 0; ni < 2; ++ni) fb[buf][ni] = *(const bf16x8*)(st + brow_off + ni * 4096 + co);
;   };
;   auto mma = [&](int buf) {
; #pragma unroll
;     for (int mi = 0; mi < 4; ++mi)
; #pragma unroll
;       for (int ni = 0; ni < 2; ++ni)
;         acc[mi][ni] = SWAP ? MFMA(fb[buf][ni], fa[buf][mi], acc[mi][ni]) : MFMA(fa[buf][mi], fb[buf][ni], acc[mi][ni]);
;   };
;   auto pat_rd = [&]() {
; #pragma unroll
;     for (int g = 0; g < 6; ++g) {
;       __builtin_amdgcn_sched_group_barrier(0x100, 1, 0);
;       __builtin_amdgcn_sched_group_barrier(0x008, 1, 0);
;     }
;     __builtin_amdgcn_sched_group_barrier(0x008, 2, 0);
;   };
; #pragma unroll 2
;   for (int kt = 0; kt < nk; ++kt) {
;     const char* st = lds + (kt & 1) * 65536;
;     ldfrag(st, 0, 0);
;     mma(1);
;     pat_rd();
;     if (kt + 1 < nk) glds(kt + 1, (kt + 1) & 1);
;     ldfrag(st, 1, 1);
;     mma(0);
;     pat_rd();
;     ldfrag(st, 2, 0);
;     mma(1);
;     pat_rd();
;     ldfrag(st, 3, 1);
;     mma(0);
;     pat_rd();
;     asm volatile("s_waitcnt vmcnt(0)" ::: "memory");
;     __syncthreads();
;   }
	s_waitcnt lgkmcnt(0)
	v_mfma_f32_32x32x16_bf16 v[114:129], v[130:133], v[170:173], v[114:129]
	v_mfma_f32_32x32x16_bf16 v[82:97], v[146:149], v[170:173], v[82:97]
	s_add_u32 m0, s100, 0x4000
	s_nop 0
	global_load_lds_dwordx4 v233, s[6:7]
	v_add_u32_e32 v233, 0x80, v233
	v_mfma_f32_32x32x16_bf16 v[114:129], v[134:137], v[174:177], v[114:129]
	v_mfma_f32_32x32x16_bf16 v[82:97], v[150:153], v[174:177], v[82:97]
	s_add_u32 m0, s100, 0x6000
	s_nop 0
	global_load_lds_dwordx4 v235, s[6:7]
	v_add_u32_e32 v235, 0x80, v235
	v_mfma_f32_32x32x16_bf16 v[114:129], v[138:141], v[178:181], v[114:129]
	v_mfma_f32_32x32x16_bf16 v[82:97], v[156:159], v[178:181], v[82:97]
	v_mfma_f32_32x32x16_bf16 v[114:129], v[142:145], v[186:189], v[114:129]
	v_mfma_f32_32x32x16_bf16 v[82:97], v[160:163], v[186:189], v[82:97]
	s_barrier
	v_add3_u32 v246, v245, v240, s10
	v_add3_u32 v247, v245, v241, s10
	v_add3_u32 v248, v245, v242, s10
	v_add3_u32 v249, v245, v243, s10
	ds_read_b128 v[190:193], v246 offset:49152
	ds_read_b128 v[194:197], v247 offset:49152
	ds_read_b128 v[198:201], v248 offset:49152
	ds_read_b128 v[228:231], v249 offset:49152
	s_barrier
	s_waitcnt lgkmcnt(0)
	v_mfma_f32_32x32x16_bf16 v[98:113], v[130:133], v[190:193], v[98:113]
	v_mfma_f32_32x32x16_bf16 v[66:81], v[146:149], v[190:193], v[66:81]
	s_add_u32 m0, s100, 0x18000
	s_nop 0
	global_load_lds_dwordx4 v236, s[8:9]
	v_add_u32_e32 v236, 0x80, v236
	v_mfma_f32_32x32x16_bf16 v[98:113], v[134:137], v[194:197], v[98:113]
	v_mfma_f32_32x32x16_bf16 v[66:81], v[150:153], v[194:197], v[66:81]
	s_add_u32 m0, s100, 0x1a000
	s_nop 0
	global_load_lds_dwordx4 v238, s[8:9]
	v_add_u32_e32 v238, 0x80, v238
	v_mfma_f32_32x32x16_bf16 v[98:113], v[138:141], v[198:201], v[98:113]
	v_mfma_f32_32x32x16_bf16 v[66:81], v[156:159], v[198:201], v[66:81]
	v_mfma_f32_32x32x16_bf16 v[98:113], v[142:145], v[228:231], v[98:113]
	v_mfma_f32_32x32x16_bf16 v[66:81], v[160:163], v[228:231], v[66:81]
	s_barrier
	v_add3_u32 v246, v244, v240, s10
	v_add3_u32 v247, v244, v241, s10
	v_add3_u32 v248, v244, v242, s10
	v_add3_u32 v249, v244, v243, s10
	ds_read_b128 v[130:133], v246 offset:16384
	ds_read_b128 v[134:137], v247 offset:16384
	ds_read_b128 v[138:141], v248 offset:16384
	ds_read_b128 v[142:145], v249 offset:16384
	ds_read_b128 v[146:149], v246 offset:20480
	ds_read_b128 v[150:153], v247 offset:20480
	ds_read_b128 v[156:159], v248 offset:20480
	ds_read_b128 v[160:163], v249 offset:20480
	s_waitcnt vmcnt(8)
	s_barrier
	s_waitcnt lgkmcnt(0)
	v_mfma_f32_32x32x16_bf16 v[50:65], v[130:133], v[170:173], v[50:65]
	v_mfma_f32_32x32x16_bf16 v[18:33], v[146:149], v[170:173], v[18:33]
	s_add_u32 m0, s100, 0x10000
	s_nop 0
	global_load_lds_dwordx4 v232, s[6:7]
	v_add_u32_e32 v232, 0x80, v232
	v_mfma_f32_32x32x16_bf16 v[50:65], v[134:137], v[174:177], v[50:65]
	v_mfma_f32_32x32x16_bf16 v[18:33], v[150:153], v[174:177], v[18:33]
	s_add_u32 m0, s100, 0x12000
	s_nop 0
	global_load_lds_dwordx4 v234, s[6:7]
	v_add_u32_e32 v234, 0x80, v234
	v_mfma_f32_32x32x16_bf16 v[50:65], v[138:141], v[178:181], v[50:65]
	v_mfma_f32_32x32x16_bf16 v[18:33], v[156:159], v[178:181], v[18:33]
	v_mfma_f32_32x32x16_bf16 v[50:65], v[142:145], v[186:189], v[50:65]
	v_mfma_f32_32x32x16_bf16 v[18:33], v[160:163], v[186:189], v[18:33]
	s_barrier
	v_add3_u32 v246, v245, v240, 0
	v_add3_u32 v247, v245, v241, 0
	v_add3_u32 v248, v245, v242, 0
	v_add3_u32 v249, v245, v243, 0
	ds_read_b128 v[170:173], v246 offset:32768
	ds_read_b128 v[174:177], v247 offset:32768
	ds_read_b128 v[178:181], v248 offset:32768
	ds_read_b128 v[186:189], v249 offset:32768
	s_waitcnt vmcnt(4)
	s_barrier
	s_waitcnt lgkmcnt(0)
	v_mfma_f32_32x32x16_bf16 v[34:49], v[130:133], v[190:193], v[34:49]
	v_mfma_f32_32x32x16_bf16 v[2:17], v[146:149], v[190:193], v[2:17]
	s_add_u32 m0, s100, 0x1c000
	s_nop 0
	global_load_lds_dwordx4 v237, s[8:9]
	v_add_u32_e32 v237, 0x80, v237
	v_mfma_f32_32x32x16_bf16 v[34:49], v[134:137], v[194:197], v[34:49]
	v_mfma_f32_32x32x16_bf16 v[2:17], v[150:153], v[194:197], v[2:17]
	s_add_u32 m0, s100, 0x1e000
	s_nop 0
	global_load_lds_dwordx4 v239, s[8:9]
	v_add_u32_e32 v239, 0x80, v239
	v_mfma_f32_32x32x16_bf16 v[34:49], v[138:141], v[198:201], v[34:49]
	v_mfma_f32_32x32x16_bf16 v[2:17], v[156:159], v[198:201], v[2:17]
	v_mfma_f32_32x32x16_bf16 v[34:49], v[142:145], v[228:231], v[34:49]
	v_mfma_f32_32x32x16_bf16 v[2:17], v[160:163], v[228:231], v[2:17]
	s_barrier
	s_add_i32 s11, s11, 2
	s_cmp_lt_u32 s11, 14
	s_cbranch_scc1 .Lg8_qa
	v_add3_u32 v246, v244, v240, 0
	v_add3_u32 v247, v244, v241, 0
	v_add3_u32 v248, v244, v242, 0
	v_add3_u32 v249, v244, v243, 0
	ds_read_b128 v[130:133], v246
	ds_read_b128 v[134:137], v247
	ds_read_b128 v[138:141], v248
	ds_read_b128 v[142:145], v249
	ds_read_b128 v[146:149], v246 offset:4096
	ds_read_b128 v[150:153], v247 offset:4096
	ds_read_b128 v[156:159], v248 offset:4096
	ds_read_b128 v[160:163], v249 offset:4096
	s_add_u32 m0, s100, 0x14000
	s_nop 0
	global_load_lds_dwordx4 v233, s[6:7]
	v_add_u32_e32 v233, 0x80, v233
	s_add_u32 m0, s100, 0x16000
	s_nop 0
	global_load_lds_dwordx4 v235, s[6:7]
	v_add_u32_e32 v235, 0x80, v235
	s_barrier
	s_waitcnt lgkmcnt(0)
	v_mfma_f32_32x32x16_bf16 v[114:129], v[130:133], v[170:173], v[114:129]
	v_mfma_f32_32x32x16_bf16 v[82:97], v[146:149], v[170:173], v[82:97]
	v_mfma_f32_32x32x16_bf16 v[114:129], v[134:137], v[174:177], v[114:129]
	v_mfma_f32_32x32x16_bf16 v[82:97], v[150:153], v[174:177], v[82:97]
	v_mfma_f32_32x32x16_bf16 v[114:129], v[138:141], v[178:181], v[114:129]
	v_mfma_f32_32x32x16_bf16 v[82:97], v[156:159], v[178:181], v[82:97]
	v_mfma_f32_32x32x16_bf16 v[114:129], v[142:145], v[186:189], v[114:129]
	v_mfma_f32_32x32x16_bf16 v[82:97], v[160:163], v[186:189], v[82:97]
	s_barrier
; #define MFMA(a, b, c) __builtin_amdgcn_mfma_f32_32x32x16_bf16((a), (b), (c), 0, 0, 0)
; template <bool SWAP>
; DI void gemm_mainloop(f32x16 (&acc)[4][2], const u16* __restrict__ A, int lda, int rlo, int rhi,
;                       const u16* __restrict__ B, int ldb, int K, char* lds, const u16* zero_line) {
;     ...
;   auto ldfrag = [&](const char* st, int ks, int buf) {
;     const int co = ((2 * ks + h) ^ sw) << 4;
; #pragma unroll
;     for (int mi = 0; mi < 4; ++mi) fa[buf][mi] = *(const bf16x8*)(st + arow_off + mi * 4096 + co);
; #pragma unroll
;     for (int ni = 0; ni < 2; ++ni) fb[buf][ni] = *(const bf16x8*)(st + brow_off + ni * 4096 + co);
;   };
;   auto mma = [&](int buf) {
; #pragma unroll
;     for (int mi = 0; mi < 4; ++mi)
; #pragma unroll
;       for (int ni = 0; ni < 2; ++ni)
;         acc[mi][ni] = SWAP ? MFMA(fb[buf][ni], fa[buf][mi], acc[mi][ni]) : MFMA(fa[buf][mi], fb[buf][ni], acc[mi][ni]);
;   };
;   auto pat_rd = [&]() {
; #pragma unroll
;     for (int g = 0; g < 6; ++g) {
;       __builtin_amdgcn_sched_group_barrier(0x100, 1, 0);
;       __builtin_amdgcn_sched_group_barrier(0x008, 1, 0);
;     }
;     __builtin_amdgcn_sched_group_barrier(0x008, 2, 0);
;   };
; #pragma unroll 2
;   for (int kt = 0; kt < nk; ++kt) {
;     const char* st = lds + (kt & 1) * 65536;
;     ldfrag(st, 0, 0);
;     mma(1);
;     pat_rd();
;     if (kt + 1 < nk) glds(kt + 1, (kt + 1) & 1);
;     ldfrag(st, 1, 1);
;     mma(0);
;     pat_rd();
;     ldfrag(st, 2, 0);
;     mma(1);
;     pat_rd();
;     ldfrag(st, 3, 1);
;     mma(0);
;     pat_rd();
;     asm volatile("s_waitcnt vmcnt(0)" ::: "memory");
;     __syncthreads();
;   }
;   mma(1);
	v_add3_u32 v246, v245, v240, 0
	v_add3_u32 v247, v245, v241, 0
	v_add3_u32 v248, v245, v242, 0
	v_add3_u32 v249, v245, v243, 0
	ds_read_b128 v[190:193], v246 offset:49152
	ds_read_b128 v[194:197], v247 offset:49152
	ds_read_b128 v[198:201], v248 offset:49152
	ds_read_b128 v[228:231], v249 offset:49152
	s_barrier
	s_waitcnt lgkmcnt(0)
	v_mfma_f32_32x32x16_bf16 v[98:113], v[130:133], v[190:193], v[98:113]
	v_mfma_f32_32x32x16_bf16 v[66:81], v[146:149], v[190:193], v[66:81]
	v_mfma_f32_32x32x16_bf16 v[98:113], v[134:137], v[194:197], v[98:113]
	v_mfma_f32_32x32x16_bf16 v[66:81], v[150:153], v[194:197], v[66:81]
	v_mfma_f32_32x32x16_bf16 v[98:113], v[138:141], v[198:201], v[98:113]
	v_mfma_f32_32x32x16_bf16 v[66:81], v[156:159], v[198:201], v[66:81]
	v_mfma_f32_32x32x16_bf16 v[98:113], v[142:145], v[228:231], v[98:113]
	v_mfma_f32_32x32x16_bf16 v[66:81], v[160:163], v[228:231], v[66:81]
	s_barrier
	v_add3_u32 v246, v244, v240, 0
	v_add3_u32 v247, v244, v241, 0
	v_add3_u32 v248, v244, v242, 0
	v_add3_u32 v249, v244, v243, 0
	ds_read_b128 v[130:133], v246 offset:16384
	ds_read_b128 v[134:137], v247 offset:16384
	ds_read_b128 v[138:141], v248 offset:16384
	ds_read_b128 v[142:145], v249 offset:16384
	ds_read_b128 v[146:149], v246 offset:20480
	ds_read_b128 v[150:153], v247 offset:20480
	ds_read_b128 v[156:159], v248 offset:20480
	ds_read_b128 v[160:163], v249 offset:20480
	s_waitcnt vmcnt(4)
	s_barrier
	s_waitcnt lgkmcnt(0)
	v_mfma_f32_32x32x16_bf16 v[50:65], v[130:133], v[170:173], v[50:65]
	v_mfma_f32_32x32x16_bf16 v[18:33], v[146:149], v[170:173], v[18:33]
	v_mfma_f32_32x32x16_bf16 v[50:65], v[134:137], v[174:177], v[50:65]
	v_mfma_f32_32x32x16_bf16 v[18:33], v[150:153], v[174:177], v[18:33]
	v_mfma_f32_32x32x16_bf16 v[50:65], v[138:141], v[178:181], v[50:65]
	v_mfma_f32_32x32x16_bf16 v[18:33], v[156:159], v[178:181], v[18:33]
	v_mfma_f32_32x32x16_bf16 v[50:65], v[142:145], v[186:189], v[50:65]
	v_mfma_f32_32x32x16_bf16 v[18:33], v[160:163], v[186:189], v[18:33]
	v_mfma_f32_32x32x16_bf16 v[34:49], v[130:133], v[190:193], v[34:49]
	v_mfma_f32_32x32x16_bf16 v[2:17], v[146:149], v[190:193], v[2:17]
	v_mfma_f32_32x32x16_bf16 v[34:49], v[134:137], v[194:197], v[34:49]
	v_mfma_f32_32x32x16_bf16 v[2:17], v[150:153], v[194:197], v[2:17]
	v_mfma_f32_32x32x16_bf16 v[34:49], v[138:141], v[198:201], v[34:49]
	v_mfma_f32_32x32x16_bf16 v[2:17], v[156:159], v[198:201], v[2:17]
	v_mfma_f32_32x32x16_bf16 v[34:49], v[142:145], v[228:231], v[34:49]
	v_mfma_f32_32x32x16_bf16 v[2:17], v[160:163], v[228:231], v[2:17]
	s_barrier
	v_add3_u32 v246, v245, v240, s10
	v_add3_u32 v247, v245, v241, s10
	v_add3_u32 v248, v245, v242, s10
	v_add3_u32 v249, v245, v243, s10
	ds_read_b128 v[170:173], v246 offset:32768
	ds_read_b128 v[174:177], v247 offset:32768
	ds_read_b128 v[178:181], v248 offset:32768
	ds_read_b128 v[186:189], v249 offset:32768
	v_add3_u32 v246, v244, v240, s10
	v_add3_u32 v247, v244, v241, s10
	v_add3_u32 v248, v244, v242, s10
	v_add3_u32 v249, v244, v243, s10
	ds_read_b128 v[130:133], v246
	ds_read_b128 v[134:137], v247
	ds_read_b128 v[138:141], v248
	ds_read_b128 v[142:145], v249
	ds_read_b128 v[146:149], v246 offset:4096
	ds_read_b128 v[150:153], v247 offset:4096
	ds_read_b128 v[156:159], v248 offset:4096
	ds_read_b128 v[160:163], v249 offset:4096
	s_waitcnt vmcnt(2)
	s_barrier
	s_waitcnt lgkmcnt(0)
	v_mfma_f32_32x32x16_bf16 v[114:129], v[130:133], v[170:173], v[114:129]
	v_mfma_f32_32x32x16_bf16 v[82:97], v[146:149], v[170:173], v[82:97]
	v_mfma_f32_32x32x16_bf16 v[114:129], v[134:137], v[174:177], v[114:129]
	v_mfma_f32_32x32x16_bf16 v[82:97], v[150:153], v[174:177], v[82:97]
	v_mfma_f32_32x32x16_bf16 v[114:129], v[138:141], v[178:181], v[114:129]
	v_mfma_f32_32x32x16_bf16 v[82:97], v[156:159], v[178:181], v[82:97]
	v_mfma_f32_32x32x16_bf16 v[114:129], v[142:145], v[186:189], v[114:129]
	v_mfma_f32_32x32x16_bf16 v[82:97], v[160:163], v[186:189], v[82:97]
	s_barrier
	v_add3_u32 v246, v245, v240, s10
	v_add3_u32 v247, v245, v241, s10
	v_add3_u32 v248, v245, v242, s10
	v_add3_u32 v249, v245, v243, s10
	ds_read_b128 v[190:193], v246 offset:49152
	ds_read_b128 v[194:197], v247 offset:49152
	ds_read_b128 v[198:201], v248 offset:49152
	ds_read_b128 v[228:231], v249 offset:49152
	s_waitcnt vmcnt(0)
	s_barrier
	s_waitcnt lgkmcnt(0)
	v_mfma_f32_32x32x16_bf16 v[98:113], v[130:133], v[190:193], v[98:113]
	v_mfma_f32_32x32x16_bf16 v[66:81], v[146:149], v[190:193], v[66:81]
	v_mfma_f32_32x32x16_bf16 v[98:113], v[134:137], v[194:197], v[98:113]
	v_mfma_f32_32x32x16_bf16 v[66:81], v[150:153], v[194:197], v[66:81]
	v_mfma_f32_32x32x16_bf16 v[98:113], v[138:141], v[198:201], v[98:113]
	v_mfma_f32_32x32x16_bf16 v[66:81], v[156:159], v[198:201], v[66:81]
	v_mfma_f32_32x32x16_bf16 v[98:113], v[142:145], v[228:231], v[98:113]
	v_mfma_f32_32x32x16_bf16 v[66:81], v[160:163], v[228:231], v[66:81]
	s_barrier
	v_add3_u32 v246, v244, v240, s10
	v_add3_u32 v247, v244, v241, s10
	v_add3_u32 v248, v244, v242, s10
	v_add3_u32 v249, v244, v243, s10
	ds_read_b128 v[130:133], v246 offset:16384
	ds_read_b128 v[134:137], v247 offset:16384
	ds_read_b128 v[138:141], v248 offset:16384
	ds_read_b128 v[142:145], v249 offset:16384
	ds_read_b128 v[146:149], v246 offset:20480
	ds_read_b128 v[150:153], v247 offset:20480
	ds_read_b128 v[156:159], v248 offset:20480
	ds_read_b128 v[160:163], v249 offset:20480
	s_barrier
	s_waitcnt lgkmcnt(0)
	v_mfma_f32_32x32x16_bf16 v[50:65], v[130:133], v[170:173], v[50:65]
	v_mfma_f32_32x32x16_bf16 v[18:33], v[146:149], v[170:173], v[18:33]
	v_mfma_f32_32x32x16_bf16 v[50:65], v[134:137], v[174:177], v[50:65]
	v_mfma_f32_32x32x16_bf16 v[18:33], v[150:153], v[174:177], v[18:33]
	v_mfma_f32_32x32x16_bf16 v[50:65], v[138:141], v[178:181], v[50:65]
	v_mfma_f32_32x32x16_bf16 v[18:33], v[156:159], v[178:181], v[18:33]
	v_mfma_f32_32x32x16_bf16 v[50:65], v[142:145], v[186:189], v[50:65]
	v_mfma_f32_32x32x16_bf16 v[18:33], v[160:163], v[186:189], v[18:33]
	v_mfma_f32_32x32x16_bf16 v[34:49], v[130:133], v[190:193], v[34:49]
	v_mfma_f32_32x32x16_bf16 v[2:17], v[146:149], v[190:193], v[2:17]
	v_mfma_f32_32x32x16_bf16 v[34:49], v[134:137], v[194:197], v[34:49]
	v_mfma_f32_32x32x16_bf16 v[2:17], v[150:153], v[194:197], v[2:17]
	v_mfma_f32_32x32x16_bf16 v[34:49], v[138:141], v[198:201], v[34:49]
	v_mfma_f32_32x32x16_bf16 v[2:17], v[156:159], v[198:201], v[2:17]
	v_mfma_f32_32x32x16_bf16 v[34:49], v[142:145], v[228:231], v[34:49]
	v_mfma_f32_32x32x16_bf16 v[2:17], v[160:163], v[228:231], v[2:17]
	s_barrier
	s_cmp_eq_u32 s101, 0
	s_cbranch_scc0 .Lg8_qa_p1
	s_barrier

; #define MFMA(a, b, c) __builtin_amdgcn_mfma_f32_32x32x16_bf16((a), (b), (c), 0, 0, 0)
; template <bool SWAP>
; DI void gemm_mainloop(f32x16 (&acc)[4][2], const u16* __restrict__ A, int lda, int rlo, int rhi,
;                       const u16* __restrict__ B, int ldb, int K, char* lds, const u16* zero_line) {
;     ...
;   auto glds = [&](int kt, int st) {
;     char* as_ = lds + st * 65536 + tid * 16;
; #pragma unroll
;     for (int i = 0; i < 4; ++i) {
;       const int rr = lr + 64 * i;
;       const u16* srca = (rr >= rlo && rr < rhi) ? (ap + (ptrdiff_t)(64 * i) * lda + kt * 64) : (zero_line + lc * 8);
;       __builtin_amdgcn_global_load_lds((const unsigned*)srca, (lds_u32*)(as_ + i * 8192), 16, 0, 0);
;       __builtin_amdgcn_global_load_lds((const unsigned*)(bp + (ptrdiff_t)(64 * i) * ldb + kt * 64), (lds_u32*)(as_ + 32768 + i * 8192), 16, 0, 0);
;     }
;   };
;     ...
;   auto ldfrag = [&](const char* st, int ks, int buf) {
;     const int co = ((2 * ks + h) ^ sw) << 4;
; #pragma unroll
;     for (int mi = 0; mi < 4; ++mi) fa[buf][mi] = *(const bf16x8*)(st + arow_off + mi * 4096 + co);
; #pragma unroll
;     for (int ni = 0; ni < 2; ++ni) fb[buf][ni] = *(const bf16x8*)(st + brow_off + ni * 4096 + co);
;   };
;   auto mma = [&](int buf) {
; #pragma unroll
;     for (int mi = 0; mi < 4; ++mi)
; #pragma unroll
;       for (int ni = 0; ni < 2; ++ni)
;         acc[mi][ni] = SWAP ? MFMA(fb[buf][ni], fa[buf][mi], acc[mi][ni]) : MFMA(fa[buf][mi], fb[buf][ni], acc[mi][ni]);
;   };
;   auto pat_rd = [&]() {
; #pragma unroll
;     for (int g = 0; g < 6; ++g) {
;       __builtin_amdgcn_sched_group_barrier(0x100, 1, 0);
;       __builtin_amdgcn_sched_group_barrier(0x008, 1, 0);
;     }
;     __builtin_amdgcn_sched_group_barrier(0x008, 2, 0);
;   };
; #pragma unroll 2
;   for (int kt = 0; kt < nk; ++kt) {
;     const char* st = lds + (kt & 1) * 65536;
;     ldfrag(st, 0, 0);
;     mma(1);
;     pat_rd();
;     if (kt + 1 < nk) glds(kt + 1, (kt + 1) & 1);
;     ldfrag(st, 1, 1);
;     mma(0);
;     pat_rd();
;     ldfrag(st, 2, 0);
;     mma(1);
;     pat_rd();
;     ldfrag(st, 3, 1);
;     mma(0);
;     pat_rd();
;     asm volatile("s_waitcnt vmcnt(0)" ::: "memory");
;     __syncthreads();
;   }
.Lg8_qb:
	v_add3_u32 v246, v244, v240, 0
	v_add3_u32 v247, v244, v241, 0
	v_add3_u32 v248, v244, v242, 0
	v_add3_u32 v249, v244, v243, 0
	ds_read_b128 v[130:133], v246
	ds_read_b128 v[134:137], v247
	ds_read_b128 v[138:141], v248
	ds_read_b128 v[142:145], v249
	ds_read_b128 v[146:149], v246 offset:4096
	ds_read_b128 v[150:153], v247 offset:4096
	ds_read_b128 v[156:159], v248 offset:4096
	ds_read_b128 v[160:163], v249 offset:4096
	s_barrier
	s_waitcnt lgkmcnt(0)
	v_mfma_f32_32x32x16_bf16 v[114:129], v[170:173], v[130:133], v[114:129]
	v_mfma_f32_32x32x16_bf16 v[82:97], v[170:173], v[146:149], v[82:97]
	s_add_u32 m0, s100, 0x14000
	s_nop 0
	global_load_lds_dwordx4 v233, s[6:7]
	v_add_u32_e32 v233, 0x80, v233
	v_mfma_f32_32x32x16_bf16 v[114:129], v[174:177], v[134:137], v[114:129]
	v_mfma_f32_32x32x16_bf16 v[82:97], v[174:177], v[150:153], v[82:97]
	s_add_u32 m0, s100, 0x16000
	s_nop 0
	global_load_lds_dwordx4 v235, s[6:7]
	v_add_u32_e32 v235, 0x80, v235
	v_mfma_f32_32x32x16_bf16 v[114:129], v[178:181], v[138:141], v[114:129]
	v_mfma_f32_32x32x16_bf16 v[82:97], v[178:181], v[156:159], v[82:97]
	v_mfma_f32_32x32x16_bf16 v[114:129], v[186:189], v[142:145], v[114:129]
	v_mfma_f32_32x32x16_bf16 v[82:97], v[186:189], v[160:163], v[82:97]
	s_barrier
	v_add3_u32 v246, v245, v240, 0
	v_add3_u32 v247, v245, v241, 0
	v_add3_u32 v248, v245, v242, 0
	v_add3_u32 v249, v245, v243, 0
	ds_read_b128 v[190:193], v246 offset:49152
	ds_read_b128 v[194:197], v247 offset:49152
	ds_read_b128 v[198:201], v248 offset:49152
	ds_read_b128 v[228:231], v249 offset:49152
	s_barrier
	s_waitcnt lgkmcnt(0)
	v_mfma_f32_32x32x16_bf16 v[98:113], v[190:193], v[130:133], v[98:113]
	v_mfma_f32_32x32x16_bf16 v[66:81], v[190:193], v[146:149], v[66:81]
	s_add_u32 m0, s100, 0x8000
	s_nop 0
	global_load_lds_dwordx4 v236, s[8:9]
	v_add_u32_e32 v236, 0x80, v236
	v_mfma_f32_32x32x16_bf16 v[98:113], v[194:197], v[134:137], v[98:113]
	v_mfma_f32_32x32x16_bf16 v[66:81], v[194:197], v[150:153], v[66:81]
	s_add_u32 m0, s100, 0xa000
	s_nop 0
	global_load_lds_dwordx4 v238, s[8:9]
	v_add_u32_e32 v238, 0x80, v238
	v_mfma_f32_32x32x16_bf16 v[98:113], v[198:201], v[138:141], v[98:113]
	v_mfma_f32_32x32x16_bf16 v[66:81], v[198:201], v[156:159], v[66:81]
	v_mfma_f32_32x32x16_bf16 v[98:113], v[228:231], v[142:145], v[98:113]
	v_mfma_f32_32x32x16_bf16 v[66:81], v[228:231], v[160:163], v[66:81]
	s_barrier
	v_add3_u32 v246, v244, v240, 0
	v_add3_u32 v247, v244, v241, 0
	v_add3_u32 v248, v244, v242, 0
	v_add3_u32 v249, v244, v243, 0
	ds_read_b128 v[130:133], v246 offset:16384
	ds_read_b128 v[134:137], v247 offset:16384
	ds_read_b128 v[138:141], v248 offset:16384
	ds_read_b128 v[142:145], v249 offset:16384
	ds_read_b128 v[146:149], v246 offset:20480
	ds_read_b128 v[150:153], v247 offset:20480
	ds_read_b128 v[156:159], v248 offset:20480
	ds_read_b128 v[160:163], v249 offset:20480
	s_waitcnt vmcnt(8)
	s_barrier
	s_waitcnt lgkmcnt(0)
	v_mfma_f32_32x32x16_bf16 v[50:65], v[170:173], v[130:133], v[50:65]
	v_mfma_f32_32x32x16_bf16 v[18:33], v[170:173], v[146:149], v[18:33]
	s_add_u32 m0, s100, 0x0
	s_nop 0
	global_load_lds_dwordx4 v232, s[6:7]
	v_add_u32_e32 v232, 0x80, v232
	v_mfma_f32_32x32x16_bf16 v[50:65], v[174:177], v[134:137], v[50:65]
	v_mfma_f32_32x32x16_bf16 v[18:33], v[174:177], v[150:153], v[18:33]
	s_add_u32 m0, s100, 0x2000
	s_nop 0
	global_load_lds_dwordx4 v234, s[6:7]
	v_add_u32_e32 v234, 0x80, v234
	v_mfma_f32_32x32x16_bf16 v[50:65], v[178:181], v[138:141], v[50:65]
	v_mfma_f32_32x32x16_bf16 v[18:33], v[178:181], v[156:159], v[18:33]
	v_mfma_f32_32x32x16_bf16 v[50:65], v[186:189], v[142:145], v[50:65]
	v_mfma_f32_32x32x16_bf16 v[18:33], v[186:189], v[160:163], v[18:33]
	s_barrier
	v_add3_u32 v246, v245, v240, s10
	v_add3_u32 v247, v245, v241, s10
	v_add3_u32 v248, v245, v242, s10
	v_add3_u32 v249, v245, v243, s10
	ds_read_b128 v[170:173], v246 offset:32768
	ds_read_b128 v[174:177], v247 offset:32768
	ds_read_b128 v[178:181], v248 offset:32768
	ds_read_b128 v[186:189], v249 offset:32768
	s_waitcnt vmcnt(4)
	s_barrier
	s_waitcnt lgkmcnt(0)
	v_mfma_f32_32x32x16_bf16 v[34:49], v[190:193], v[130:133], v[34:49]
	v_mfma_f32_32x32x16_bf16 v[2:17], v[190:193], v[146:149], v[2:17]
	s_add_u32 m0, s100, 0xc000
	s_nop 0
	global_load_lds_dwordx4 v237, s[8:9]
	v_add_u32_e32 v237, 0x80, v237
	v_mfma_f32_32x32x16_bf16 v[34:49], v[194:197], v[134:137], v[34:49]
	v_mfma_f32_32x32x16_bf16 v[2:17], v[194:197], v[150:153], v[2:17]
	s_add_u32 m0, s100, 0xe000
	s_nop 0
	global_load_lds_dwordx4 v239, s[8:9]
	v_add_u32_e32 v239, 0x80, v239
	v_mfma_f32_32x32x16_bf16 v[34:49], v[198:201], v[138:141], v[34:49]
	v_mfma_f32_32x32x16_bf16 v[2:17], v[198:201], v[156:159], v[2:17]
	v_mfma_f32_32x32x16_bf16 v[34:49], v[228:231], v[142:145], v[34:49]
	v_mfma_f32_32x32x16_bf16 v[2:17], v[228:231], v[160:163], v[2:17]
	s_barrier
	v_add3_u32 v246, v244, v240, s10
	v_add3_u32 v247, v244, v241, s10
	v_add3_u32 v248, v244, v242, s10
	v_add3_u32 v249, v244, v243, s10
	ds_read_b128 v[130:133], v246
	ds_read_b128 v[134:137], v247
	ds_read_b128 v[138:141], v248
	ds_read_b128 v[142:145], v249
	ds_read_b128 v[146:149], v246 offset:4096
	ds_read_b128 v[150:153], v247 offset:4096
	ds_read_b128 v[156:159], v248 offset:4096
	ds_read_b128 v[160:163], v249 offset:4096
	s_barrier
; #define MFMA(a, b, c) __builtin_amdgcn_mfma_f32_32x32x16_bf16((a), (b), (c), 0, 0, 0)
; template <bool SWAP>
; DI void gemm_mainloop(f32x16 (&acc)[4][2], const u16* __restrict__ A, int lda, int rlo, int rhi,
;                       const u16* __restrict__ B, int ldb, int K, char* lds, const u16* zero_line) {
;     ...
;   auto glds = [&](int kt, int st) {
;     char* as_ = lds + st * 65536 + tid * 16;
; #pragma unroll
;     for (int i = 0; i < 4; ++i) {
;       const int rr = lr + 64 * i;
;       const u16* srca = (rr >= rlo && rr < rhi) ? (ap + (ptrdiff_t)(64 * i) * lda + kt * 64) : (zero_line + lc * 8);
;       __builtin_amdgcn_global_load_lds((const unsigned*)srca, (lds_u32*)(as_ + i * 8192), 16, 0, 0);
;       __builtin_amdgcn_global_load_lds((const unsigned*)(bp + (ptrdiff_t)(64 * i) * ldb + kt * 64), (lds_u32*)(as_ + 32768 + i * 8192), 16, 0, 0);
;     }
;   };
;     ...
;   auto ldfrag = [&](const char* st, int ks, int buf) {
;     const int co = ((2 * ks + h) ^ sw) << 4;
; #pragma unroll
;     for (int mi = 0; mi < 4; ++mi) fa[buf][mi] = *(const bf16x8*)(st + arow_off + mi * 4096 + co);
; #pragma unroll
;     for (int ni = 0; ni < 2; ++ni) fb[buf][ni] = *(const bf16x8*)(st + brow_off + ni * 4096 + co);
;   };
;   auto mma = [&](int buf) {
; #pragma unroll
;     for (int mi = 0; mi < 4; ++mi)
; #pragma unroll
;       for (int ni = 0; ni < 2; ++ni)
;         acc[mi][ni] = SWAP ? MFMA(fb[buf][ni], fa[buf][mi], acc[mi][ni]) : MFMA(fa[buf][mi], fb[buf][ni], acc[mi][ni]);
;   };
;   auto pat_rd = [&]() {
; #pragma unroll
;     for (int g = 0; g < 6; ++g) {
;       __builtin_amdgcn_sched_group_barrier(0x100, 1, 0);
;       __builtin_amdgcn_sched_group_barrier(0x008, 1, 0);
;     }
;     __builtin_amdgcn_sched_group_barrier(0x008, 2, 0);
;   };
; #pragma unroll 2
;   for (int kt = 0; kt < nk; ++kt) {
;     const char* st = lds + (kt & 1) * 65536;
;     ldfrag(st, 0, 0);
;     mma(1);
;     pat_rd();
;     if (kt + 1 < nk) glds(kt + 1, (kt + 1) & 1);
;     ldfrag(st, 1, 1);
;     mma(0);
;     pat_rd();
;     ldfrag(st, 2, 0);
;     mma(1);
;     pat_rd();
;     ldfrag(st, 3, 1);
;     mma(0);
;     pat_rd();
;     asm volatile("s_waitcnt vmcnt(0)" ::: "memory");
;     __syncthreads();
;   }
	s_waitcnt lgkmcnt(0)
	v_mfma_f32_32x32x16_bf16 v[114:129], v[170:173], v[130:133], v[114:129]
	v_mfma_f32_32x32x16_bf16 v[82:97], v[170:173], v[146:149], v[82:97]
	s_add_u32 m0, s100, 0x4000
	s_nop 0
	global_load_lds_dwordx4 v233, s[6:7]
	v_add_u32_e32 v233, 0x80, v233
	v_mfma_f32_32x32x16_bf16 v[114:129], v[174:177], v[134:137], v[114:129]
	v_mfma_f32_32x32x16_bf16 v[82:97], v[174:177], v[150:153], v[82:97]
	s_add_u32 m0, s100, 0x6000
	s_nop 0
	global_load_lds_dwordx4 v235, s[6:7]
	v_add_u32_e32 v235, 0x80, v235
	v_mfma_f32_32x32x16_bf16 v[114:129], v[178:181], v[138:141], v[114:129]
	v_mfma_f32_32x32x16_bf16 v[82:97], v[178:181], v[156:159], v[82:97]
	v_mfma_f32_32x32x16_bf16 v[114:129], v[186:189], v[142:145], v[114:129]
	v_mfma_f32_32x32x16_bf16 v[82:97], v[186:189], v[160:163], v[82:97]
	s_barrier
	v_add3_u32 v246, v245, v240, s10
	v_add3_u32 v247, v245, v241, s10
	v_add3_u32 v248, v245, v242, s10
	v_add3_u32 v249, v245, v243, s10
	ds_read_b128 v[190:193], v246 offset:49152
	ds_read_b128 v[194:197], v247 offset:49152
	ds_read_b128 v[198:201], v248 offset:49152
	ds_read_b128 v[228:231], v249 offset:49152
	s_barrier
	s_waitcnt lgkmcnt(0)
	v_mfma_f32_32x32x16_bf16 v[98:113], v[190:193], v[130:133], v[98:113]
	v_mfma_f32_32x32x16_bf16 v[66:81], v[190:193], v[146:149], v[66:81]
	s_add_u32 m0, s100, 0x18000
	s_nop 0
	global_load_lds_dwordx4 v236, s[8:9]
	v_add_u32_e32 v236, 0x80, v236
	v_mfma_f32_32x32x16_bf16 v[98:113], v[194:197], v[134:137], v[98:113]
	v_mfma_f32_32x32x16_bf16 v[66:81], v[194:197], v[150:153], v[66:81]
	s_add_u32 m0, s100, 0x1a000
	s_nop 0
	global_load_lds_dwordx4 v238, s[8:9]
	v_add_u32_e32 v238, 0x80, v238
	v_mfma_f32_32x32x16_bf16 v[98:113], v[198:201], v[138:141], v[98:113]
	v_mfma_f32_32x32x16_bf16 v[66:81], v[198:201], v[156:159], v[66:81]
	v_mfma_f32_32x32x16_bf16 v[98:113], v[228:231], v[142:145], v[98:113]
	v_mfma_f32_32x32x16_bf16 v[66:81], v[228:231], v[160:163], v[66:81]
	s_barrier
	v_add3_u32 v246, v244, v240, s10
	v_add3_u32 v247, v244, v241, s10
	v_add3_u32 v248, v244, v242, s10
	v_add3_u32 v249, v244, v243, s10
	ds_read_b128 v[130:133], v246 offset:16384
	ds_read_b128 v[134:137], v247 offset:16384
	ds_read_b128 v[138:141], v248 offset:16384
	ds_read_b128 v[142:145], v249 offset:16384
	ds_read_b128 v[146:149], v246 offset:20480
	ds_read_b128 v[150:153], v247 offset:20480
	ds_read_b128 v[156:159], v248 offset:20480
	ds_read_b128 v[160:163], v249 offset:20480
	s_waitcnt vmcnt(8)
	s_barrier
	s_waitcnt lgkmcnt(0)
	v_mfma_f32_32x32x16_bf16 v[50:65], v[170:173], v[130:133], v[50:65]
	v_mfma_f32_32x32x16_bf16 v[18:33], v[170:173], v[146:149], v[18:33]
	s_add_u32 m0, s100, 0x10000
	s_nop 0
	global_load_lds_dwordx4 v232, s[6:7]
	v_add_u32_e32 v232, 0x80, v232
	v_mfma_f32_32x32x16_bf16 v[50:65], v[174:177], v[134:137], v[50:65]
	v_mfma_f32_32x32x16_bf16 v[18:33], v[174:177], v[150:153], v[18:33]
	s_add_u32 m0, s100, 0x12000
	s_nop 0
	global_load_lds_dwordx4 v234, s[6:7]
	v_add_u32_e32 v234, 0x80, v234
	v_mfma_f32_32x32x16_bf16 v[50:65], v[178:181], v[138:141], v[50:65]
	v_mfma_f32_32x32x16_bf16 v[18:33], v[178:181], v[156:159], v[18:33]
	v_mfma_f32_32x32x16_bf16 v[50:65], v[186:189], v[142:145], v[50:65]
	v_mfma_f32_32x32x16_bf16 v[18:33], v[186:189], v[160:163], v[18:33]
	s_barrier
	v_add3_u32 v246, v245, v240, 0
	v_add3_u32 v247, v245, v241, 0
	v_add3_u32 v248, v245, v242, 0
	v_add3_u32 v249, v245, v243, 0
	ds_read_b128 v[170:173], v246 offset:32768
	ds_read_b128 v[174:177], v247 offset:32768
	ds_read_b128 v[178:181], v248 offset:32768
	ds_read_b128 v[186:189], v249 offset:32768
	s_waitcnt vmcnt(4)
	s_barrier
	s_waitcnt lgkmcnt(0)
	v_mfma_f32_32x32x16_bf16 v[34:49], v[190:193], v[130:133], v[34:49]
	v_mfma_f32_32x32x16_bf16 v[2:17], v[190:193], v[146:149], v[2:17]
	s_add_u32 m0, s100, 0x1c000
	s_nop 0
	global_load_lds_dwordx4 v237, s[8:9]
	v_add_u32_e32 v237, 0x80, v237
	v_mfma_f32_32x32x16_bf16 v[34:49], v[194:197], v[134:137], v[34:49]
	v_mfma_f32_32x32x16_bf16 v[2:17], v[194:197], v[150:153], v[2:17]
	s_add_u32 m0, s100, 0x1e000
	s_nop 0
	global_load_lds_dwordx4 v239, s[8:9]
	v_add_u32_e32 v239, 0x80, v239
	v_mfma_f32_32x32x16_bf16 v[34:49], v[198:201], v[138:141], v[34:49]
	v_mfma_f32_32x32x16_bf16 v[2:17], v[198:201], v[156:159], v[2:17]
	v_mfma_f32_32x32x16_bf16 v[34:49], v[228:231], v[142:145], v[34:49]
	v_mfma_f32_32x32x16_bf16 v[2:17], v[228:231], v[160:163], v[2:17]
	s_barrier
	s_add_i32 s11, s11, 2
	s_cmp_lt_u32 s11, 14
	s_cbranch_scc1 .Lg8_qb
	v_add3_u32 v246, v244, v240, 0
	v_add3_u32 v247, v244, v241, 0
	v_add3_u32 v248, v244, v242, 0
	v_add3_u32 v249, v244, v243, 0
	ds_read_b128 v[130:133], v246
	ds_read_b128 v[134:137], v247
	ds_read_b128 v[138:141], v248
	ds_read_b128 v[142:145], v249
	ds_read_b128 v[146:149], v246 offset:4096
	ds_read_b128 v[150:153], v247 offset:4096
	ds_read_b128 v[156:159], v248 offset:4096
	ds_read_b128 v[160:163], v249 offset:4096
	s_add_u32 m0, s100, 0x14000
	s_nop 0
	global_load_lds_dwordx4 v233, s[6:7]
	v_add_u32_e32 v233, 0x80, v233
	s_add_u32 m0, s100, 0x16000
	s_nop 0
	global_load_lds_dwordx4 v235, s[6:7]
	v_add_u32_e32 v235, 0x80, v235
	s_barrier
	s_waitcnt lgkmcnt(0)
	v_mfma_f32_32x32x16_bf16 v[114:129], v[170:173], v[130:133], v[114:129]
	v_mfma_f32_32x32x16_bf16 v[82:97], v[170:173], v[146:149], v[82:97]
	v_mfma_f32_32x32x16_bf16 v[114:129], v[174:177], v[134:137], v[114:129]
	v_mfma_f32_32x32x16_bf16 v[82:97], v[174:177], v[150:153], v[82:97]
	v_mfma_f32_32x32x16_bf16 v[114:129], v[178:181], v[138:141], v[114:129]
	v_mfma_f32_32x32x16_bf16 v[82:97], v[178:181], v[156:159], v[82:97]
	v_mfma_f32_32x32x16_bf16 v[114:129], v[186:189], v[142:145], v[114:129]
	v_mfma_f32_32x32x16_bf16 v[82:97], v[186:189], v[160:163], v[82:97]
	s_barrier
; #define MFMA(a, b, c) __builtin_amdgcn_mfma_f32_32x32x16_bf16((a), (b), (c), 0, 0, 0)
; template <bool SWAP>
; DI void gemm_mainloop(f32x16 (&acc)[4][2], const u16* __restrict__ A, int lda, int rlo, int rhi,
;                       const u16* __restrict__ B, int ldb, int K, char* lds, const u16* zero_line) {
;     ...
;   auto ldfrag = [&](const char* st, int ks, int buf) {
;     const int co = ((2 * ks + h) ^ sw) << 4;
; #pragma unroll
;     for (int mi = 0; mi < 4; ++mi) fa[buf][mi] = *(const bf16x8*)(st + arow_off + mi * 4096 + co);
; #pragma unroll
;     for (int ni = 0; ni < 2; ++ni) fb[buf][ni] = *(const bf16x8*)(st + brow_off + ni * 4096 + co);
;   };
;   auto mma = [&](int buf) {
; #pragma unroll
;     for (int mi = 0; mi < 4; ++mi)
; #pragma unroll
;       for (int ni = 0; ni < 2; ++ni)
;         acc[mi][ni] = SWAP ? MFMA(fb[buf][ni], fa[buf][mi], acc[mi][ni]) : MFMA(fa[buf][mi], fb[buf][ni], acc[mi][ni]);
;   };
;   auto pat_rd = [&]() {
; #pragma unroll
;     for (int g = 0; g < 6; ++g) {
;       __builtin_amdgcn_sched_group_barrier(0x100, 1, 0);
;       __builtin_amdgcn_sched_group_barrier(0x008, 1, 0);
;     }
;     __builtin_amdgcn_sched_group_barrier(0x008, 2, 0);
;   };
; #pragma unroll 2
;   for (int kt = 0; kt < nk; ++kt) {
;     const char* st = lds + (kt & 1) * 65536;
;     ldfrag(st, 0, 0);
;     mma(1);
;     pat_rd();
;     if (kt + 1 < nk) glds(kt + 1, (kt + 1) & 1);
;     ldfrag(st, 1, 1);
;     mma(0);
;     pat_rd();
;     ldfrag(st, 2, 0);
;     mma(1);
;     pat_rd();
;     ldfrag(st, 3, 1);
;     mma(0);
;     pat_rd();
;     asm volatile("s_waitcnt vmcnt(0)" ::: "memory");
;     __syncthreads();
;   }
;   mma(1);
	v_add3_u32 v246, v245, v240, 0
	v_add3_u32 v247, v245, v241, 0
	v_add3_u32 v248, v245, v242, 0
	v_add3_u32 v249, v245, v243, 0
	ds_read_b128 v[190:193], v246 offset:49152
	ds_read_b128 v[194:197], v247 offset:49152
	ds_read_b128 v[198:201], v248 offset:49152
	ds_read_b128 v[228:231], v249 offset:49152
	s_barrier
	s_waitcnt lgkmcnt(0)
	v_mfma_f32_32x32x16_bf16 v[98:113], v[190:193], v[130:133], v[98:113]
	v_mfma_f32_32x32x16_bf16 v[66:81], v[190:193], v[146:149], v[66:81]
	v_mfma_f32_32x32x16_bf16 v[98:113], v[194:197], v[134:137], v[98:113]
	v_mfma_f32_32x32x16_bf16 v[66:81], v[194:197], v[150:153], v[66:81]
	v_mfma_f32_32x32x16_bf16 v[98:113], v[198:201], v[138:141], v[98:113]
	v_mfma_f32_32x32x16_bf16 v[66:81], v[198:201], v[156:159], v[66:81]
	v_mfma_f32_32x32x16_bf16 v[98:113], v[228:231], v[142:145], v[98:113]
	v_mfma_f32_32x32x16_bf16 v[66:81], v[228:231], v[160:163], v[66:81]
	s_barrier
	v_add3_u32 v246, v244, v240, 0
	v_add3_u32 v247, v244, v241, 0
	v_add3_u32 v248, v244, v242, 0
	v_add3_u32 v249, v244, v243, 0
	ds_read_b128 v[130:133], v246 offset:16384
	ds_read_b128 v[134:137], v247 offset:16384
	ds_read_b128 v[138:141], v248 offset:16384
	ds_read_b128 v[142:145], v249 offset:16384
	ds_read_b128 v[146:149], v246 offset:20480
	ds_read_b128 v[150:153], v247 offset:20480
	ds_read_b128 v[156:159], v248 offset:20480
	ds_read_b128 v[160:163], v249 offset:20480
	s_waitcnt vmcnt(4)
	s_barrier
	s_waitcnt lgkmcnt(0)
	v_mfma_f32_32x32x16_bf16 v[50:65], v[170:173], v[130:133], v[50:65]
	v_mfma_f32_32x32x16_bf16 v[18:33], v[170:173], v[146:149], v[18:33]
	v_mfma_f32_32x32x16_bf16 v[50:65], v[174:177], v[134:137], v[50:65]
	v_mfma_f32_32x32x16_bf16 v[18:33], v[174:177], v[150:153], v[18:33]
	v_mfma_f32_32x32x16_bf16 v[50:65], v[178:181], v[138:141], v[50:65]
	v_mfma_f32_32x32x16_bf16 v[18:33], v[178:181], v[156:159], v[18:33]
	v_mfma_f32_32x32x16_bf16 v[50:65], v[186:189], v[142:145], v[50:65]
	v_mfma_f32_32x32x16_bf16 v[18:33], v[186:189], v[160:163], v[18:33]
	v_mfma_f32_32x32x16_bf16 v[34:49], v[190:193], v[130:133], v[34:49]
	v_mfma_f32_32x32x16_bf16 v[2:17], v[190:193], v[146:149], v[2:17]
	v_mfma_f32_32x32x16_bf16 v[34:49], v[194:197], v[134:137], v[34:49]
	v_mfma_f32_32x32x16_bf16 v[2:17], v[194:197], v[150:153], v[2:17]
	v_mfma_f32_32x32x16_bf16 v[34:49], v[198:201], v[138:141], v[34:49]
	v_mfma_f32_32x32x16_bf16 v[2:17], v[198:201], v[156:159], v[2:17]
	v_mfma_f32_32x32x16_bf16 v[34:49], v[228:231], v[142:145], v[34:49]
	v_mfma_f32_32x32x16_bf16 v[2:17], v[228:231], v[160:163], v[2:17]
	s_barrier
	v_add3_u32 v246, v245, v240, s10
	v_add3_u32 v247, v245, v241, s10
	v_add3_u32 v248, v245, v242, s10
	v_add3_u32 v249, v245, v243, s10
	ds_read_b128 v[170:173], v246 offset:32768
	ds_read_b128 v[174:177], v247 offset:32768
	ds_read_b128 v[178:181], v248 offset:32768
	ds_read_b128 v[186:189], v249 offset:32768
	v_add3_u32 v246, v244, v240, s10
	v_add3_u32 v247, v244, v241, s10
	v_add3_u32 v248, v244, v242, s10
	v_add3_u32 v249, v244, v243, s10
	ds_read_b128 v[130:133], v246
	ds_read_b128 v[134:137], v247
	ds_read_b128 v[138:141], v248
	ds_read_b128 v[142:145], v249
	ds_read_b128 v[146:149], v246 offset:4096
	ds_read_b128 v[150:153], v247 offset:4096
	ds_read_b128 v[156:159], v248 offset:4096
	ds_read_b128 v[160:163], v249 offset:4096
	s_waitcnt vmcnt(2)
	s_barrier
	s_waitcnt lgkmcnt(0)
	v_mfma_f32_32x32x16_bf16 v[114:129], v[170:173], v[130:133], v[114:129]
	v_mfma_f32_32x32x16_bf16 v[82:97], v[170:173], v[146:149], v[82:97]
	v_mfma_f32_32x32x16_bf16 v[114:129], v[174:177], v[134:137], v[114:129]
	v_mfma_f32_32x32x16_bf16 v[82:97], v[174:177], v[150:153], v[82:97]
	v_mfma_f32_32x32x16_bf16 v[114:129], v[178:181], v[138:141], v[114:129]
	v_mfma_f32_32x32x16_bf16 v[82:97], v[178:181], v[156:159], v[82:97]
	v_mfma_f32_32x32x16_bf16 v[114:129], v[186:189], v[142:145], v[114:129]
	v_mfma_f32_32x32x16_bf16 v[82:97], v[186:189], v[160:163], v[82:97]
	s_barrier
	v_add3_u32 v246, v245, v240, s10
	v_add3_u32 v247, v245, v241, s10
	v_add3_u32 v248, v245, v242, s10
	v_add3_u32 v249, v245, v243, s10
	ds_read_b128 v[190:193], v246 offset:49152
	ds_read_b128 v[194:197], v247 offset:49152
	ds_read_b128 v[198:201], v248 offset:49152
	ds_read_b128 v[228:231], v249 offset:49152
	s_waitcnt vmcnt(0)
	s_barrier
	s_waitcnt lgkmcnt(0)
	v_mfma_f32_32x32x16_bf16 v[98:113], v[190:193], v[130:133], v[98:113]
	v_mfma_f32_32x32x16_bf16 v[66:81], v[190:193], v[146:149], v[66:81]
	v_mfma_f32_32x32x16_bf16 v[98:113], v[194:197], v[134:137], v[98:113]
	v_mfma_f32_32x32x16_bf16 v[66:81], v[194:197], v[150:153], v[66:81]
	v_mfma_f32_32x32x16_bf16 v[98:113], v[198:201], v[138:141], v[98:113]
	v_mfma_f32_32x32x16_bf16 v[66:81], v[198:201], v[156:159], v[66:81]
	v_mfma_f32_32x32x16_bf16 v[98:113], v[228:231], v[142:145], v[98:113]
	v_mfma_f32_32x32x16_bf16 v[66:81], v[228:231], v[160:163], v[66:81]
	s_barrier
	v_add3_u32 v246, v244, v240, s10
	v_add3_u32 v247, v244, v241, s10
	v_add3_u32 v248, v244, v242, s10
	v_add3_u32 v249, v244, v243, s10
	ds_read_b128 v[130:133], v246 offset:16384
	ds_read_b128 v[134:137], v247 offset:16384
	ds_read_b128 v[138:141], v248 offset:16384
	ds_read_b128 v[142:145], v249 offset:16384
	ds_read_b128 v[146:149], v246 offset:20480
	ds_read_b128 v[150:153], v247 offset:20480
	ds_read_b128 v[156:159], v248 offset:20480
	ds_read_b128 v[160:163], v249 offset:20480
	s_barrier
	s_waitcnt lgkmcnt(0)
	v_mfma_f32_32x32x16_bf16 v[50:65], v[170:173], v[130:133], v[50:65]
	v_mfma_f32_32x32x16_bf16 v[18:33], v[170:173], v[146:149], v[18:33]
	v_mfma_f32_32x32x16_bf16 v[50:65], v[174:177], v[134:137], v[50:65]
	v_mfma_f32_32x32x16_bf16 v[18:33], v[174:177], v[150:153], v[18:33]
	v_mfma_f32_32x32x16_bf16 v[50:65], v[178:181], v[138:141], v[50:65]
	v_mfma_f32_32x32x16_bf16 v[18:33], v[178:181], v[156:159], v[18:33]
	v_mfma_f32_32x32x16_bf16 v[50:65], v[186:189], v[142:145], v[50:65]
	v_mfma_f32_32x32x16_bf16 v[18:33], v[186:189], v[160:163], v[18:33]
	v_mfma_f32_32x32x16_bf16 v[34:49], v[190:193], v[130:133], v[34:49]
	v_mfma_f32_32x32x16_bf16 v[2:17], v[190:193], v[146:149], v[2:17]
	v_mfma_f32_32x32x16_bf16 v[34:49], v[194:197], v[134:137], v[34:49]
	v_mfma_f32_32x32x16_bf16 v[2:17], v[194:197], v[150:153], v[2:17]
	v_mfma_f32_32x32x16_bf16 v[34:49], v[198:201], v[138:141], v[34:49]
	v_mfma_f32_32x32x16_bf16 v[2:17], v[198:201], v[156:159], v[2:17]
	v_mfma_f32_32x32x16_bf16 v[34:49], v[228:231], v[142:145], v[34:49]
	v_mfma_f32_32x32x16_bf16 v[2:17], v[228:231], v[160:163], v[2:17]
	s_barrier
	s_cmp_eq_u32 s101, 0
	s_cbranch_scc0 .Lg8_qb_p1
	s_barrier

; #define MFMA(a, b, c) __builtin_amdgcn_mfma_f32_32x32x16_bf16((a), (b), (c), 0, 0, 0)
; template <bool SWAP>
; DI void gemm_mainloop(f32x16 (&acc)[4][2], const u16* __restrict__ A, int lda, int rlo, int rhi,
;                       const u16* __restrict__ B, int ldb, int K, char* lds, const u16* zero_line) {
;     ...
;   auto glds = [&](int kt, int st) {
;     char* as_ = lds + st * 65536 + tid * 16;
; #pragma unroll
;     for (int i = 0; i < 4; ++i) {
;       const int rr = lr + 64 * i;
;       const u16* srca = (rr >= rlo && rr < rhi) ? (ap + (ptrdiff_t)(64 * i) * lda + kt * 64) : (zero_line + lc * 8);
;       __builtin_amdgcn_global_load_lds((const unsigned*)srca, (lds_u32*)(as_ + i * 8192), 16, 0, 0);
;       __builtin_amdgcn_global_load_lds((const unsigned*)(bp + (ptrdiff_t)(64 * i) * ldb + kt * 64), (lds_u32*)(as_ + 32768 + i * 8192), 16, 0, 0);
;     }
;   };
;     ...
;   auto ldfrag = [&](const char* st, int ks, int buf) {
;     const int co = ((2 * ks + h) ^ sw) << 4;
; #pragma unroll
;     for (int mi = 0; mi < 4; ++mi) fa[buf][mi] = *(const bf16x8*)(st + arow_off + mi * 4096 + co);
; #pragma unroll
;     for (int ni = 0; ni < 2; ++ni) fb[buf][ni] = *(const bf16x8*)(st + brow_off + ni * 4096 + co);
;   };
;   auto mma = [&](int buf) {
; #pragma unroll
;     for (int mi = 0; mi < 4; ++mi)
; #pragma unroll
;       for (int ni = 0; ni < 2; ++ni)
;         acc[mi][ni] = SWAP ? MFMA(fb[buf][ni], fa[buf][mi], acc[mi][ni]) : MFMA(fa[buf][mi], fb[buf][ni], acc[mi][ni]);
;   };
;   auto pat_rd = [&]() {
; #pragma unroll
;     for (int g = 0; g < 6; ++g) {
;       __builtin_amdgcn_sched_group_barrier(0x100, 1, 0);
;       __builtin_amdgcn_sched_group_barrier(0x008, 1, 0);
;     }
;     __builtin_amdgcn_sched_group_barrier(0x008, 2, 0);
;   };
; #pragma unroll 2
;   for (int kt = 0; kt < nk; ++kt) {
;     const char* st = lds + (kt & 1) * 65536;
;     ldfrag(st, 0, 0);
;     mma(1);
;     pat_rd();
;     if (kt + 1 < nk) glds(kt + 1, (kt + 1) & 1);
;     ldfrag(st, 1, 1);
;     mma(0);
;     pat_rd();
;     ldfrag(st, 2, 0);
;     mma(1);
;     pat_rd();
;     ldfrag(st, 3, 1);
;     mma(0);
;     pat_rd();
;     asm volatile("s_waitcnt vmcnt(0)" ::: "memory");
;     __syncthreads();
;   }
.Lg8_m246:
	v_add3_u32 v242, v240, v236, 0
	v_add3_u32 v243, v240, v237, 0
	v_add3_u32 v244, v240, v238, 0
	v_add3_u32 v245, v240, v239, 0
	ds_read_b128 v[130:133], v242
	ds_read_b128 v[134:137], v243
	ds_read_b128 v[138:141], v244
	ds_read_b128 v[142:145], v245
	ds_read_b128 v[146:149], v242 offset:4096
	ds_read_b128 v[150:153], v243 offset:4096
	ds_read_b128 v[154:157], v244 offset:4096
	ds_read_b128 v[158:161], v245 offset:4096
	s_barrier
	s_waitcnt lgkmcnt(0)
	v_mfma_f32_32x32x16_bf16 v[114:129], v[162:165], v[130:133], v[114:129]
	v_mfma_f32_32x32x16_bf16 v[82:97], v[162:165], v[146:149], v[82:97]
	s_add_u32 m0, s100, 0x14000
	s_nop 0
	global_load_lds_dwordx4 v229, s[6:7]
	v_add_u32_e32 v229, 0x80, v229
	v_mfma_f32_32x32x16_bf16 v[114:129], v[166:169], v[134:137], v[114:129]
	v_mfma_f32_32x32x16_bf16 v[82:97], v[166:169], v[150:153], v[82:97]
	s_add_u32 m0, s100, 0x16000
	s_nop 0
	global_load_lds_dwordx4 v231, s[6:7]
	v_add_u32_e32 v231, 0x80, v231
	v_mfma_f32_32x32x16_bf16 v[114:129], v[170:173], v[138:141], v[114:129]
	v_mfma_f32_32x32x16_bf16 v[82:97], v[170:173], v[154:157], v[82:97]
	v_mfma_f32_32x32x16_bf16 v[114:129], v[174:177], v[142:145], v[114:129]
	v_mfma_f32_32x32x16_bf16 v[82:97], v[174:177], v[158:161], v[82:97]
	s_barrier
	v_add3_u32 v242, v241, v236, 0
	v_add3_u32 v243, v241, v237, 0
	v_add3_u32 v244, v241, v238, 0
	v_add3_u32 v245, v241, v239, 0
	ds_read_b128 v[180:183], v242 offset:49152
	ds_read_b128 v[186:189], v243 offset:49152
	ds_read_b128 v[190:193], v244 offset:49152
	ds_read_b128 v[194:197], v245 offset:49152
	s_barrier
	s_waitcnt lgkmcnt(0)
	v_mfma_f32_32x32x16_bf16 v[98:113], v[180:183], v[130:133], v[98:113]
	v_mfma_f32_32x32x16_bf16 v[66:81], v[180:183], v[146:149], v[66:81]
	s_add_u32 m0, s100, 0x8000
	s_nop 0
	global_load_lds_dwordx4 v232, s[8:9]
	v_add_u32_e32 v232, 0x80, v232
	v_mfma_f32_32x32x16_bf16 v[98:113], v[186:189], v[134:137], v[98:113]
	v_mfma_f32_32x32x16_bf16 v[66:81], v[186:189], v[150:153], v[66:81]
	s_add_u32 m0, s100, 0xa000
	s_nop 0
	global_load_lds_dwordx4 v234, s[8:9]
	v_add_u32_e32 v234, 0x80, v234
	v_mfma_f32_32x32x16_bf16 v[98:113], v[190:193], v[138:141], v[98:113]
	v_mfma_f32_32x32x16_bf16 v[66:81], v[190:193], v[154:157], v[66:81]
	v_mfma_f32_32x32x16_bf16 v[98:113], v[194:197], v[142:145], v[98:113]
	v_mfma_f32_32x32x16_bf16 v[66:81], v[194:197], v[158:161], v[66:81]
	s_barrier
	v_add3_u32 v242, v240, v236, 0
	v_add3_u32 v243, v240, v237, 0
	v_add3_u32 v244, v240, v238, 0
	v_add3_u32 v245, v240, v239, 0
	ds_read_b128 v[130:133], v242 offset:16384
	ds_read_b128 v[134:137], v243 offset:16384
	ds_read_b128 v[138:141], v244 offset:16384
	ds_read_b128 v[142:145], v245 offset:16384
	ds_read_b128 v[146:149], v242 offset:20480
	ds_read_b128 v[150:153], v243 offset:20480
	ds_read_b128 v[154:157], v244 offset:20480
	ds_read_b128 v[158:161], v245 offset:20480
	s_waitcnt vmcnt(8)
	s_barrier
	s_waitcnt lgkmcnt(0)
	v_mfma_f32_32x32x16_bf16 v[50:65], v[162:165], v[130:133], v[50:65]
	v_mfma_f32_32x32x16_bf16 v[18:33], v[162:165], v[146:149], v[18:33]
	s_add_u32 m0, s100, 0x0
	s_nop 0
	global_load_lds_dwordx4 v228, s[6:7]
	v_add_u32_e32 v228, 0x80, v228
	v_mfma_f32_32x32x16_bf16 v[50:65], v[166:169], v[134:137], v[50:65]
	v_mfma_f32_32x32x16_bf16 v[18:33], v[166:169], v[150:153], v[18:33]
	s_add_u32 m0, s100, 0x2000
	s_nop 0
	global_load_lds_dwordx4 v230, s[6:7]
	v_add_u32_e32 v230, 0x80, v230
	v_mfma_f32_32x32x16_bf16 v[50:65], v[170:173], v[138:141], v[50:65]
	v_mfma_f32_32x32x16_bf16 v[18:33], v[170:173], v[154:157], v[18:33]
	v_mfma_f32_32x32x16_bf16 v[50:65], v[174:177], v[142:145], v[50:65]
	v_mfma_f32_32x32x16_bf16 v[18:33], v[174:177], v[158:161], v[18:33]
	s_barrier
	v_add3_u32 v242, v241, v236, s10
	v_add3_u32 v243, v241, v237, s10
	v_add3_u32 v244, v241, v238, s10
	v_add3_u32 v245, v241, v239, s10
	ds_read_b128 v[162:165], v242 offset:32768
	ds_read_b128 v[166:169], v243 offset:32768
	ds_read_b128 v[170:173], v244 offset:32768
	ds_read_b128 v[174:177], v245 offset:32768
	s_waitcnt vmcnt(4)
	s_barrier
	s_waitcnt lgkmcnt(0)
	v_mfma_f32_32x32x16_bf16 v[34:49], v[180:183], v[130:133], v[34:49]
	v_mfma_f32_32x32x16_bf16 v[2:17], v[180:183], v[146:149], v[2:17]
	s_add_u32 m0, s100, 0xc000
	s_nop 0
	global_load_lds_dwordx4 v233, s[8:9]
	v_add_u32_e32 v233, 0x80, v233
	v_mfma_f32_32x32x16_bf16 v[34:49], v[186:189], v[134:137], v[34:49]
	v_mfma_f32_32x32x16_bf16 v[2:17], v[186:189], v[150:153], v[2:17]
	s_add_u32 m0, s100, 0xe000
	s_nop 0
	global_load_lds_dwordx4 v235, s[8:9]
	v_add_u32_e32 v235, 0x80, v235
	v_mfma_f32_32x32x16_bf16 v[34:49], v[190:193], v[138:141], v[34:49]
	v_mfma_f32_32x32x16_bf16 v[2:17], v[190:193], v[154:157], v[2:17]
	v_mfma_f32_32x32x16_bf16 v[34:49], v[194:197], v[142:145], v[34:49]
	v_mfma_f32_32x32x16_bf16 v[2:17], v[194:197], v[158:161], v[2:17]
	s_barrier
	v_add3_u32 v242, v240, v236, s10
	v_add3_u32 v243, v240, v237, s10
	v_add3_u32 v244, v240, v238, s10
	v_add3_u32 v245, v240, v239, s10
	ds_read_b128 v[130:133], v242
	ds_read_b128 v[134:137], v243
	ds_read_b128 v[138:141], v244
	ds_read_b128 v[142:145], v245
	ds_read_b128 v[146:149], v242 offset:4096
	ds_read_b128 v[150:153], v243 offset:4096
	ds_read_b128 v[154:157], v244 offset:4096
	ds_read_b128 v[158:161], v245 offset:4096
	s_barrier
; #define MFMA(a, b, c) __builtin_amdgcn_mfma_f32_32x32x16_bf16((a), (b), (c), 0, 0, 0)
; template <bool SWAP>
; DI void gemm_mainloop(f32x16 (&acc)[4][2], const u16* __restrict__ A, int lda, int rlo, int rhi,
;                       const u16* __restrict__ B, int ldb, int K, char* lds, const u16* zero_line) {
;     ...
;   auto glds = [&](int kt, int st) {
;     char* as_ = lds + st * 65536 + tid * 16;
; #pragma unroll
;     for (int i = 0; i < 4; ++i) {
;       const int rr = lr + 64 * i;
;       const u16* srca = (rr >= rlo && rr < rhi) ? (ap + (ptrdiff_t)(64 * i) * lda + kt * 64) : (zero_line + lc * 8);
;       __builtin_amdgcn_global_load_lds((const unsigned*)srca, (lds_u32*)(as_ + i * 8192), 16, 0, 0);
;       __builtin_amdgcn_global_load_lds((const unsigned*)(bp + (ptrdiff_t)(64 * i) * ldb + kt * 64), (lds_u32*)(as_ + 32768 + i * 8192), 16, 0, 0);
;     }
;   };
;     ...
;   auto ldfrag = [&](const char* st, int ks, int buf) {
;     const int co = ((2 * ks + h) ^ sw) << 4;
; #pragma unroll
;     for (int mi = 0; mi < 4; ++mi) fa[buf][mi] = *(const bf16x8*)(st + arow_off + mi * 4096 + co);
; #pragma unroll
;     for (int ni = 0; ni < 2; ++ni) fb[buf][ni] = *(const bf16x8*)(st + brow_off + ni * 4096 + co);
;   };
;   auto mma = [&](int buf) {
; #pragma unroll
;     for (int mi = 0; mi < 4; ++mi)
; #pragma unroll
;       for (int ni = 0; ni < 2; ++ni)
;         acc[mi][ni] = SWAP ? MFMA(fb[buf][ni], fa[buf][mi], acc[mi][ni]) : MFMA(fa[buf][mi], fb[buf][ni], acc[mi][ni]);
;   };
;   auto pat_rd = [&]() {
; #pragma unroll
;     for (int g = 0; g < 6; ++g) {
;       __builtin_amdgcn_sched_group_barrier(0x100, 1, 0);
;       __builtin_amdgcn_sched_group_barrier(0x008, 1, 0);
;     }
;     __builtin_amdgcn_sched_group_barrier(0x008, 2, 0);
;   };
; #pragma unroll 2
;   for (int kt = 0; kt < nk; ++kt) {
;     const char* st = lds + (kt & 1) * 65536;
;     ldfrag(st, 0, 0);
;     mma(1);
;     pat_rd();
;     if (kt + 1 < nk) glds(kt + 1, (kt + 1) & 1);
;     ldfrag(st, 1, 1);
;     mma(0);
;     pat_rd();
;     ldfrag(st, 2, 0);
;     mma(1);
;     pat_rd();
;     ldfrag(st, 3, 1);
;     mma(0);
;     pat_rd();
;     asm volatile("s_waitcnt vmcnt(0)" ::: "memory");
;     __syncthreads();
;   }
	s_waitcnt lgkmcnt(0)
	v_mfma_f32_32x32x16_bf16 v[114:129], v[162:165], v[130:133], v[114:129]
	v_mfma_f32_32x32x16_bf16 v[82:97], v[162:165], v[146:149], v[82:97]
	s_add_u32 m0, s100, 0x4000
	s_nop 0
	global_load_lds_dwordx4 v229, s[6:7]
	v_add_u32_e32 v229, 0x80, v229
	v_mfma_f32_32x32x16_bf16 v[114:129], v[166:169], v[134:137], v[114:129]
	v_mfma_f32_32x32x16_bf16 v[82:97], v[166:169], v[150:153], v[82:97]
	s_add_u32 m0, s100, 0x6000
	s_nop 0
	global_load_lds_dwordx4 v231, s[6:7]
	v_add_u32_e32 v231, 0x80, v231
	v_mfma_f32_32x32x16_bf16 v[114:129], v[170:173], v[138:141], v[114:129]
	v_mfma_f32_32x32x16_bf16 v[82:97], v[170:173], v[154:157], v[82:97]
	v_mfma_f32_32x32x16_bf16 v[114:129], v[174:177], v[142:145], v[114:129]
	v_mfma_f32_32x32x16_bf16 v[82:97], v[174:177], v[158:161], v[82:97]
	s_barrier
	v_add3_u32 v242, v241, v236, s10
	v_add3_u32 v243, v241, v237, s10
	v_add3_u32 v244, v241, v238, s10
	v_add3_u32 v245, v241, v239, s10
	ds_read_b128 v[180:183], v242 offset:49152
	ds_read_b128 v[186:189], v243 offset:49152
	ds_read_b128 v[190:193], v244 offset:49152
	ds_read_b128 v[194:197], v245 offset:49152
	s_barrier
	s_waitcnt lgkmcnt(0)
	v_mfma_f32_32x32x16_bf16 v[98:113], v[180:183], v[130:133], v[98:113]
	v_mfma_f32_32x32x16_bf16 v[66:81], v[180:183], v[146:149], v[66:81]
	s_add_u32 m0, s100, 0x18000
	s_nop 0
	global_load_lds_dwordx4 v232, s[8:9]
	v_add_u32_e32 v232, 0x80, v232
	v_mfma_f32_32x32x16_bf16 v[98:113], v[186:189], v[134:137], v[98:113]
	v_mfma_f32_32x32x16_bf16 v[66:81], v[186:189], v[150:153], v[66:81]
	s_add_u32 m0, s100, 0x1a000
	s_nop 0
	global_load_lds_dwordx4 v234, s[8:9]
	v_add_u32_e32 v234, 0x80, v234
	v_mfma_f32_32x32x16_bf16 v[98:113], v[190:193], v[138:141], v[98:113]
	v_mfma_f32_32x32x16_bf16 v[66:81], v[190:193], v[154:157], v[66:81]
	v_mfma_f32_32x32x16_bf16 v[98:113], v[194:197], v[142:145], v[98:113]
	v_mfma_f32_32x32x16_bf16 v[66:81], v[194:197], v[158:161], v[66:81]
	s_barrier
	v_add3_u32 v242, v240, v236, s10
	v_add3_u32 v243, v240, v237, s10
	v_add3_u32 v244, v240, v238, s10
	v_add3_u32 v245, v240, v239, s10
	ds_read_b128 v[130:133], v242 offset:16384
	ds_read_b128 v[134:137], v243 offset:16384
	ds_read_b128 v[138:141], v244 offset:16384
	ds_read_b128 v[142:145], v245 offset:16384
	ds_read_b128 v[146:149], v242 offset:20480
	ds_read_b128 v[150:153], v243 offset:20480
	ds_read_b128 v[154:157], v244 offset:20480
	ds_read_b128 v[158:161], v245 offset:20480
	s_waitcnt vmcnt(8)
	s_barrier
	s_waitcnt lgkmcnt(0)
	v_mfma_f32_32x32x16_bf16 v[50:65], v[162:165], v[130:133], v[50:65]
	v_mfma_f32_32x32x16_bf16 v[18:33], v[162:165], v[146:149], v[18:33]
	s_add_u32 m0, s100, 0x10000
	s_nop 0
	global_load_lds_dwordx4 v228, s[6:7]
	v_add_u32_e32 v228, 0x80, v228
	v_mfma_f32_32x32x16_bf16 v[50:65], v[166:169], v[134:137], v[50:65]
	v_mfma_f32_32x32x16_bf16 v[18:33], v[166:169], v[150:153], v[18:33]
	s_add_u32 m0, s100, 0x12000
	s_nop 0
	global_load_lds_dwordx4 v230, s[6:7]
	v_add_u32_e32 v230, 0x80, v230
	v_mfma_f32_32x32x16_bf16 v[50:65], v[170:173], v[138:141], v[50:65]
	v_mfma_f32_32x32x16_bf16 v[18:33], v[170:173], v[154:157], v[18:33]
	v_mfma_f32_32x32x16_bf16 v[50:65], v[174:177], v[142:145], v[50:65]
	v_mfma_f32_32x32x16_bf16 v[18:33], v[174:177], v[158:161], v[18:33]
	s_barrier
	v_add3_u32 v242, v241, v236, 0
	v_add3_u32 v243, v241, v237, 0
	v_add3_u32 v244, v241, v238, 0
	v_add3_u32 v245, v241, v239, 0
	ds_read_b128 v[162:165], v242 offset:32768
	ds_read_b128 v[166:169], v243 offset:32768
	ds_read_b128 v[170:173], v244 offset:32768
	ds_read_b128 v[174:177], v245 offset:32768
	s_waitcnt vmcnt(4)
	s_barrier
	s_waitcnt lgkmcnt(0)
	v_mfma_f32_32x32x16_bf16 v[34:49], v[180:183], v[130:133], v[34:49]
	v_mfma_f32_32x32x16_bf16 v[2:17], v[180:183], v[146:149], v[2:17]
	s_add_u32 m0, s100, 0x1c000
	s_nop 0
	global_load_lds_dwordx4 v233, s[8:9]
	v_add_u32_e32 v233, 0x80, v233
	v_mfma_f32_32x32x16_bf16 v[34:49], v[186:189], v[134:137], v[34:49]
	v_mfma_f32_32x32x16_bf16 v[2:17], v[186:189], v[150:153], v[2:17]
	s_add_u32 m0, s100, 0x1e000
	s_nop 0
	global_load_lds_dwordx4 v235, s[8:9]
	v_add_u32_e32 v235, 0x80, v235
	v_mfma_f32_32x32x16_bf16 v[34:49], v[190:193], v[138:141], v[34:49]
	v_mfma_f32_32x32x16_bf16 v[2:17], v[190:193], v[154:157], v[2:17]
	v_mfma_f32_32x32x16_bf16 v[34:49], v[194:197], v[142:145], v[34:49]
	v_mfma_f32_32x32x16_bf16 v[2:17], v[194:197], v[158:161], v[2:17]
	s_barrier
	s_add_i32 s11, s11, 2
	s_cmp_lt_u32 s11, s25
	s_cbranch_scc1 .Lg8_m246
	v_add3_u32 v242, v240, v236, 0
	v_add3_u32 v243, v240, v237, 0
	v_add3_u32 v244, v240, v238, 0
	v_add3_u32 v245, v240, v239, 0
	ds_read_b128 v[130:133], v242
	ds_read_b128 v[134:137], v243
	ds_read_b128 v[138:141], v244
	ds_read_b128 v[142:145], v245
	ds_read_b128 v[146:149], v242 offset:4096
	ds_read_b128 v[150:153], v243 offset:4096
	ds_read_b128 v[154:157], v244 offset:4096
	ds_read_b128 v[158:161], v245 offset:4096
	s_add_u32 m0, s100, 0x14000
	s_nop 0
	global_load_lds_dwordx4 v229, s[6:7]
	v_add_u32_e32 v229, 0x80, v229
	s_add_u32 m0, s100, 0x16000
	s_nop 0
	global_load_lds_dwordx4 v231, s[6:7]
	v_add_u32_e32 v231, 0x80, v231
	s_barrier
	s_waitcnt lgkmcnt(0)
	v_mfma_f32_32x32x16_bf16 v[114:129], v[162:165], v[130:133], v[114:129]
	v_mfma_f32_32x32x16_bf16 v[82:97], v[162:165], v[146:149], v[82:97]
	v_mfma_f32_32x32x16_bf16 v[114:129], v[166:169], v[134:137], v[114:129]
	v_mfma_f32_32x32x16_bf16 v[82:97], v[166:169], v[150:153], v[82:97]
	v_mfma_f32_32x32x16_bf16 v[114:129], v[170:173], v[138:141], v[114:129]
	v_mfma_f32_32x32x16_bf16 v[82:97], v[170:173], v[154:157], v[82:97]
	v_mfma_f32_32x32x16_bf16 v[114:129], v[174:177], v[142:145], v[114:129]
	v_mfma_f32_32x32x16_bf16 v[82:97], v[174:177], v[158:161], v[82:97]
	s_barrier
; #define MFMA(a, b, c) __builtin_amdgcn_mfma_f32_32x32x16_bf16((a), (b), (c), 0, 0, 0)
; template <bool SWAP>
; DI void gemm_mainloop(f32x16 (&acc)[4][2], const u16* __restrict__ A, int lda, int rlo, int rhi,
;                       const u16* __restrict__ B, int ldb, int K, char* lds, const u16* zero_line) {
;     ...
;   auto ldfrag = [&](const char* st, int ks, int buf) {
;     const int co = ((2 * ks + h) ^ sw) << 4;
; #pragma unroll
;     for (int mi = 0; mi < 4; ++mi) fa[buf][mi] = *(const bf16x8*)(st + arow_off + mi * 4096 + co);
; #pragma unroll
;     for (int ni = 0; ni < 2; ++ni) fb[buf][ni] = *(const bf16x8*)(st + brow_off + ni * 4096 + co);
;   };
;   auto mma = [&](int buf) {
; #pragma unroll
;     for (int mi = 0; mi < 4; ++mi)
; #pragma unroll
;       for (int ni = 0; ni < 2; ++ni)
;         acc[mi][ni] = SWAP ? MFMA(fb[buf][ni], fa[buf][mi], acc[mi][ni]) : MFMA(fa[buf][mi], fb[buf][ni], acc[mi][ni]);
;   };
;   auto pat_rd = [&]() {
; #pragma unroll
;     for (int g = 0; g < 6; ++g) {
;       __builtin_amdgcn_sched_group_barrier(0x100, 1, 0);
;       __builtin_amdgcn_sched_group_barrier(0x008, 1, 0);
;     }
;     __builtin_amdgcn_sched_group_barrier(0x008, 2, 0);
;   };
; #pragma unroll 2
;   for (int kt = 0; kt < nk; ++kt) {
;     const char* st = lds + (kt & 1) * 65536;
;     ldfrag(st, 0, 0);
;     mma(1);
;     pat_rd();
;     if (kt + 1 < nk) glds(kt + 1, (kt + 1) & 1);
;     ldfrag(st, 1, 1);
;     mma(0);
;     pat_rd();
;     ldfrag(st, 2, 0);
;     mma(1);
;     pat_rd();
;     ldfrag(st, 3, 1);
;     mma(0);
;     pat_rd();
;     asm volatile("s_waitcnt vmcnt(0)" ::: "memory");
;     __syncthreads();
;   }
;   mma(1);
	v_add3_u32 v242, v241, v236, 0
	v_add3_u32 v243, v241, v237, 0
	v_add3_u32 v244, v241, v238, 0
	v_add3_u32 v245, v241, v239, 0
	ds_read_b128 v[180:183], v242 offset:49152
	ds_read_b128 v[186:189], v243 offset:49152
	ds_read_b128 v[190:193], v244 offset:49152
	ds_read_b128 v[194:197], v245 offset:49152
	s_barrier
	s_waitcnt lgkmcnt(0)
	v_mfma_f32_32x32x16_bf16 v[98:113], v[180:183], v[130:133], v[98:113]
	v_mfma_f32_32x32x16_bf16 v[66:81], v[180:183], v[146:149], v[66:81]
	v_mfma_f32_32x32x16_bf16 v[98:113], v[186:189], v[134:137], v[98:113]
	v_mfma_f32_32x32x16_bf16 v[66:81], v[186:189], v[150:153], v[66:81]
	v_mfma_f32_32x32x16_bf16 v[98:113], v[190:193], v[138:141], v[98:113]
	v_mfma_f32_32x32x16_bf16 v[66:81], v[190:193], v[154:157], v[66:81]
	v_mfma_f32_32x32x16_bf16 v[98:113], v[194:197], v[142:145], v[98:113]
	v_mfma_f32_32x32x16_bf16 v[66:81], v[194:197], v[158:161], v[66:81]
	s_barrier
	v_add3_u32 v242, v240, v236, 0
	v_add3_u32 v243, v240, v237, 0
	v_add3_u32 v244, v240, v238, 0
	v_add3_u32 v245, v240, v239, 0
	ds_read_b128 v[130:133], v242 offset:16384
	ds_read_b128 v[134:137], v243 offset:16384
	ds_read_b128 v[138:141], v244 offset:16384
	ds_read_b128 v[142:145], v245 offset:16384
	ds_read_b128 v[146:149], v242 offset:20480
	ds_read_b128 v[150:153], v243 offset:20480
	ds_read_b128 v[154:157], v244 offset:20480
	ds_read_b128 v[158:161], v245 offset:20480
	s_waitcnt vmcnt(4)
	s_barrier
	s_waitcnt lgkmcnt(0)
	v_mfma_f32_32x32x16_bf16 v[50:65], v[162:165], v[130:133], v[50:65]
	v_mfma_f32_32x32x16_bf16 v[18:33], v[162:165], v[146:149], v[18:33]
	v_mfma_f32_32x32x16_bf16 v[50:65], v[166:169], v[134:137], v[50:65]
	v_mfma_f32_32x32x16_bf16 v[18:33], v[166:169], v[150:153], v[18:33]
	v_mfma_f32_32x32x16_bf16 v[50:65], v[170:173], v[138:141], v[50:65]
	v_mfma_f32_32x32x16_bf16 v[18:33], v[170:173], v[154:157], v[18:33]
	v_mfma_f32_32x32x16_bf16 v[50:65], v[174:177], v[142:145], v[50:65]
	v_mfma_f32_32x32x16_bf16 v[18:33], v[174:177], v[158:161], v[18:33]
	v_mfma_f32_32x32x16_bf16 v[34:49], v[180:183], v[130:133], v[34:49]
	v_mfma_f32_32x32x16_bf16 v[2:17], v[180:183], v[146:149], v[2:17]
	v_mfma_f32_32x32x16_bf16 v[34:49], v[186:189], v[134:137], v[34:49]
	v_mfma_f32_32x32x16_bf16 v[2:17], v[186:189], v[150:153], v[2:17]
	v_mfma_f32_32x32x16_bf16 v[34:49], v[190:193], v[138:141], v[34:49]
	v_mfma_f32_32x32x16_bf16 v[2:17], v[190:193], v[154:157], v[2:17]
	v_mfma_f32_32x32x16_bf16 v[34:49], v[194:197], v[142:145], v[34:49]
	v_mfma_f32_32x32x16_bf16 v[2:17], v[194:197], v[158:161], v[2:17]
	s_barrier
	v_add3_u32 v242, v241, v236, s10
	v_add3_u32 v243, v241, v237, s10
	v_add3_u32 v244, v241, v238, s10
	v_add3_u32 v245, v241, v239, s10
	ds_read_b128 v[162:165], v242 offset:32768
	ds_read_b128 v[166:169], v243 offset:32768
	ds_read_b128 v[170:173], v244 offset:32768
	ds_read_b128 v[174:177], v245 offset:32768
	v_add3_u32 v242, v240, v236, s10
	v_add3_u32 v243, v240, v237, s10
	v_add3_u32 v244, v240, v238, s10
	v_add3_u32 v245, v240, v239, s10
	ds_read_b128 v[130:133], v242
	ds_read_b128 v[134:137], v243
	ds_read_b128 v[138:141], v244
	ds_read_b128 v[142:145], v245
	ds_read_b128 v[146:149], v242 offset:4096
	ds_read_b128 v[150:153], v243 offset:4096
	ds_read_b128 v[154:157], v244 offset:4096
	ds_read_b128 v[158:161], v245 offset:4096
	s_waitcnt vmcnt(2)
	s_barrier
	s_waitcnt lgkmcnt(0)
	v_mfma_f32_32x32x16_bf16 v[114:129], v[162:165], v[130:133], v[114:129]
	v_mfma_f32_32x32x16_bf16 v[82:97], v[162:165], v[146:149], v[82:97]
	v_mfma_f32_32x32x16_bf16 v[114:129], v[166:169], v[134:137], v[114:129]
	v_mfma_f32_32x32x16_bf16 v[82:97], v[166:169], v[150:153], v[82:97]
	v_mfma_f32_32x32x16_bf16 v[114:129], v[170:173], v[138:141], v[114:129]
	v_mfma_f32_32x32x16_bf16 v[82:97], v[170:173], v[154:157], v[82:97]
	v_mfma_f32_32x32x16_bf16 v[114:129], v[174:177], v[142:145], v[114:129]
	v_mfma_f32_32x32x16_bf16 v[82:97], v[174:177], v[158:161], v[82:97]
	s_barrier
	v_add3_u32 v242, v241, v236, s10
	v_add3_u32 v243, v241, v237, s10
	v_add3_u32 v244, v241, v238, s10
	v_add3_u32 v245, v241, v239, s10
	ds_read_b128 v[180:183], v242 offset:49152
	ds_read_b128 v[186:189], v243 offset:49152
	ds_read_b128 v[190:193], v244 offset:49152
	ds_read_b128 v[194:197], v245 offset:49152
	s_waitcnt vmcnt(0)
	s_barrier
	s_waitcnt lgkmcnt(0)
	v_mfma_f32_32x32x16_bf16 v[98:113], v[180:183], v[130:133], v[98:113]
	v_mfma_f32_32x32x16_bf16 v[66:81], v[180:183], v[146:149], v[66:81]
	v_mfma_f32_32x32x16_bf16 v[98:113], v[186:189], v[134:137], v[98:113]
	v_mfma_f32_32x32x16_bf16 v[66:81], v[186:189], v[150:153], v[66:81]
	v_mfma_f32_32x32x16_bf16 v[98:113], v[190:193], v[138:141], v[98:113]
	v_mfma_f32_32x32x16_bf16 v[66:81], v[190:193], v[154:157], v[66:81]
	v_mfma_f32_32x32x16_bf16 v[98:113], v[194:197], v[142:145], v[98:113]
	v_mfma_f32_32x32x16_bf16 v[66:81], v[194:197], v[158:161], v[66:81]
	s_barrier
	v_add3_u32 v242, v240, v236, s10
	v_add3_u32 v243, v240, v237, s10
	v_add3_u32 v244, v240, v238, s10
	v_add3_u32 v245, v240, v239, s10
	ds_read_b128 v[130:133], v242 offset:16384
	ds_read_b128 v[134:137], v243 offset:16384
	ds_read_b128 v[138:141], v244 offset:16384
	ds_read_b128 v[142:145], v245 offset:16384
	ds_read_b128 v[146:149], v242 offset:20480
	ds_read_b128 v[150:153], v243 offset:20480
	ds_read_b128 v[154:157], v244 offset:20480
	ds_read_b128 v[158:161], v245 offset:20480
	s_barrier
	s_waitcnt lgkmcnt(0)
	v_mfma_f32_32x32x16_bf16 v[50:65], v[162:165], v[130:133], v[50:65]
	v_mfma_f32_32x32x16_bf16 v[18:33], v[162:165], v[146:149], v[18:33]
	v_mfma_f32_32x32x16_bf16 v[50:65], v[166:169], v[134:137], v[50:65]
	v_mfma_f32_32x32x16_bf16 v[18:33], v[166:169], v[150:153], v[18:33]
	v_mfma_f32_32x32x16_bf16 v[50:65], v[170:173], v[138:141], v[50:65]
	v_mfma_f32_32x32x16_bf16 v[18:33], v[170:173], v[154:157], v[18:33]
	v_mfma_f32_32x32x16_bf16 v[50:65], v[174:177], v[142:145], v[50:65]
	v_mfma_f32_32x32x16_bf16 v[18:33], v[174:177], v[158:161], v[18:33]
	v_mfma_f32_32x32x16_bf16 v[34:49], v[180:183], v[130:133], v[34:49]
	v_mfma_f32_32x32x16_bf16 v[2:17], v[180:183], v[146:149], v[2:17]
	v_mfma_f32_32x32x16_bf16 v[34:49], v[186:189], v[134:137], v[34:49]
	v_mfma_f32_32x32x16_bf16 v[2:17], v[186:189], v[150:153], v[2:17]
	v_mfma_f32_32x32x16_bf16 v[34:49], v[190:193], v[138:141], v[34:49]
	v_mfma_f32_32x32x16_bf16 v[2:17], v[190:193], v[154:157], v[2:17]
	v_mfma_f32_32x32x16_bf16 v[34:49], v[194:197], v[142:145], v[34:49]
	v_mfma_f32_32x32x16_bf16 v[2:17], v[194:197], v[158:161], v[2:17]
	s_barrier
	s_cmp_eq_u32 s101, 0
	s_cbranch_scc0 .Lg8_m246_p1
	s_barrier

; #define MFMA(a, b, c) __builtin_amdgcn_mfma_f32_32x32x16_bf16((a), (b), (c), 0, 0, 0)
; template <bool SWAP>
; DI void gemm_mainloop(f32x16 (&acc)[4][2], const u16* __restrict__ A, int lda, int rlo, int rhi,
;                       const u16* __restrict__ B, int ldb, int K, char* lds, const u16* zero_line) {
;     ...
;   auto glds = [&](int kt, int st) {
;     char* as_ = lds + st * 65536 + tid * 16;
; #pragma unroll
;     for (int i = 0; i < 4; ++i) {
;       const int rr = lr + 64 * i;
;       const u16* srca = (rr >= rlo && rr < rhi) ? (ap + (ptrdiff_t)(64 * i) * lda + kt * 64) : (zero_line + lc * 8);
;       __builtin_amdgcn_global_load_lds((const unsigned*)srca, (lds_u32*)(as_ + i * 8192), 16, 0, 0);
;       __builtin_amdgcn_global_load_lds((const unsigned*)(bp + (ptrdiff_t)(64 * i) * ldb + kt * 64), (lds_u32*)(as_ + 32768 + i * 8192), 16, 0, 0);
;     }
;   };
;     ...
;   auto ldfrag = [&](const char* st, int ks, int buf) {
;     const int co = ((2 * ks + h) ^ sw) << 4;
; #pragma unroll
;     for (int mi = 0; mi < 4; ++mi) fa[buf][mi] = *(const bf16x8*)(st + arow_off + mi * 4096 + co);
; #pragma unroll
;     for (int ni = 0; ni < 2; ++ni) fb[buf][ni] = *(const bf16x8*)(st + brow_off + ni * 4096 + co);
;   };
;   auto mma = [&](int buf) {
; #pragma unroll
;     for (int mi = 0; mi < 4; ++mi)
; #pragma unroll
;       for (int ni = 0; ni < 2; ++ni)
;         acc[mi][ni] = SWAP ? MFMA(fb[buf][ni], fa[buf][mi], acc[mi][ni]) : MFMA(fa[buf][mi], fb[buf][ni], acc[mi][ni]);
;   };
;   auto pat_rd = [&]() {
; #pragma unroll
;     for (int g = 0; g < 6; ++g) {
;       __builtin_amdgcn_sched_group_barrier(0x100, 1, 0);
;       __builtin_amdgcn_sched_group_barrier(0x008, 1, 0);
;     }
;     __builtin_amdgcn_sched_group_barrier(0x008, 2, 0);
;   };
; #pragma unroll 2
;   for (int kt = 0; kt < nk; ++kt) {
;     const char* st = lds + (kt & 1) * 65536;
;     ldfrag(st, 0, 0);
;     mma(1);
;     pat_rd();
;     if (kt + 1 < nk) glds(kt + 1, (kt + 1) & 1);
;     ldfrag(st, 1, 1);
;     mma(0);
;     pat_rd();
;     ldfrag(st, 2, 0);
;     mma(1);
;     pat_rd();
;     ldfrag(st, 3, 1);
;     mma(0);
;     pat_rd();
;     asm volatile("s_waitcnt vmcnt(0)" ::: "memory");
;     __syncthreads();
;   }
.Lg8_ia:
	v_add3_u32 v187, v166, v161, 0
	v_add3_u32 v248, v166, v163, 0
	ds_read_b128 v[130:133], v187
	ds_read_b128 v[134:137], v248
	ds_read_b128 v[146:149], v187 offset:4096
	ds_read_b128 v[150:153], v248 offset:4096
	v_add3_u32 v187, v166, v164, 0
	v_add3_u32 v248, v166, v165, 0
	ds_read_b128 v[138:141], v187
	ds_read_b128 v[142:145], v248
	ds_read_b128 v[168:171], v187 offset:4096
	ds_read_b128 v[172:175], v248 offset:4096
	s_barrier
	s_waitcnt lgkmcnt(0)
	v_mfma_f32_32x32x16_bf16 v[114:129], v[176:179], v[130:133], v[114:129]
	v_mfma_f32_32x32x16_bf16 v[98:113], v[176:179], v[146:149], v[98:113]
	s_add_u32 m0, s100, 0x14000
	s_nop 0
	global_load_lds_dwordx4 v241, s[6:7]
	v_add_u32_e32 v241, 0x80, v241
	v_mfma_f32_32x32x16_bf16 v[114:129], v[180:183], v[134:137], v[114:129]
	v_mfma_f32_32x32x16_bf16 v[98:113], v[180:183], v[150:153], v[98:113]
	s_add_u32 m0, s100, 0x16000
	s_nop 0
	global_load_lds_dwordx4 v243, s[6:7]
	v_add_u32_e32 v243, 0x80, v243
	v_mfma_f32_32x32x16_bf16 v[114:129], v[192:195], v[138:141], v[114:129]
	v_mfma_f32_32x32x16_bf16 v[98:113], v[192:195], v[168:171], v[98:113]
	v_mfma_f32_32x32x16_bf16 v[114:129], v[196:199], v[142:145], v[114:129]
	v_mfma_f32_32x32x16_bf16 v[98:113], v[196:199], v[172:175], v[98:113]
	s_barrier
	v_add3_u32 v187, v186, v161, 0
	v_add3_u32 v248, v186, v163, 0
	ds_read_b128 v[200:203], v187 offset:49152
	ds_read_b128 v[228:231], v248 offset:49152
	v_add3_u32 v187, v186, v164, 0
	v_add3_u32 v248, v186, v165, 0
	ds_read_b128 v[232:235], v187 offset:49152
	ds_read_b128 v[236:239], v248 offset:49152
	s_barrier
	s_waitcnt lgkmcnt(0)
	v_mfma_f32_32x32x16_bf16 v[82:97], v[200:203], v[130:133], v[82:97]
	v_mfma_f32_32x32x16_bf16 v[50:65], v[200:203], v[146:149], v[50:65]
	s_add_u32 m0, s100, 0x8000
	s_nop 0
	global_load_lds_dwordx4 v244, s[8:9]
	v_add_u32_e32 v244, 0x80, v244
	v_mfma_f32_32x32x16_bf16 v[82:97], v[228:231], v[134:137], v[82:97]
	v_mfma_f32_32x32x16_bf16 v[50:65], v[228:231], v[150:153], v[50:65]
	s_add_u32 m0, s100, 0xa000
	s_nop 0
	global_load_lds_dwordx4 v246, s[8:9]
	v_add_u32_e32 v246, 0x80, v246
	v_mfma_f32_32x32x16_bf16 v[82:97], v[232:235], v[138:141], v[82:97]
	v_mfma_f32_32x32x16_bf16 v[50:65], v[232:235], v[168:171], v[50:65]
	v_mfma_f32_32x32x16_bf16 v[82:97], v[236:239], v[142:145], v[82:97]
	v_mfma_f32_32x32x16_bf16 v[50:65], v[236:239], v[172:175], v[50:65]
	s_barrier
	v_add3_u32 v187, v166, v161, 0
	v_add3_u32 v248, v166, v163, 0
	ds_read_b128 v[130:133], v187 offset:16384
	ds_read_b128 v[134:137], v248 offset:16384
	ds_read_b128 v[146:149], v187 offset:20480
	ds_read_b128 v[150:153], v248 offset:20480
	v_add3_u32 v187, v166, v164, 0
	v_add3_u32 v248, v166, v165, 0
	ds_read_b128 v[138:141], v187 offset:16384
	ds_read_b128 v[142:145], v248 offset:16384
	ds_read_b128 v[168:171], v187 offset:20480
	ds_read_b128 v[172:175], v248 offset:20480
	s_waitcnt vmcnt(8)
	s_barrier
	s_waitcnt lgkmcnt(0)
	v_mfma_f32_32x32x16_bf16 v[66:81], v[176:179], v[130:133], v[66:81]
	v_mfma_f32_32x32x16_bf16 v[34:49], v[176:179], v[146:149], v[34:49]
	s_add_u32 m0, s100, 0x0
	s_nop 0
	global_load_lds_dwordx4 v240, s[6:7]
	v_add_u32_e32 v240, 0x80, v240
	v_mfma_f32_32x32x16_bf16 v[66:81], v[180:183], v[134:137], v[66:81]
	v_mfma_f32_32x32x16_bf16 v[34:49], v[180:183], v[150:153], v[34:49]
	s_add_u32 m0, s100, 0x2000
	s_nop 0
	global_load_lds_dwordx4 v242, s[6:7]
	v_add_u32_e32 v242, 0x80, v242
	v_mfma_f32_32x32x16_bf16 v[66:81], v[192:195], v[138:141], v[66:81]
	v_mfma_f32_32x32x16_bf16 v[34:49], v[192:195], v[168:171], v[34:49]
	v_mfma_f32_32x32x16_bf16 v[66:81], v[196:199], v[142:145], v[66:81]
	v_mfma_f32_32x32x16_bf16 v[34:49], v[196:199], v[172:175], v[34:49]
	s_barrier
	v_add3_u32 v187, v186, v161, s10
	v_add3_u32 v248, v186, v163, s10
	ds_read_b128 v[176:179], v187 offset:32768
	ds_read_b128 v[180:183], v248 offset:32768
	v_add3_u32 v187, v186, v164, s10
	v_add3_u32 v248, v186, v165, s10
	ds_read_b128 v[192:195], v187 offset:32768
	ds_read_b128 v[196:199], v248 offset:32768
	s_waitcnt vmcnt(4)
	s_barrier
	s_waitcnt lgkmcnt(0)
	v_mfma_f32_32x32x16_bf16 v[18:33], v[200:203], v[130:133], v[18:33]
	v_mfma_f32_32x32x16_bf16 v[2:17], v[200:203], v[146:149], v[2:17]
	s_add_u32 m0, s100, 0xc000
	s_nop 0
	global_load_lds_dwordx4 v245, s[8:9]
	v_add_u32_e32 v245, 0x80, v245
	v_mfma_f32_32x32x16_bf16 v[18:33], v[228:231], v[134:137], v[18:33]
	v_mfma_f32_32x32x16_bf16 v[2:17], v[228:231], v[150:153], v[2:17]
	s_add_u32 m0, s100, 0xe000
	s_nop 0
	global_load_lds_dwordx4 v247, s[8:9]
	v_add_u32_e32 v247, 0x80, v247
	v_mfma_f32_32x32x16_bf16 v[18:33], v[232:235], v[138:141], v[18:33]
	v_mfma_f32_32x32x16_bf16 v[2:17], v[232:235], v[168:171], v[2:17]
	v_mfma_f32_32x32x16_bf16 v[18:33], v[236:239], v[142:145], v[18:33]
	v_mfma_f32_32x32x16_bf16 v[2:17], v[236:239], v[172:175], v[2:17]
	s_barrier
	v_add3_u32 v187, v166, v161, s10
	v_add3_u32 v248, v166, v163, s10
	ds_read_b128 v[130:133], v187
	ds_read_b128 v[134:137], v248
	ds_read_b128 v[146:149], v187 offset:4096
	ds_read_b128 v[150:153], v248 offset:4096
	v_add3_u32 v187, v166, v164, s10
	v_add3_u32 v248, v166, v165, s10
	ds_read_b128 v[138:141], v187
	ds_read_b128 v[142:145], v248
	ds_read_b128 v[168:171], v187 offset:4096
	ds_read_b128 v[172:175], v248 offset:4096
	s_barrier
; #define MFMA(a, b, c) __builtin_amdgcn_mfma_f32_32x32x16_bf16((a), (b), (c), 0, 0, 0)
; template <bool SWAP>
; DI void gemm_mainloop(f32x16 (&acc)[4][2], const u16* __restrict__ A, int lda, int rlo, int rhi,
;                       const u16* __restrict__ B, int ldb, int K, char* lds, const u16* zero_line) {
;     ...
;   auto glds = [&](int kt, int st) {
;     char* as_ = lds + st * 65536 + tid * 16;
; #pragma unroll
;     for (int i = 0; i < 4; ++i) {
;       const int rr = lr + 64 * i;
;       const u16* srca = (rr >= rlo && rr < rhi) ? (ap + (ptrdiff_t)(64 * i) * lda + kt * 64) : (zero_line + lc * 8);
;       __builtin_amdgcn_global_load_lds((const unsigned*)srca, (lds_u32*)(as_ + i * 8192), 16, 0, 0);
;       __builtin_amdgcn_global_load_lds((const unsigned*)(bp + (ptrdiff_t)(64 * i) * ldb + kt * 64), (lds_u32*)(as_ + 32768 + i * 8192), 16, 0, 0);
;     }
;   };
;     ...
;   auto ldfrag = [&](const char* st, int ks, int buf) {
;     const int co = ((2 * ks + h) ^ sw) << 4;
; #pragma unroll
;     for (int mi = 0; mi < 4; ++mi) fa[buf][mi] = *(const bf16x8*)(st + arow_off + mi * 4096 + co);
; #pragma unroll
;     for (int ni = 0; ni < 2; ++ni) fb[buf][ni] = *(const bf16x8*)(st + brow_off + ni * 4096 + co);
;   };
;   auto mma = [&](int buf) {
; #pragma unroll
;     for (int mi = 0; mi < 4; ++mi)
; #pragma unroll
;       for (int ni = 0; ni < 2; ++ni)
;         acc[mi][ni] = SWAP ? MFMA(fb[buf][ni], fa[buf][mi], acc[mi][ni]) : MFMA(fa[buf][mi], fb[buf][ni], acc[mi][ni]);
;   };
;   auto pat_rd = [&]() {
; #pragma unroll
;     for (int g = 0; g < 6; ++g) {
;       __builtin_amdgcn_sched_group_barrier(0x100, 1, 0);
;       __builtin_amdgcn_sched_group_barrier(0x008, 1, 0);
;     }
;     __builtin_amdgcn_sched_group_barrier(0x008, 2, 0);
;   };
; #pragma unroll 2
;   for (int kt = 0; kt < nk; ++kt) {
;     const char* st = lds + (kt & 1) * 65536;
;     ldfrag(st, 0, 0);
;     mma(1);
;     pat_rd();
;     if (kt + 1 < nk) glds(kt + 1, (kt + 1) & 1);
;     ldfrag(st, 1, 1);
;     mma(0);
;     pat_rd();
;     ldfrag(st, 2, 0);
;     mma(1);
;     pat_rd();
;     ldfrag(st, 3, 1);
;     mma(0);
;     pat_rd();
;     asm volatile("s_waitcnt vmcnt(0)" ::: "memory");
;     __syncthreads();
;   }
	s_waitcnt lgkmcnt(0)
	v_mfma_f32_32x32x16_bf16 v[114:129], v[176:179], v[130:133], v[114:129]
	v_mfma_f32_32x32x16_bf16 v[98:113], v[176:179], v[146:149], v[98:113]
	s_add_u32 m0, s100, 0x4000
	s_nop 0
	global_load_lds_dwordx4 v241, s[6:7]
	v_add_u32_e32 v241, 0x80, v241
	v_mfma_f32_32x32x16_bf16 v[114:129], v[180:183], v[134:137], v[114:129]
	v_mfma_f32_32x32x16_bf16 v[98:113], v[180:183], v[150:153], v[98:113]
	s_add_u32 m0, s100, 0x6000
	s_nop 0
	global_load_lds_dwordx4 v243, s[6:7]
	v_add_u32_e32 v243, 0x80, v243
	v_mfma_f32_32x32x16_bf16 v[114:129], v[192:195], v[138:141], v[114:129]
	v_mfma_f32_32x32x16_bf16 v[98:113], v[192:195], v[168:171], v[98:113]
	v_mfma_f32_32x32x16_bf16 v[114:129], v[196:199], v[142:145], v[114:129]
	v_mfma_f32_32x32x16_bf16 v[98:113], v[196:199], v[172:175], v[98:113]
	s_barrier
	v_add3_u32 v187, v186, v161, s10
	v_add3_u32 v248, v186, v163, s10
	ds_read_b128 v[200:203], v187 offset:49152
	ds_read_b128 v[228:231], v248 offset:49152
	v_add3_u32 v187, v186, v164, s10
	v_add3_u32 v248, v186, v165, s10
	ds_read_b128 v[232:235], v187 offset:49152
	ds_read_b128 v[236:239], v248 offset:49152
	s_barrier
	s_waitcnt lgkmcnt(0)
	v_mfma_f32_32x32x16_bf16 v[82:97], v[200:203], v[130:133], v[82:97]
	v_mfma_f32_32x32x16_bf16 v[50:65], v[200:203], v[146:149], v[50:65]
	s_add_u32 m0, s100, 0x18000
	s_nop 0
	global_load_lds_dwordx4 v244, s[8:9]
	v_add_u32_e32 v244, 0x80, v244
	v_mfma_f32_32x32x16_bf16 v[82:97], v[228:231], v[134:137], v[82:97]
	v_mfma_f32_32x32x16_bf16 v[50:65], v[228:231], v[150:153], v[50:65]
	s_add_u32 m0, s100, 0x1a000
	s_nop 0
	global_load_lds_dwordx4 v246, s[8:9]
	v_add_u32_e32 v246, 0x80, v246
	v_mfma_f32_32x32x16_bf16 v[82:97], v[232:235], v[138:141], v[82:97]
	v_mfma_f32_32x32x16_bf16 v[50:65], v[232:235], v[168:171], v[50:65]
	v_mfma_f32_32x32x16_bf16 v[82:97], v[236:239], v[142:145], v[82:97]
	v_mfma_f32_32x32x16_bf16 v[50:65], v[236:239], v[172:175], v[50:65]
	s_barrier
	v_add3_u32 v187, v166, v161, s10
	v_add3_u32 v248, v166, v163, s10
	ds_read_b128 v[130:133], v187 offset:16384
	ds_read_b128 v[134:137], v248 offset:16384
	ds_read_b128 v[146:149], v187 offset:20480
	ds_read_b128 v[150:153], v248 offset:20480
	v_add3_u32 v187, v166, v164, s10
	v_add3_u32 v248, v166, v165, s10
	ds_read_b128 v[138:141], v187 offset:16384
	ds_read_b128 v[142:145], v248 offset:16384
	ds_read_b128 v[168:171], v187 offset:20480
	ds_read_b128 v[172:175], v248 offset:20480
	s_waitcnt vmcnt(8)
	s_barrier
	s_waitcnt lgkmcnt(0)
	v_mfma_f32_32x32x16_bf16 v[66:81], v[176:179], v[130:133], v[66:81]
	v_mfma_f32_32x32x16_bf16 v[34:49], v[176:179], v[146:149], v[34:49]
	s_add_u32 m0, s100, 0x10000
	s_nop 0
	global_load_lds_dwordx4 v240, s[6:7]
	v_add_u32_e32 v240, 0x80, v240
	v_mfma_f32_32x32x16_bf16 v[66:81], v[180:183], v[134:137], v[66:81]
	v_mfma_f32_32x32x16_bf16 v[34:49], v[180:183], v[150:153], v[34:49]
	s_add_u32 m0, s100, 0x12000
	s_nop 0
	global_load_lds_dwordx4 v242, s[6:7]
	v_add_u32_e32 v242, 0x80, v242
	v_mfma_f32_32x32x16_bf16 v[66:81], v[192:195], v[138:141], v[66:81]
	v_mfma_f32_32x32x16_bf16 v[34:49], v[192:195], v[168:171], v[34:49]
	v_mfma_f32_32x32x16_bf16 v[66:81], v[196:199], v[142:145], v[66:81]
	v_mfma_f32_32x32x16_bf16 v[34:49], v[196:199], v[172:175], v[34:49]
	s_barrier
	v_add3_u32 v187, v186, v161, 0
	v_add3_u32 v248, v186, v163, 0
	ds_read_b128 v[176:179], v187 offset:32768
	ds_read_b128 v[180:183], v248 offset:32768
	v_add3_u32 v187, v186, v164, 0
	v_add3_u32 v248, v186, v165, 0
	ds_read_b128 v[192:195], v187 offset:32768
	ds_read_b128 v[196:199], v248 offset:32768
	s_waitcnt vmcnt(4)
	s_barrier
	s_waitcnt lgkmcnt(0)
	v_mfma_f32_32x32x16_bf16 v[18:33], v[200:203], v[130:133], v[18:33]
	v_mfma_f32_32x32x16_bf16 v[2:17], v[200:203], v[146:149], v[2:17]
	s_add_u32 m0, s100, 0x1c000
	s_nop 0
	global_load_lds_dwordx4 v245, s[8:9]
	v_add_u32_e32 v245, 0x80, v245
	v_mfma_f32_32x32x16_bf16 v[18:33], v[228:231], v[134:137], v[18:33]
	v_mfma_f32_32x32x16_bf16 v[2:17], v[228:231], v[150:153], v[2:17]
	s_add_u32 m0, s100, 0x1e000
	s_nop 0
	global_load_lds_dwordx4 v247, s[8:9]
	v_add_u32_e32 v247, 0x80, v247
	v_mfma_f32_32x32x16_bf16 v[18:33], v[232:235], v[138:141], v[18:33]
	v_mfma_f32_32x32x16_bf16 v[2:17], v[232:235], v[168:171], v[2:17]
	v_mfma_f32_32x32x16_bf16 v[18:33], v[236:239], v[142:145], v[18:33]
	v_mfma_f32_32x32x16_bf16 v[2:17], v[236:239], v[172:175], v[2:17]
	s_barrier
	s_add_i32 s11, s11, 2
	s_cmp_lt_u32 s11, 14
	s_cbranch_scc1 .Lg8_ia
	v_add3_u32 v187, v166, v161, 0
	v_add3_u32 v248, v166, v163, 0
	ds_read_b128 v[130:133], v187
	ds_read_b128 v[134:137], v248
	ds_read_b128 v[146:149], v187 offset:4096
	ds_read_b128 v[150:153], v248 offset:4096
	v_add3_u32 v187, v166, v164, 0
	v_add3_u32 v248, v166, v165, 0
	ds_read_b128 v[138:141], v187
	ds_read_b128 v[142:145], v248
	ds_read_b128 v[168:171], v187 offset:4096
	ds_read_b128 v[172:175], v248 offset:4096
	s_add_u32 m0, s100, 0x14000
	s_nop 0
	global_load_lds_dwordx4 v241, s[6:7]
	v_add_u32_e32 v241, 0x80, v241
	s_add_u32 m0, s100, 0x16000
	s_nop 0
	global_load_lds_dwordx4 v243, s[6:7]
	v_add_u32_e32 v243, 0x80, v243
	s_barrier
	s_waitcnt lgkmcnt(0)
	v_mfma_f32_32x32x16_bf16 v[114:129], v[176:179], v[130:133], v[114:129]
	v_mfma_f32_32x32x16_bf16 v[98:113], v[176:179], v[146:149], v[98:113]
	v_mfma_f32_32x32x16_bf16 v[114:129], v[180:183], v[134:137], v[114:129]
	v_mfma_f32_32x32x16_bf16 v[98:113], v[180:183], v[150:153], v[98:113]
	v_mfma_f32_32x32x16_bf16 v[114:129], v[192:195], v[138:141], v[114:129]
	v_mfma_f32_32x32x16_bf16 v[98:113], v[192:195], v[168:171], v[98:113]
	v_mfma_f32_32x32x16_bf16 v[114:129], v[196:199], v[142:145], v[114:129]
	v_mfma_f32_32x32x16_bf16 v[98:113], v[196:199], v[172:175], v[98:113]
	s_barrier
; template <bool SWAP>
; DI void gemm_mainloop(f32x16 (&acc)[4][2], const u16* __restrict__ A, int lda, int rlo, int rhi,
;                       const u16* __restrict__ B, int ldb, int K, char* lds, const u16* zero_line) {
;     ...
;   for (int kt = 0; kt < nk; ++kt) {
;     const char* st = lds + (kt & 1) * 65536;
;     ldfrag(st, 0, 0);
;     mma(1);
;     pat_rd();
;     if (kt + 1 < nk) glds(kt + 1, (kt + 1) & 1);
;     ldfrag(st, 1, 1);
;     mma(0);
;     pat_rd();
;     ldfrag(st, 2, 0);
;     mma(1);
;     pat_rd();
;     ldfrag(st, 3, 1);
;     mma(0);
;     pat_rd();
;     asm volatile("s_waitcnt vmcnt(0)" ::: "memory");
;     __syncthreads();
;   }
;   mma(1);
	v_add3_u32 v187, v186, v161, 0
	v_add3_u32 v248, v186, v163, 0
	ds_read_b128 v[200:203], v187 offset:49152
	ds_read_b128 v[228:231], v248 offset:49152
	v_add3_u32 v187, v186, v164, 0
	v_add3_u32 v248, v186, v165, 0
	ds_read_b128 v[232:235], v187 offset:49152
	ds_read_b128 v[236:239], v248 offset:49152
	s_barrier
	s_waitcnt lgkmcnt(0)
	v_mfma_f32_32x32x16_bf16 v[82:97], v[200:203], v[130:133], v[82:97]
	v_mfma_f32_32x32x16_bf16 v[50:65], v[200:203], v[146:149], v[50:65]
	v_mfma_f32_32x32x16_bf16 v[82:97], v[228:231], v[134:137], v[82:97]
	v_mfma_f32_32x32x16_bf16 v[50:65], v[228:231], v[150:153], v[50:65]
	v_mfma_f32_32x32x16_bf16 v[82:97], v[232:235], v[138:141], v[82:97]
	v_mfma_f32_32x32x16_bf16 v[50:65], v[232:235], v[168:171], v[50:65]
	v_mfma_f32_32x32x16_bf16 v[82:97], v[236:239], v[142:145], v[82:97]
	v_mfma_f32_32x32x16_bf16 v[50:65], v[236:239], v[172:175], v[50:65]
	s_barrier
	v_add3_u32 v187, v166, v161, 0
	v_add3_u32 v248, v166, v163, 0
	ds_read_b128 v[130:133], v187 offset:16384
	ds_read_b128 v[134:137], v248 offset:16384
	ds_read_b128 v[146:149], v187 offset:20480
	ds_read_b128 v[150:153], v248 offset:20480
	v_add3_u32 v187, v166, v164, 0
	v_add3_u32 v248, v166, v165, 0
	ds_read_b128 v[138:141], v187 offset:16384
	ds_read_b128 v[142:145], v248 offset:16384
	ds_read_b128 v[168:171], v187 offset:20480
	ds_read_b128 v[172:175], v248 offset:20480
	s_waitcnt vmcnt(4)
	s_barrier
	s_waitcnt lgkmcnt(0)
	v_mfma_f32_32x32x16_bf16 v[66:81], v[176:179], v[130:133], v[66:81]
	v_mfma_f32_32x32x16_bf16 v[34:49], v[176:179], v[146:149], v[34:49]
	v_mfma_f32_32x32x16_bf16 v[66:81], v[180:183], v[134:137], v[66:81]
	v_mfma_f32_32x32x16_bf16 v[34:49], v[180:183], v[150:153], v[34:49]
	v_mfma_f32_32x32x16_bf16 v[66:81], v[192:195], v[138:141], v[66:81]
	v_mfma_f32_32x32x16_bf16 v[34:49], v[192:195], v[168:171], v[34:49]
	v_mfma_f32_32x32x16_bf16 v[66:81], v[196:199], v[142:145], v[66:81]
	v_mfma_f32_32x32x16_bf16 v[34:49], v[196:199], v[172:175], v[34:49]
	v_mfma_f32_32x32x16_bf16 v[18:33], v[200:203], v[130:133], v[18:33]
	v_mfma_f32_32x32x16_bf16 v[2:17], v[200:203], v[146:149], v[2:17]
	v_mfma_f32_32x32x16_bf16 v[18:33], v[228:231], v[134:137], v[18:33]
	v_mfma_f32_32x32x16_bf16 v[2:17], v[228:231], v[150:153], v[2:17]
	v_mfma_f32_32x32x16_bf16 v[18:33], v[232:235], v[138:141], v[18:33]
	v_mfma_f32_32x32x16_bf16 v[2:17], v[232:235], v[168:171], v[2:17]
	v_mfma_f32_32x32x16_bf16 v[18:33], v[236:239], v[142:145], v[18:33]
	v_mfma_f32_32x32x16_bf16 v[2:17], v[236:239], v[172:175], v[2:17]
	s_barrier
	v_add3_u32 v187, v186, v161, s10
	v_add3_u32 v248, v186, v163, s10
	ds_read_b128 v[176:179], v187 offset:32768
	ds_read_b128 v[180:183], v248 offset:32768
	v_add3_u32 v187, v186, v164, s10
	v_add3_u32 v248, v186, v165, s10
	ds_read_b128 v[192:195], v187 offset:32768
	ds_read_b128 v[196:199], v248 offset:32768
	v_add3_u32 v187, v166, v161, s10
	v_add3_u32 v248, v166, v163, s10
	ds_read_b128 v[130:133], v187
	ds_read_b128 v[134:137], v248
	ds_read_b128 v[146:149], v187 offset:4096
	ds_read_b128 v[150:153], v248 offset:4096
	v_add3_u32 v187, v166, v164, s10
	v_add3_u32 v248, v166, v165, s10
	ds_read_b128 v[138:141], v187
	ds_read_b128 v[142:145], v248
	ds_read_b128 v[168:171], v187 offset:4096
	ds_read_b128 v[172:175], v248 offset:4096
	s_waitcnt vmcnt(2)
	s_barrier
	s_waitcnt lgkmcnt(0)
	v_mfma_f32_32x32x16_bf16 v[114:129], v[176:179], v[130:133], v[114:129]
	v_mfma_f32_32x32x16_bf16 v[98:113], v[176:179], v[146:149], v[98:113]
	v_mfma_f32_32x32x16_bf16 v[114:129], v[180:183], v[134:137], v[114:129]
	v_mfma_f32_32x32x16_bf16 v[98:113], v[180:183], v[150:153], v[98:113]
	v_mfma_f32_32x32x16_bf16 v[114:129], v[192:195], v[138:141], v[114:129]
	v_mfma_f32_32x32x16_bf16 v[98:113], v[192:195], v[168:171], v[98:113]
	v_mfma_f32_32x32x16_bf16 v[114:129], v[196:199], v[142:145], v[114:129]
	v_mfma_f32_32x32x16_bf16 v[98:113], v[196:199], v[172:175], v[98:113]
	s_barrier
	v_add3_u32 v187, v186, v161, s10
	v_add3_u32 v248, v186, v163, s10
	ds_read_b128 v[200:203], v187 offset:49152
	ds_read_b128 v[228:231], v248 offset:49152
	v_add3_u32 v187, v186, v164, s10
	v_add3_u32 v248, v186, v165, s10
	ds_read_b128 v[232:235], v187 offset:49152
	ds_read_b128 v[236:239], v248 offset:49152
	s_waitcnt vmcnt(0)
	s_barrier
	s_waitcnt lgkmcnt(0)
	v_mfma_f32_32x32x16_bf16 v[82:97], v[200:203], v[130:133], v[82:97]
	v_mfma_f32_32x32x16_bf16 v[50:65], v[200:203], v[146:149], v[50:65]
	v_mfma_f32_32x32x16_bf16 v[82:97], v[228:231], v[134:137], v[82:97]
	v_mfma_f32_32x32x16_bf16 v[50:65], v[228:231], v[150:153], v[50:65]
	v_mfma_f32_32x32x16_bf16 v[82:97], v[232:235], v[138:141], v[82:97]
	v_mfma_f32_32x32x16_bf16 v[50:65], v[232:235], v[168:171], v[50:65]
	v_mfma_f32_32x32x16_bf16 v[82:97], v[236:239], v[142:145], v[82:97]
	v_mfma_f32_32x32x16_bf16 v[50:65], v[236:239], v[172:175], v[50:65]
	s_barrier
	v_add3_u32 v187, v166, v161, s10
	v_add3_u32 v248, v166, v163, s10
	ds_read_b128 v[130:133], v187 offset:16384
	ds_read_b128 v[134:137], v248 offset:16384
	ds_read_b128 v[146:149], v187 offset:20480
	ds_read_b128 v[150:153], v248 offset:20480
	v_add3_u32 v187, v166, v164, s10
	v_add3_u32 v248, v166, v165, s10
	ds_read_b128 v[138:141], v187 offset:16384
	ds_read_b128 v[142:145], v248 offset:16384
	ds_read_b128 v[168:171], v187 offset:20480
	ds_read_b128 v[172:175], v248 offset:20480
	s_barrier
	s_waitcnt lgkmcnt(0)
	v_mfma_f32_32x32x16_bf16 v[66:81], v[176:179], v[130:133], v[66:81]
	v_mfma_f32_32x32x16_bf16 v[34:49], v[176:179], v[146:149], v[34:49]
	v_mfma_f32_32x32x16_bf16 v[66:81], v[180:183], v[134:137], v[66:81]
	v_mfma_f32_32x32x16_bf16 v[34:49], v[180:183], v[150:153], v[34:49]
	v_mfma_f32_32x32x16_bf16 v[66:81], v[192:195], v[138:141], v[66:81]
	v_mfma_f32_32x32x16_bf16 v[34:49], v[192:195], v[168:171], v[34:49]
	v_mfma_f32_32x32x16_bf16 v[66:81], v[196:199], v[142:145], v[66:81]
	v_mfma_f32_32x32x16_bf16 v[34:49], v[196:199], v[172:175], v[34:49]
	v_mfma_f32_32x32x16_bf16 v[18:33], v[200:203], v[130:133], v[18:33]
	v_mfma_f32_32x32x16_bf16 v[2:17], v[200:203], v[146:149], v[2:17]
	v_mfma_f32_32x32x16_bf16 v[18:33], v[228:231], v[134:137], v[18:33]
	v_mfma_f32_32x32x16_bf16 v[2:17], v[228:231], v[150:153], v[2:17]
	v_mfma_f32_32x32x16_bf16 v[18:33], v[232:235], v[138:141], v[18:33]
	v_mfma_f32_32x32x16_bf16 v[2:17], v[232:235], v[168:171], v[2:17]
	v_mfma_f32_32x32x16_bf16 v[18:33], v[236:239], v[142:145], v[18:33]
	v_mfma_f32_32x32x16_bf16 v[2:17], v[236:239], v[172:175], v[2:17]
	s_barrier
	s_cmp_eq_u32 s101, 0
	s_cbranch_scc0 .Lg8_ia_p1
	s_barrier

; template <bool SWAP>
; DI void gemm_mainloop(f32x16 (&acc)[4][2], const u16* __restrict__ A, int lda, int rlo, int rhi,
;                       const u16* __restrict__ B, int ldb, int K, char* lds, const u16* zero_line) {
;     ...
;   for (int kt = 0; kt < nk; ++kt) {
;     const char* st = lds + (kt & 1) * 65536;
;     ldfrag(st, 0, 0);
;     mma(1);
;     pat_rd();
;     if (kt + 1 < nk) glds(kt + 1, (kt + 1) & 1);
;     ldfrag(st, 1, 1);
;     mma(0);
;     pat_rd();
;     ldfrag(st, 2, 0);
;     mma(1);
;     pat_rd();
;     ldfrag(st, 3, 1);
;     mma(0);
;     pat_rd();
;     asm volatile("s_waitcnt vmcnt(0)" ::: "memory");
;     __syncthreads();
.Lg8_ib:
	v_add3_u32 v187, v166, v161, 0
	v_add3_u32 v248, v166, v163, 0
	ds_read_b128 v[130:133], v187
	ds_read_b128 v[134:137], v248
	ds_read_b128 v[146:149], v187 offset:4096
	ds_read_b128 v[150:153], v248 offset:4096
	v_add3_u32 v187, v166, v164, 0
	v_add3_u32 v248, v166, v165, 0
	ds_read_b128 v[138:141], v187
	ds_read_b128 v[142:145], v248
	ds_read_b128 v[168:171], v187 offset:4096
	ds_read_b128 v[172:175], v248 offset:4096
	s_barrier
	s_waitcnt lgkmcnt(0)
	v_mfma_f32_32x32x16_bf16 v[114:129], v[130:133], v[176:179], v[114:129]
	v_mfma_f32_32x32x16_bf16 v[98:113], v[146:149], v[176:179], v[98:113]
	s_add_u32 m0, s100, 0x14000
	s_nop 0
	global_load_lds_dwordx4 v241, s[6:7]
	v_add_u32_e32 v241, 0x80, v241
	v_mfma_f32_32x32x16_bf16 v[114:129], v[134:137], v[180:183], v[114:129]
	v_mfma_f32_32x32x16_bf16 v[98:113], v[150:153], v[180:183], v[98:113]
	s_add_u32 m0, s100, 0x16000
	s_nop 0
	global_load_lds_dwordx4 v243, s[6:7]
	v_add_u32_e32 v243, 0x80, v243
	v_mfma_f32_32x32x16_bf16 v[114:129], v[138:141], v[192:195], v[114:129]
	v_mfma_f32_32x32x16_bf16 v[98:113], v[168:171], v[192:195], v[98:113]
	v_mfma_f32_32x32x16_bf16 v[114:129], v[142:145], v[196:199], v[114:129]
	v_mfma_f32_32x32x16_bf16 v[98:113], v[172:175], v[196:199], v[98:113]
	s_barrier
	v_add3_u32 v187, v186, v161, 0
	v_add3_u32 v248, v186, v163, 0
	ds_read_b128 v[200:203], v187 offset:49152
	ds_read_b128 v[228:231], v248 offset:49152
	v_add3_u32 v187, v186, v164, 0
	v_add3_u32 v248, v186, v165, 0
	ds_read_b128 v[232:235], v187 offset:49152
	ds_read_b128 v[236:239], v248 offset:49152
	s_barrier
	s_waitcnt lgkmcnt(0)
	v_mfma_f32_32x32x16_bf16 v[82:97], v[130:133], v[200:203], v[82:97]
	v_mfma_f32_32x32x16_bf16 v[50:65], v[146:149], v[200:203], v[50:65]
	s_add_u32 m0, s100, 0x8000
	s_nop 0
	global_load_lds_dwordx4 v244, s[8:9]
	v_add_u32_e32 v244, 0x80, v244
	v_mfma_f32_32x32x16_bf16 v[82:97], v[134:137], v[228:231], v[82:97]
	v_mfma_f32_32x32x16_bf16 v[50:65], v[150:153], v[228:231], v[50:65]
	s_add_u32 m0, s100, 0xa000
	s_nop 0
	global_load_lds_dwordx4 v246, s[8:9]
	v_add_u32_e32 v246, 0x80, v246
	v_mfma_f32_32x32x16_bf16 v[82:97], v[138:141], v[232:235], v[82:97]
	v_mfma_f32_32x32x16_bf16 v[50:65], v[168:171], v[232:235], v[50:65]
	v_mfma_f32_32x32x16_bf16 v[82:97], v[142:145], v[236:239], v[82:97]
	v_mfma_f32_32x32x16_bf16 v[50:65], v[172:175], v[236:239], v[50:65]
	s_barrier
	v_add3_u32 v187, v166, v161, 0
	v_add3_u32 v248, v166, v163, 0
	ds_read_b128 v[130:133], v187 offset:16384
	ds_read_b128 v[134:137], v248 offset:16384
	ds_read_b128 v[146:149], v187 offset:20480
	ds_read_b128 v[150:153], v248 offset:20480
	v_add3_u32 v187, v166, v164, 0
	v_add3_u32 v248, v166, v165, 0
	ds_read_b128 v[138:141], v187 offset:16384
	ds_read_b128 v[142:145], v248 offset:16384
	ds_read_b128 v[168:171], v187 offset:20480
	ds_read_b128 v[172:175], v248 offset:20480
	s_waitcnt vmcnt(8)
	s_barrier
	s_waitcnt lgkmcnt(0)
	v_mfma_f32_32x32x16_bf16 v[66:81], v[130:133], v[176:179], v[66:81]
	v_mfma_f32_32x32x16_bf16 v[34:49], v[146:149], v[176:179], v[34:49]
	s_add_u32 m0, s100, 0x0
	s_nop 0
	global_load_lds_dwordx4 v240, s[6:7]
	v_add_u32_e32 v240, 0x80, v240
	v_mfma_f32_32x32x16_bf16 v[66:81], v[134:137], v[180:183], v[66:81]
	v_mfma_f32_32x32x16_bf16 v[34:49], v[150:153], v[180:183], v[34:49]
	s_add_u32 m0, s100, 0x2000
	s_nop 0
	global_load_lds_dwordx4 v242, s[6:7]
	v_add_u32_e32 v242, 0x80, v242
	v_mfma_f32_32x32x16_bf16 v[66:81], v[138:141], v[192:195], v[66:81]
	v_mfma_f32_32x32x16_bf16 v[34:49], v[168:171], v[192:195], v[34:49]
	v_mfma_f32_32x32x16_bf16 v[66:81], v[142:145], v[196:199], v[66:81]
	v_mfma_f32_32x32x16_bf16 v[34:49], v[172:175], v[196:199], v[34:49]
	s_barrier
	v_add3_u32 v187, v186, v161, s10
	v_add3_u32 v248, v186, v163, s10
	ds_read_b128 v[176:179], v187 offset:32768
	ds_read_b128 v[180:183], v248 offset:32768
	v_add3_u32 v187, v186, v164, s10
	v_add3_u32 v248, v186, v165, s10
	ds_read_b128 v[192:195], v187 offset:32768
	ds_read_b128 v[196:199], v248 offset:32768
	s_waitcnt vmcnt(4)
	s_barrier
	s_waitcnt lgkmcnt(0)
	v_mfma_f32_32x32x16_bf16 v[18:33], v[130:133], v[200:203], v[18:33]
	v_mfma_f32_32x32x16_bf16 v[2:17], v[146:149], v[200:203], v[2:17]
	s_add_u32 m0, s100, 0xc000
	s_nop 0
	global_load_lds_dwordx4 v245, s[8:9]
	v_add_u32_e32 v245, 0x80, v245
	v_mfma_f32_32x32x16_bf16 v[18:33], v[134:137], v[228:231], v[18:33]
	v_mfma_f32_32x32x16_bf16 v[2:17], v[150:153], v[228:231], v[2:17]
	s_add_u32 m0, s100, 0xe000
	s_nop 0
	global_load_lds_dwordx4 v247, s[8:9]
	v_add_u32_e32 v247, 0x80, v247
	v_mfma_f32_32x32x16_bf16 v[18:33], v[138:141], v[232:235], v[18:33]
	v_mfma_f32_32x32x16_bf16 v[2:17], v[168:171], v[232:235], v[2:17]
	v_mfma_f32_32x32x16_bf16 v[18:33], v[142:145], v[236:239], v[18:33]
	v_mfma_f32_32x32x16_bf16 v[2:17], v[172:175], v[236:239], v[2:17]
	s_barrier
	v_add3_u32 v187, v166, v161, s10
	v_add3_u32 v248, v166, v163, s10
	ds_read_b128 v[130:133], v187
	ds_read_b128 v[134:137], v248
	ds_read_b128 v[146:149], v187 offset:4096
	ds_read_b128 v[150:153], v248 offset:4096
	v_add3_u32 v187, v166, v164, s10
	v_add3_u32 v248, v166, v165, s10
	ds_read_b128 v[138:141], v187
	ds_read_b128 v[142:145], v248
	ds_read_b128 v[168:171], v187 offset:4096
	ds_read_b128 v[172:175], v248 offset:4096
	s_barrier
; template <bool SWAP>
; DI void gemm_mainloop(f32x16 (&acc)[4][2], const u16* __restrict__ A, int lda, int rlo, int rhi,
;                       const u16* __restrict__ B, int ldb, int K, char* lds, const u16* zero_line) {
;     ...
;   for (int kt = 0; kt < nk; ++kt) {
;     const char* st = lds + (kt & 1) * 65536;
;     ldfrag(st, 0, 0);
;     mma(1);
;     pat_rd();
;     if (kt + 1 < nk) glds(kt + 1, (kt + 1) & 1);
;     ldfrag(st, 1, 1);
;     mma(0);
;     pat_rd();
;     ldfrag(st, 2, 0);
;     mma(1);
;     pat_rd();
;     ldfrag(st, 3, 1);
;     mma(0);
;     pat_rd();
;     asm volatile("s_waitcnt vmcnt(0)" ::: "memory");
;     __syncthreads();
	s_waitcnt lgkmcnt(0)
	v_mfma_f32_32x32x16_bf16 v[114:129], v[130:133], v[176:179], v[114:129]
	v_mfma_f32_32x32x16_bf16 v[98:113], v[146:149], v[176:179], v[98:113]
	s_add_u32 m0, s100, 0x4000
	s_nop 0
	global_load_lds_dwordx4 v241, s[6:7]
	v_add_u32_e32 v241, 0x80, v241
	v_mfma_f32_32x32x16_bf16 v[114:129], v[134:137], v[180:183], v[114:129]
	v_mfma_f32_32x32x16_bf16 v[98:113], v[150:153], v[180:183], v[98:113]
	s_add_u32 m0, s100, 0x6000
	s_nop 0
	global_load_lds_dwordx4 v243, s[6:7]
	v_add_u32_e32 v243, 0x80, v243
	v_mfma_f32_32x32x16_bf16 v[114:129], v[138:141], v[192:195], v[114:129]
	v_mfma_f32_32x32x16_bf16 v[98:113], v[168:171], v[192:195], v[98:113]
	v_mfma_f32_32x32x16_bf16 v[114:129], v[142:145], v[196:199], v[114:129]
	v_mfma_f32_32x32x16_bf16 v[98:113], v[172:175], v[196:199], v[98:113]
	s_barrier
	v_add3_u32 v187, v186, v161, s10
	v_add3_u32 v248, v186, v163, s10
	ds_read_b128 v[200:203], v187 offset:49152
	ds_read_b128 v[228:231], v248 offset:49152
	v_add3_u32 v187, v186, v164, s10
	v_add3_u32 v248, v186, v165, s10
	ds_read_b128 v[232:235], v187 offset:49152
	ds_read_b128 v[236:239], v248 offset:49152
	s_barrier
	s_waitcnt lgkmcnt(0)
	v_mfma_f32_32x32x16_bf16 v[82:97], v[130:133], v[200:203], v[82:97]
	v_mfma_f32_32x32x16_bf16 v[50:65], v[146:149], v[200:203], v[50:65]
	s_add_u32 m0, s100, 0x18000
	s_nop 0
	global_load_lds_dwordx4 v244, s[8:9]
	v_add_u32_e32 v244, 0x80, v244
	v_mfma_f32_32x32x16_bf16 v[82:97], v[134:137], v[228:231], v[82:97]
	v_mfma_f32_32x32x16_bf16 v[50:65], v[150:153], v[228:231], v[50:65]
	s_add_u32 m0, s100, 0x1a000
	s_nop 0
	global_load_lds_dwordx4 v246, s[8:9]
	v_add_u32_e32 v246, 0x80, v246
	v_mfma_f32_32x32x16_bf16 v[82:97], v[138:141], v[232:235], v[82:97]
	v_mfma_f32_32x32x16_bf16 v[50:65], v[168:171], v[232:235], v[50:65]
	v_mfma_f32_32x32x16_bf16 v[82:97], v[142:145], v[236:239], v[82:97]
	v_mfma_f32_32x32x16_bf16 v[50:65], v[172:175], v[236:239], v[50:65]
	s_barrier
	v_add3_u32 v187, v166, v161, s10
	v_add3_u32 v248, v166, v163, s10
	ds_read_b128 v[130:133], v187 offset:16384
	ds_read_b128 v[134:137], v248 offset:16384
	ds_read_b128 v[146:149], v187 offset:20480
	ds_read_b128 v[150:153], v248 offset:20480
	v_add3_u32 v187, v166, v164, s10
	v_add3_u32 v248, v166, v165, s10
	ds_read_b128 v[138:141], v187 offset:16384
	ds_read_b128 v[142:145], v248 offset:16384
	ds_read_b128 v[168:171], v187 offset:20480
	ds_read_b128 v[172:175], v248 offset:20480
	s_waitcnt vmcnt(8)
	s_barrier
	s_waitcnt lgkmcnt(0)
	v_mfma_f32_32x32x16_bf16 v[66:81], v[130:133], v[176:179], v[66:81]
	v_mfma_f32_32x32x16_bf16 v[34:49], v[146:149], v[176:179], v[34:49]
	s_add_u32 m0, s100, 0x10000
	s_nop 0
	global_load_lds_dwordx4 v240, s[6:7]
	v_add_u32_e32 v240, 0x80, v240
	v_mfma_f32_32x32x16_bf16 v[66:81], v[134:137], v[180:183], v[66:81]
	v_mfma_f32_32x32x16_bf16 v[34:49], v[150:153], v[180:183], v[34:49]
	s_add_u32 m0, s100, 0x12000
	s_nop 0
	global_load_lds_dwordx4 v242, s[6:7]
	v_add_u32_e32 v242, 0x80, v242
	v_mfma_f32_32x32x16_bf16 v[66:81], v[138:141], v[192:195], v[66:81]
	v_mfma_f32_32x32x16_bf16 v[34:49], v[168:171], v[192:195], v[34:49]
	v_mfma_f32_32x32x16_bf16 v[66:81], v[142:145], v[196:199], v[66:81]
	v_mfma_f32_32x32x16_bf16 v[34:49], v[172:175], v[196:199], v[34:49]
	s_barrier
	v_add3_u32 v187, v186, v161, 0
	v_add3_u32 v248, v186, v163, 0
	ds_read_b128 v[176:179], v187 offset:32768
	ds_read_b128 v[180:183], v248 offset:32768
	v_add3_u32 v187, v186, v164, 0
	v_add3_u32 v248, v186, v165, 0
	ds_read_b128 v[192:195], v187 offset:32768
	ds_read_b128 v[196:199], v248 offset:32768
	s_waitcnt vmcnt(4)
	s_barrier
	s_waitcnt lgkmcnt(0)
	v_mfma_f32_32x32x16_bf16 v[18:33], v[130:133], v[200:203], v[18:33]
	v_mfma_f32_32x32x16_bf16 v[2:17], v[146:149], v[200:203], v[2:17]
	s_add_u32 m0, s100, 0x1c000
	s_nop 0
	global_load_lds_dwordx4 v245, s[8:9]
	v_add_u32_e32 v245, 0x80, v245
	v_mfma_f32_32x32x16_bf16 v[18:33], v[134:137], v[228:231], v[18:33]
	v_mfma_f32_32x32x16_bf16 v[2:17], v[150:153], v[228:231], v[2:17]
	s_add_u32 m0, s100, 0x1e000
	s_nop 0
	global_load_lds_dwordx4 v247, s[8:9]
	v_add_u32_e32 v247, 0x80, v247
	v_mfma_f32_32x32x16_bf16 v[18:33], v[138:141], v[232:235], v[18:33]
	v_mfma_f32_32x32x16_bf16 v[2:17], v[168:171], v[232:235], v[2:17]
	v_mfma_f32_32x32x16_bf16 v[18:33], v[142:145], v[236:239], v[18:33]
	v_mfma_f32_32x32x16_bf16 v[2:17], v[172:175], v[236:239], v[2:17]
	s_barrier
	s_add_i32 s11, s11, 2
	s_cmp_lt_u32 s11, 14
	s_cbranch_scc1 .Lg8_ib
	v_add3_u32 v187, v166, v161, 0
	v_add3_u32 v248, v166, v163, 0
	ds_read_b128 v[130:133], v187
	ds_read_b128 v[134:137], v248
	ds_read_b128 v[146:149], v187 offset:4096
	ds_read_b128 v[150:153], v248 offset:4096
	v_add3_u32 v187, v166, v164, 0
	v_add3_u32 v248, v166, v165, 0
	ds_read_b128 v[138:141], v187
	ds_read_b128 v[142:145], v248
	ds_read_b128 v[168:171], v187 offset:4096
	ds_read_b128 v[172:175], v248 offset:4096
	s_add_u32 m0, s100, 0x14000
	s_nop 0
	global_load_lds_dwordx4 v241, s[6:7]
	v_add_u32_e32 v241, 0x80, v241
	s_add_u32 m0, s100, 0x16000
	s_nop 0
	global_load_lds_dwordx4 v243, s[6:7]
	v_add_u32_e32 v243, 0x80, v243
	s_barrier
	s_waitcnt lgkmcnt(0)
	v_mfma_f32_32x32x16_bf16 v[114:129], v[130:133], v[176:179], v[114:129]
	v_mfma_f32_32x32x16_bf16 v[98:113], v[146:149], v[176:179], v[98:113]
	v_mfma_f32_32x32x16_bf16 v[114:129], v[134:137], v[180:183], v[114:129]
	v_mfma_f32_32x32x16_bf16 v[98:113], v[150:153], v[180:183], v[98:113]
	v_mfma_f32_32x32x16_bf16 v[114:129], v[138:141], v[192:195], v[114:129]
	v_mfma_f32_32x32x16_bf16 v[98:113], v[168:171], v[192:195], v[98:113]
	v_mfma_f32_32x32x16_bf16 v[114:129], v[142:145], v[196:199], v[114:129]
	v_mfma_f32_32x32x16_bf16 v[98:113], v[172:175], v[196:199], v[98:113]
	s_barrier
; template <bool SWAP>
; DI void gemm_mainloop(f32x16 (&acc)[4][2], const u16* __restrict__ A, int lda, int rlo, int rhi,
;                       const u16* __restrict__ B, int ldb, int K, char* lds, const u16* zero_line) {
;     ...
;   for (int kt = 0; kt < nk; ++kt) {
;     const char* st = lds + (kt & 1) * 65536;
;     ldfrag(st, 0, 0);
;     mma(1);
;     pat_rd();
;     if (kt + 1 < nk) glds(kt + 1, (kt + 1) & 1);
;     ldfrag(st, 1, 1);
;     mma(0);
;     pat_rd();
;     ldfrag(st, 2, 0);
;     mma(1);
;     pat_rd();
;     ldfrag(st, 3, 1);
;     mma(0);
;     pat_rd();
;     asm volatile("s_waitcnt vmcnt(0)" ::: "memory");
;     __syncthreads();
;   }
;   mma(1);
	v_add3_u32 v187, v186, v161, 0
	v_add3_u32 v248, v186, v163, 0
	ds_read_b128 v[200:203], v187 offset:49152
	ds_read_b128 v[228:231], v248 offset:49152
	v_add3_u32 v187, v186, v164, 0
	v_add3_u32 v248, v186, v165, 0
	ds_read_b128 v[232:235], v187 offset:49152
	ds_read_b128 v[236:239], v248 offset:49152
	s_barrier
	s_waitcnt lgkmcnt(0)
	v_mfma_f32_32x32x16_bf16 v[82:97], v[130:133], v[200:203], v[82:97]
	v_mfma_f32_32x32x16_bf16 v[50:65], v[146:149], v[200:203], v[50:65]
	v_mfma_f32_32x32x16_bf16 v[82:97], v[134:137], v[228:231], v[82:97]
	v_mfma_f32_32x32x16_bf16 v[50:65], v[150:153], v[228:231], v[50:65]
	v_mfma_f32_32x32x16_bf16 v[82:97], v[138:141], v[232:235], v[82:97]
	v_mfma_f32_32x32x16_bf16 v[50:65], v[168:171], v[232:235], v[50:65]
	v_mfma_f32_32x32x16_bf16 v[82:97], v[142:145], v[236:239], v[82:97]
	v_mfma_f32_32x32x16_bf16 v[50:65], v[172:175], v[236:239], v[50:65]
	s_barrier
	v_add3_u32 v187, v166, v161, 0
	v_add3_u32 v248, v166, v163, 0
	ds_read_b128 v[130:133], v187 offset:16384
	ds_read_b128 v[134:137], v248 offset:16384
	ds_read_b128 v[146:149], v187 offset:20480
	ds_read_b128 v[150:153], v248 offset:20480
	v_add3_u32 v187, v166, v164, 0
	v_add3_u32 v248, v166, v165, 0
	ds_read_b128 v[138:141], v187 offset:16384
	ds_read_b128 v[142:145], v248 offset:16384
	ds_read_b128 v[168:171], v187 offset:20480
	ds_read_b128 v[172:175], v248 offset:20480
	s_waitcnt vmcnt(4)
	s_barrier
	s_waitcnt lgkmcnt(0)
	v_mfma_f32_32x32x16_bf16 v[66:81], v[130:133], v[176:179], v[66:81]
	v_mfma_f32_32x32x16_bf16 v[34:49], v[146:149], v[176:179], v[34:49]
	v_mfma_f32_32x32x16_bf16 v[66:81], v[134:137], v[180:183], v[66:81]
	v_mfma_f32_32x32x16_bf16 v[34:49], v[150:153], v[180:183], v[34:49]
	v_mfma_f32_32x32x16_bf16 v[66:81], v[138:141], v[192:195], v[66:81]
	v_mfma_f32_32x32x16_bf16 v[34:49], v[168:171], v[192:195], v[34:49]
	v_mfma_f32_32x32x16_bf16 v[66:81], v[142:145], v[196:199], v[66:81]
	v_mfma_f32_32x32x16_bf16 v[34:49], v[172:175], v[196:199], v[34:49]
	v_mfma_f32_32x32x16_bf16 v[18:33], v[130:133], v[200:203], v[18:33]
	v_mfma_f32_32x32x16_bf16 v[2:17], v[146:149], v[200:203], v[2:17]
	v_mfma_f32_32x32x16_bf16 v[18:33], v[134:137], v[228:231], v[18:33]
	v_mfma_f32_32x32x16_bf16 v[2:17], v[150:153], v[228:231], v[2:17]
	v_mfma_f32_32x32x16_bf16 v[18:33], v[138:141], v[232:235], v[18:33]
	v_mfma_f32_32x32x16_bf16 v[2:17], v[168:171], v[232:235], v[2:17]
	v_mfma_f32_32x32x16_bf16 v[18:33], v[142:145], v[236:239], v[18:33]
	v_mfma_f32_32x32x16_bf16 v[2:17], v[172:175], v[236:239], v[2:17]
	s_barrier
	v_add3_u32 v187, v186, v161, s10
	v_add3_u32 v248, v186, v163, s10
	ds_read_b128 v[176:179], v187 offset:32768
	ds_read_b128 v[180:183], v248 offset:32768
	v_add3_u32 v187, v186, v164, s10
	v_add3_u32 v248, v186, v165, s10
	ds_read_b128 v[192:195], v187 offset:32768
	ds_read_b128 v[196:199], v248 offset:32768
	v_add3_u32 v187, v166, v161, s10
	v_add3_u32 v248, v166, v163, s10
	ds_read_b128 v[130:133], v187
	ds_read_b128 v[134:137], v248
	ds_read_b128 v[146:149], v187 offset:4096
	ds_read_b128 v[150:153], v248 offset:4096
	v_add3_u32 v187, v166, v164, s10
	v_add3_u32 v248, v166, v165, s10
	ds_read_b128 v[138:141], v187
	ds_read_b128 v[142:145], v248
	ds_read_b128 v[168:171], v187 offset:4096
	ds_read_b128 v[172:175], v248 offset:4096
	s_waitcnt vmcnt(2)
	s_barrier
	s_waitcnt lgkmcnt(0)
	v_mfma_f32_32x32x16_bf16 v[114:129], v[130:133], v[176:179], v[114:129]
	v_mfma_f32_32x32x16_bf16 v[98:113], v[146:149], v[176:179], v[98:113]
	v_mfma_f32_32x32x16_bf16 v[114:129], v[134:137], v[180:183], v[114:129]
	v_mfma_f32_32x32x16_bf16 v[98:113], v[150:153], v[180:183], v[98:113]
	v_mfma_f32_32x32x16_bf16 v[114:129], v[138:141], v[192:195], v[114:129]
	v_mfma_f32_32x32x16_bf16 v[98:113], v[168:171], v[192:195], v[98:113]
	v_mfma_f32_32x32x16_bf16 v[114:129], v[142:145], v[196:199], v[114:129]
	v_mfma_f32_32x32x16_bf16 v[98:113], v[172:175], v[196:199], v[98:113]
	s_barrier
	v_add3_u32 v187, v186, v161, s10
	v_add3_u32 v248, v186, v163, s10
	ds_read_b128 v[200:203], v187 offset:49152
	ds_read_b128 v[228:231], v248 offset:49152
	v_add3_u32 v187, v186, v164, s10
	v_add3_u32 v248, v186, v165, s10
	ds_read_b128 v[232:235], v187 offset:49152
	ds_read_b128 v[236:239], v248 offset:49152
	s_waitcnt vmcnt(0)
	s_barrier
	s_waitcnt lgkmcnt(0)
	v_mfma_f32_32x32x16_bf16 v[82:97], v[130:133], v[200:203], v[82:97]
	v_mfma_f32_32x32x16_bf16 v[50:65], v[146:149], v[200:203], v[50:65]
	v_mfma_f32_32x32x16_bf16 v[82:97], v[134:137], v[228:231], v[82:97]
	v_mfma_f32_32x32x16_bf16 v[50:65], v[150:153], v[228:231], v[50:65]
	v_mfma_f32_32x32x16_bf16 v[82:97], v[138:141], v[232:235], v[82:97]
	v_mfma_f32_32x32x16_bf16 v[50:65], v[168:171], v[232:235], v[50:65]
	v_mfma_f32_32x32x16_bf16 v[82:97], v[142:145], v[236:239], v[82:97]
	v_mfma_f32_32x32x16_bf16 v[50:65], v[172:175], v[236:239], v[50:65]
	s_barrier
	v_add3_u32 v187, v166, v161, s10
	v_add3_u32 v248, v166, v163, s10
	ds_read_b128 v[130:133], v187 offset:16384
	ds_read_b128 v[134:137], v248 offset:16384
	ds_read_b128 v[146:149], v187 offset:20480
	ds_read_b128 v[150:153], v248 offset:20480
	v_add3_u32 v187, v166, v164, s10
	v_add3_u32 v248, v166, v165, s10
	ds_read_b128 v[138:141], v187 offset:16384
	ds_read_b128 v[142:145], v248 offset:16384
	ds_read_b128 v[168:171], v187 offset:20480
	ds_read_b128 v[172:175], v248 offset:20480
	s_barrier
	s_waitcnt lgkmcnt(0)
	v_mfma_f32_32x32x16_bf16 v[66:81], v[130:133], v[176:179], v[66:81]
	v_mfma_f32_32x32x16_bf16 v[34:49], v[146:149], v[176:179], v[34:49]
	v_mfma_f32_32x32x16_bf16 v[66:81], v[134:137], v[180:183], v[66:81]
	v_mfma_f32_32x32x16_bf16 v[34:49], v[150:153], v[180:183], v[34:49]
	v_mfma_f32_32x32x16_bf16 v[66:81], v[138:141], v[192:195], v[66:81]
	v_mfma_f32_32x32x16_bf16 v[34:49], v[168:171], v[192:195], v[34:49]
	v_mfma_f32_32x32x16_bf16 v[66:81], v[142:145], v[196:199], v[66:81]
	v_mfma_f32_32x32x16_bf16 v[34:49], v[172:175], v[196:199], v[34:49]
	v_mfma_f32_32x32x16_bf16 v[18:33], v[130:133], v[200:203], v[18:33]
	v_mfma_f32_32x32x16_bf16 v[2:17], v[146:149], v[200:203], v[2:17]
	v_mfma_f32_32x32x16_bf16 v[18:33], v[134:137], v[228:231], v[18:33]
	v_mfma_f32_32x32x16_bf16 v[2:17], v[150:153], v[228:231], v[2:17]
	v_mfma_f32_32x32x16_bf16 v[18:33], v[138:141], v[232:235], v[18:33]
	v_mfma_f32_32x32x16_bf16 v[2:17], v[168:171], v[232:235], v[2:17]
	v_mfma_f32_32x32x16_bf16 v[18:33], v[142:145], v[236:239], v[18:33]
	v_mfma_f32_32x32x16_bf16 v[2:17], v[172:175], v[236:239], v[2:17]
	s_barrier
	s_cmp_eq_u32 s101, 0
	s_cbranch_scc0 .Lg8_ib_p1
	s_barrier
